# GEMM K-loop: At k=0 reads for ph3/ph7 only moved into the ph2/ph6 MMA segment (ph1/ph5 unchanged, vmcnt(10) kept)
# speedup vs baseline: 1.0075x; 1.0075x over previous
.LBB0_296:
	s_ashr_i32 s9, s8, 31
	v_cmp_lt_i64_e32 vcc, s[12:13], v[180:181]
	s_lshl_b64 s[12:13], s[8:9], 19
	s_add_u32 s12, s29, s12
	s_addc_u32 s13, s30, s13
	s_and_b64 s[14:15], vcc, exec
	s_cselect_b32 s9, s13, s21
	s_cselect_b32 s44, s12, s20
	s_ashr_i32 s7, s6, 31
	s_lshl_b64 s[14:15], s[6:7], 19
	s_add_u32 s14, s31, s14
	s_addc_u32 s15, s33, s15
	s_and_b64 s[24:25], vcc, exec
	s_cselect_b32 s7, s15, s23
	s_cselect_b32 s45, s14, s22
	s_add_u32 s20, s20, 0x40080
	s_addc_u32 s21, s21, 0
	s_add_u32 s46, s22, 0x100
	s_addc_u32 s47, s23, 0
	s_mov_b32 s48, -2
	s_add_u32 s22, s20, 0xfffc0080
	s_addc_u32 s23, s21, -1
	s_add_i32 s49, 0, 0x10000
	v_add_u32_e32 v145, s49, v142
	ds_read_b128 v[146:149], v145
	ds_read_b128 v[150:153], v145 offset:1024
	ds_read_b128 v[154:157], v145 offset:2048
	ds_read_b128 v[158:161], v145 offset:3072
	s_cmp_eq_u32 s48, 12
	s_cselect_b32 s25, s9, s23
	s_cselect_b32 s24, s44, s22
	s_cselect_b32 s23, s7, s47
	s_cselect_b32 s22, s45, s46
	s_add_i32 m0, s19, 0xc000
	ds_read_b128 v[162:165], v144
	ds_read_b128 v[166:169], v144 offset:1024
	ds_read_b128 v[170:173], v144 offset:2048
	ds_read_b128 v[174:177], v144 offset:3072
	ds_read_b128 v[190:193], v144 offset:4096
	ds_read_b128 v[194:197], v144 offset:5120
	ds_read_b128 v[198:201], v144 offset:6144
	ds_read_b128 v[202:205], v144 offset:7168
	global_load_lds_dwordx4 v138, s[20:21]
	s_add_i32 m0, s19, 0xe000
	s_nop 0
	global_load_lds_dwordx4 v140, s[20:21]
	s_waitcnt lgkmcnt(8)
	s_barrier
	s_waitcnt lgkmcnt(0)
	s_waitcnt lgkmcnt(0)
	v_mfma_f32_16x16x32_bf16 v[126:129], v[146:149], v[162:165], 0
	v_mfma_f32_16x16x32_bf16 v[118:121], v[154:157], v[162:165], 0
	v_mfma_f32_16x16x32_bf16 v[110:113], v[146:149], v[170:173], 0
	v_mfma_f32_16x16x32_bf16 v[102:105], v[154:157], v[170:173], 0
	v_mfma_f32_16x16x32_bf16 v[94:97], v[146:149], v[190:193], 0
	v_mfma_f32_16x16x32_bf16 v[86:89], v[154:157], v[190:193], 0
	v_mfma_f32_16x16x32_bf16 v[78:81], v[146:149], v[198:201], 0
	v_mfma_f32_16x16x32_bf16 v[70:73], v[154:157], v[198:201], 0
	v_mfma_f32_16x16x32_bf16 v[126:129], v[150:153], v[166:169], v[126:129]
	v_mfma_f32_16x16x32_bf16 v[118:121], v[158:161], v[166:169], v[118:121]
	v_mfma_f32_16x16x32_bf16 v[110:113], v[150:153], v[174:177], v[110:113]
	v_mfma_f32_16x16x32_bf16 v[102:105], v[158:161], v[174:177], v[102:105]
	v_mfma_f32_16x16x32_bf16 v[94:97], v[150:153], v[194:197], v[94:97]
	v_mfma_f32_16x16x32_bf16 v[86:89], v[158:161], v[194:197], v[86:89]
	v_mfma_f32_16x16x32_bf16 v[78:81], v[150:153], v[202:205], v[78:81]
	v_mfma_f32_16x16x32_bf16 v[70:73], v[158:161], v[202:205], v[70:73]
	s_barrier
	s_add_i32 s54, 0, 0x14000
	s_add_i32 s49, s49, s35
	v_add_u32_e32 v145, s54, v142
	s_add_u32 s64, s22, 0x80
	s_addc_u32 s65, s23, 0
	s_mov_b32 m0, s49
	ds_read_b128 v[206:209], v145
	ds_read_b128 v[210:213], v145 offset:1024
	ds_read_b128 v[214:217], v145 offset:2048
	ds_read_b128 v[218:221], v145 offset:3072
	global_load_lds_dwordx4 v134, s[22:23]
	s_add_i32 m0, s49, 0x2000
	s_nop 0
	global_load_lds_dwordx4 v130, s[22:23]
	s_barrier
	s_waitcnt lgkmcnt(0)
	s_waitcnt lgkmcnt(0)
	v_mfma_f32_16x16x32_bf16 v[122:125], v[206:209], v[162:165], 0
	v_mfma_f32_16x16x32_bf16 v[114:117], v[214:217], v[162:165], 0
	v_mfma_f32_16x16x32_bf16 v[106:109], v[206:209], v[170:173], 0
	v_mfma_f32_16x16x32_bf16 v[98:101], v[214:217], v[170:173], 0
	v_mfma_f32_16x16x32_bf16 v[90:93], v[206:209], v[190:193], 0
	v_mfma_f32_16x16x32_bf16 v[82:85], v[214:217], v[190:193], 0
	v_mfma_f32_16x16x32_bf16 v[74:77], v[206:209], v[198:201], 0
	v_mfma_f32_16x16x32_bf16 v[66:69], v[214:217], v[198:201], 0
	ds_read_b128 v[162:165], v144 offset:16384
	v_mfma_f32_16x16x32_bf16 v[122:125], v[210:213], v[166:169], v[122:125]
	v_mfma_f32_16x16x32_bf16 v[114:117], v[218:221], v[166:169], v[114:117]
	ds_read_b128 v[170:173], v144 offset:18432
	v_mfma_f32_16x16x32_bf16 v[106:109], v[210:213], v[174:177], v[106:109]
	v_mfma_f32_16x16x32_bf16 v[98:101], v[218:221], v[174:177], v[98:101]
	ds_read_b128 v[190:193], v144 offset:20480
	v_mfma_f32_16x16x32_bf16 v[90:93], v[210:213], v[194:197], v[90:93]
	v_mfma_f32_16x16x32_bf16 v[82:85], v[218:221], v[194:197], v[82:85]
	ds_read_b128 v[198:201], v144 offset:22528
	v_mfma_f32_16x16x32_bf16 v[74:77], v[210:213], v[202:205], v[74:77]
	v_mfma_f32_16x16x32_bf16 v[66:69], v[218:221], v[202:205], v[66:69]
	s_barrier
	s_mov_b32 m0, s19
	s_add_u32 s62, s24, 0x80
	s_addc_u32 s63, s25, 0
	ds_read_b128 v[166:169], v144 offset:17408
	ds_read_b128 v[174:177], v144 offset:19456
	ds_read_b128 v[194:197], v144 offset:21504
	ds_read_b128 v[202:205], v144 offset:23552
	global_load_lds_dwordx4 v136, s[24:25]
	s_mov_b32 m0, s36
	s_nop 0
	global_load_lds_dwordx4 v132, s[24:25]
	s_waitcnt vmcnt(10)
	s_barrier
	s_waitcnt lgkmcnt(0)
	s_waitcnt lgkmcnt(0)
	v_mfma_f32_16x16x32_bf16 v[62:65], v[146:149], v[162:165], 0
	v_mfma_f32_16x16x32_bf16 v[54:57], v[154:157], v[162:165], 0
	v_mfma_f32_16x16x32_bf16 v[46:49], v[146:149], v[170:173], 0
	v_mfma_f32_16x16x32_bf16 v[38:41], v[154:157], v[170:173], 0
	v_mfma_f32_16x16x32_bf16 v[30:33], v[146:149], v[190:193], 0
	v_mfma_f32_16x16x32_bf16 v[22:25], v[154:157], v[190:193], 0
	v_mfma_f32_16x16x32_bf16 v[14:17], v[146:149], v[198:201], 0
	v_mfma_f32_16x16x32_bf16 v[6:9], v[154:157], v[198:201], 0
	v_mfma_f32_16x16x32_bf16 v[62:65], v[150:153], v[166:169], v[62:65]
	v_mfma_f32_16x16x32_bf16 v[54:57], v[158:161], v[166:169], v[54:57]
	v_mfma_f32_16x16x32_bf16 v[46:49], v[150:153], v[174:177], v[46:49]
	v_mfma_f32_16x16x32_bf16 v[38:41], v[158:161], v[174:177], v[38:41]
	v_mfma_f32_16x16x32_bf16 v[30:33], v[150:153], v[194:197], v[30:33]
	v_mfma_f32_16x16x32_bf16 v[22:25], v[158:161], v[194:197], v[22:25]
	v_mfma_f32_16x16x32_bf16 v[14:17], v[150:153], v[202:205], v[14:17]
	v_mfma_f32_16x16x32_bf16 v[6:9], v[158:161], v[202:205], v[6:9]
	s_barrier
	v_add_u32_e32 v158, 0x18000, v142
	ds_read_b128 v[146:149], v158
	ds_read_b128 v[150:153], v158 offset:1024
	ds_read_b128 v[154:157], v158 offset:2048
	ds_read_b128 v[158:161], v158 offset:3072
	s_add_u32 s50, s22, 0x40000
	s_addc_u32 s51, s23, 0
	s_add_i32 s49, s54, s35
	s_mov_b32 m0, s49
	s_nop 0
	global_load_lds_dwordx4 v134, s[50:51]
	s_add_i32 m0, s49, 0x2000
	s_nop 0
	global_load_lds_dwordx4 v130, s[50:51]
	s_waitcnt vmcnt(6)
	s_barrier
	v_mfma_f32_16x16x32_bf16 v[58:61], v[206:209], v[162:165], 0
	v_mfma_f32_16x16x32_bf16 v[50:53], v[214:217], v[162:165], 0
	v_mfma_f32_16x16x32_bf16 v[42:45], v[206:209], v[170:173], 0
	v_mfma_f32_16x16x32_bf16 v[34:37], v[214:217], v[170:173], 0
	v_mfma_f32_16x16x32_bf16 v[26:29], v[206:209], v[190:193], 0
	v_mfma_f32_16x16x32_bf16 v[18:21], v[214:217], v[190:193], 0
	v_mfma_f32_16x16x32_bf16 v[10:13], v[206:209], v[198:201], 0
	v_mfma_f32_16x16x32_bf16 v[2:5], v[214:217], v[198:201], 0
	v_mfma_f32_16x16x32_bf16 v[58:61], v[210:213], v[166:169], v[58:61]
	v_mfma_f32_16x16x32_bf16 v[50:53], v[218:221], v[166:169], v[50:53]
	v_mfma_f32_16x16x32_bf16 v[42:45], v[210:213], v[174:177], v[42:45]
	v_mfma_f32_16x16x32_bf16 v[34:37], v[218:221], v[174:177], v[34:37]
	v_mfma_f32_16x16x32_bf16 v[26:29], v[210:213], v[194:197], v[26:29]
	v_mfma_f32_16x16x32_bf16 v[18:21], v[218:221], v[194:197], v[18:21]
	v_mfma_f32_16x16x32_bf16 v[10:13], v[210:213], v[202:205], v[10:13]
	v_mfma_f32_16x16x32_bf16 v[2:5], v[218:221], v[202:205], v[2:5]
	s_barrier
	s_add_i32 s49, 0, 0x18000
	v_add_u32_e32 v145, s49, v142
	s_add_u32 s24, s24, 0x40000
	s_addc_u32 s25, s25, 0
	s_mov_b32 m0, s37
	ds_read_b128 v[162:165], v144 offset:32768
	ds_read_b128 v[166:169], v144 offset:33792
	ds_read_b128 v[170:173], v144 offset:34816
	ds_read_b128 v[174:177], v144 offset:35840
	ds_read_b128 v[190:193], v144 offset:36864
	ds_read_b128 v[194:197], v144 offset:37888
	ds_read_b128 v[198:201], v144 offset:38912
	ds_read_b128 v[202:205], v144 offset:39936
	global_load_lds_dwordx4 v136, s[24:25]
	s_mov_b32 m0, s38
	s_nop 0
	global_load_lds_dwordx4 v132, s[24:25]
	s_waitcnt lgkmcnt(8)
	s_barrier
	s_waitcnt lgkmcnt(0)
	s_waitcnt lgkmcnt(0)
	v_mfma_f32_16x16x32_bf16 v[126:129], v[146:149], v[162:165], v[126:129]
	v_mfma_f32_16x16x32_bf16 v[118:121], v[154:157], v[162:165], v[118:121]
	v_mfma_f32_16x16x32_bf16 v[110:113], v[146:149], v[170:173], v[110:113]
	v_mfma_f32_16x16x32_bf16 v[102:105], v[154:157], v[170:173], v[102:105]
	v_mfma_f32_16x16x32_bf16 v[94:97], v[146:149], v[190:193], v[94:97]
	v_mfma_f32_16x16x32_bf16 v[86:89], v[154:157], v[190:193], v[86:89]
	v_mfma_f32_16x16x32_bf16 v[78:81], v[146:149], v[198:201], v[78:81]
	v_mfma_f32_16x16x32_bf16 v[70:73], v[154:157], v[198:201], v[70:73]
	v_mfma_f32_16x16x32_bf16 v[126:129], v[150:153], v[166:169], v[126:129]
	v_mfma_f32_16x16x32_bf16 v[118:121], v[158:161], v[166:169], v[118:121]
	v_mfma_f32_16x16x32_bf16 v[110:113], v[150:153], v[174:177], v[110:113]
	v_mfma_f32_16x16x32_bf16 v[102:105], v[158:161], v[174:177], v[102:105]
	v_mfma_f32_16x16x32_bf16 v[94:97], v[150:153], v[194:197], v[94:97]
	v_mfma_f32_16x16x32_bf16 v[86:89], v[158:161], v[194:197], v[86:89]
	v_mfma_f32_16x16x32_bf16 v[78:81], v[150:153], v[202:205], v[78:81]
	v_mfma_f32_16x16x32_bf16 v[70:73], v[158:161], v[202:205], v[70:73]
	s_barrier
	s_add_i32 s24, 0, 0x1c000
	s_add_i32 s25, s49, s35
	v_add_u32_e32 v145, s24, v142
	s_mov_b32 m0, s25
	ds_read_b128 v[206:209], v145
	ds_read_b128 v[210:213], v145 offset:1024
	ds_read_b128 v[214:217], v145 offset:2048
	ds_read_b128 v[218:221], v145 offset:3072
	global_load_lds_dwordx4 v134, s[64:65]
	s_add_i32 m0, s25, 0x2000
	s_nop 0
	global_load_lds_dwordx4 v130, s[64:65]
	s_barrier
	s_waitcnt lgkmcnt(0)
	s_waitcnt lgkmcnt(0)
	v_mfma_f32_16x16x32_bf16 v[122:125], v[206:209], v[162:165], v[122:125]
	v_mfma_f32_16x16x32_bf16 v[114:117], v[214:217], v[162:165], v[114:117]
	v_mfma_f32_16x16x32_bf16 v[106:109], v[206:209], v[170:173], v[106:109]
	v_mfma_f32_16x16x32_bf16 v[98:101], v[214:217], v[170:173], v[98:101]
	v_mfma_f32_16x16x32_bf16 v[90:93], v[206:209], v[190:193], v[90:93]
	v_mfma_f32_16x16x32_bf16 v[82:85], v[214:217], v[190:193], v[82:85]
	v_mfma_f32_16x16x32_bf16 v[74:77], v[206:209], v[198:201], v[74:77]
	v_mfma_f32_16x16x32_bf16 v[66:69], v[214:217], v[198:201], v[66:69]
	ds_read_b128 v[162:165], v144 offset:49152
	v_mfma_f32_16x16x32_bf16 v[122:125], v[210:213], v[166:169], v[122:125]
	v_mfma_f32_16x16x32_bf16 v[114:117], v[218:221], v[166:169], v[114:117]
	ds_read_b128 v[170:173], v144 offset:51200
	v_mfma_f32_16x16x32_bf16 v[106:109], v[210:213], v[174:177], v[106:109]
	v_mfma_f32_16x16x32_bf16 v[98:101], v[218:221], v[174:177], v[98:101]
	ds_read_b128 v[190:193], v144 offset:53248
	v_mfma_f32_16x16x32_bf16 v[90:93], v[210:213], v[194:197], v[90:93]
	v_mfma_f32_16x16x32_bf16 v[82:85], v[218:221], v[194:197], v[82:85]
	ds_read_b128 v[198:201], v144 offset:55296
	v_mfma_f32_16x16x32_bf16 v[74:77], v[210:213], v[202:205], v[74:77]
	v_mfma_f32_16x16x32_bf16 v[66:69], v[218:221], v[202:205], v[66:69]
	s_barrier
	s_mov_b32 m0, s39
	ds_read_b128 v[166:169], v144 offset:50176
	ds_read_b128 v[174:177], v144 offset:52224
	ds_read_b128 v[194:197], v144 offset:54272
	ds_read_b128 v[202:205], v144 offset:56320
	global_load_lds_dwordx4 v136, s[62:63]
	s_mov_b32 m0, s40
	s_nop 0
	global_load_lds_dwordx4 v132, s[62:63]
	s_waitcnt vmcnt(10)
	s_barrier
	s_waitcnt lgkmcnt(0)
	s_waitcnt lgkmcnt(0)
	v_mfma_f32_16x16x32_bf16 v[62:65], v[146:149], v[162:165], v[62:65]
	v_mfma_f32_16x16x32_bf16 v[54:57], v[154:157], v[162:165], v[54:57]
	v_mfma_f32_16x16x32_bf16 v[46:49], v[146:149], v[170:173], v[46:49]
	v_mfma_f32_16x16x32_bf16 v[38:41], v[154:157], v[170:173], v[38:41]
	v_mfma_f32_16x16x32_bf16 v[30:33], v[146:149], v[190:193], v[30:33]
	v_mfma_f32_16x16x32_bf16 v[22:25], v[154:157], v[190:193], v[22:25]
	v_mfma_f32_16x16x32_bf16 v[14:17], v[146:149], v[198:201], v[14:17]
	v_mfma_f32_16x16x32_bf16 v[6:9], v[154:157], v[198:201], v[6:9]
	v_mfma_f32_16x16x32_bf16 v[62:65], v[150:153], v[166:169], v[62:65]
	v_mfma_f32_16x16x32_bf16 v[54:57], v[158:161], v[166:169], v[54:57]
	v_mfma_f32_16x16x32_bf16 v[46:49], v[150:153], v[174:177], v[46:49]
	v_mfma_f32_16x16x32_bf16 v[38:41], v[158:161], v[174:177], v[38:41]
	v_mfma_f32_16x16x32_bf16 v[30:33], v[150:153], v[194:197], v[30:33]
	v_mfma_f32_16x16x32_bf16 v[22:25], v[158:161], v[194:197], v[22:25]
	v_mfma_f32_16x16x32_bf16 v[14:17], v[150:153], v[202:205], v[14:17]
	v_mfma_f32_16x16x32_bf16 v[6:9], v[158:161], v[202:205], v[6:9]
	s_barrier
	v_add_u32_e32 v158, 0x10000, v142
	ds_read_b128 v[146:149], v158
	ds_read_b128 v[150:153], v158 offset:1024
	ds_read_b128 v[154:157], v158 offset:2048
	ds_read_b128 v[158:161], v158 offset:3072
	s_add_u32 s22, s22, 0x40080
	s_addc_u32 s23, s23, 0
	s_add_i32 s24, s24, s35
	s_mov_b32 m0, s24
	s_nop 0
	global_load_lds_dwordx4 v134, s[22:23]
	s_add_i32 m0, s24, 0x2000
	s_nop 0
	global_load_lds_dwordx4 v130, s[22:23]
	s_waitcnt vmcnt(6)
	s_barrier
	v_mfma_f32_16x16x32_bf16 v[58:61], v[206:209], v[162:165], v[58:61]
	v_mfma_f32_16x16x32_bf16 v[50:53], v[214:217], v[162:165], v[50:53]
	v_mfma_f32_16x16x32_bf16 v[42:45], v[206:209], v[170:173], v[42:45]
	v_mfma_f32_16x16x32_bf16 v[34:37], v[214:217], v[170:173], v[34:37]
	v_mfma_f32_16x16x32_bf16 v[26:29], v[206:209], v[190:193], v[26:29]
	v_mfma_f32_16x16x32_bf16 v[18:21], v[214:217], v[190:193], v[18:21]
	v_mfma_f32_16x16x32_bf16 v[10:13], v[206:209], v[198:201], v[10:13]
	v_mfma_f32_16x16x32_bf16 v[2:5], v[214:217], v[198:201], v[2:5]
	v_mfma_f32_16x16x32_bf16 v[58:61], v[210:213], v[166:169], v[58:61]
	v_mfma_f32_16x16x32_bf16 v[50:53], v[218:221], v[166:169], v[50:53]
	v_mfma_f32_16x16x32_bf16 v[42:45], v[210:213], v[174:177], v[42:45]
	v_mfma_f32_16x16x32_bf16 v[34:37], v[218:221], v[174:177], v[34:37]
	v_mfma_f32_16x16x32_bf16 v[26:29], v[210:213], v[194:197], v[26:29]
	v_mfma_f32_16x16x32_bf16 v[18:21], v[218:221], v[194:197], v[18:21]
	v_mfma_f32_16x16x32_bf16 v[10:13], v[210:213], v[202:205], v[10:13]
	v_mfma_f32_16x16x32_bf16 v[2:5], v[218:221], v[202:205], v[2:5]
	s_barrier
	s_add_i32 s48, s48, 2
	s_add_u32 s20, s20, 0x100
	s_addc_u32 s21, s21, 0
	s_add_u32 s46, s46, 0x100
	s_addc_u32 s47, s47, 0
.LBB0_297:
	s_add_u32 s22, s20, 0xfffc0080
	s_addc_u32 s23, s21, -1
	s_add_i32 s49, 0, 0x10000
	v_add_u32_e32 v145, s49, v142
	s_cmp_eq_u32 s48, 12
	s_cselect_b32 s25, s9, s23
	s_cselect_b32 s24, s44, s22
	s_cselect_b32 s23, s7, s47
	s_cselect_b32 s22, s45, s46
	s_add_i32 m0, s19, 0xc000
	ds_read_b128 v[162:165], v144
	ds_read_b128 v[166:169], v144 offset:1024
	ds_read_b128 v[170:173], v144 offset:2048
	ds_read_b128 v[174:177], v144 offset:3072
	ds_read_b128 v[190:193], v144 offset:4096
	ds_read_b128 v[194:197], v144 offset:5120
	ds_read_b128 v[198:201], v144 offset:6144
	ds_read_b128 v[202:205], v144 offset:7168
	global_load_lds_dwordx4 v138, s[20:21]
	s_add_i32 m0, s19, 0xe000
	s_nop 0
	global_load_lds_dwordx4 v140, s[20:21]
	s_waitcnt lgkmcnt(8)
	s_barrier
	s_waitcnt lgkmcnt(0)
	s_waitcnt lgkmcnt(0)
	v_mfma_f32_16x16x32_bf16 v[126:129], v[146:149], v[162:165], v[126:129]
	v_mfma_f32_16x16x32_bf16 v[118:121], v[154:157], v[162:165], v[118:121]
	v_mfma_f32_16x16x32_bf16 v[110:113], v[146:149], v[170:173], v[110:113]
	v_mfma_f32_16x16x32_bf16 v[102:105], v[154:157], v[170:173], v[102:105]
	v_mfma_f32_16x16x32_bf16 v[94:97], v[146:149], v[190:193], v[94:97]
	v_mfma_f32_16x16x32_bf16 v[86:89], v[154:157], v[190:193], v[86:89]
	v_mfma_f32_16x16x32_bf16 v[78:81], v[146:149], v[198:201], v[78:81]
	v_mfma_f32_16x16x32_bf16 v[70:73], v[154:157], v[198:201], v[70:73]
	v_mfma_f32_16x16x32_bf16 v[126:129], v[150:153], v[166:169], v[126:129]
	v_mfma_f32_16x16x32_bf16 v[118:121], v[158:161], v[166:169], v[118:121]
	v_mfma_f32_16x16x32_bf16 v[110:113], v[150:153], v[174:177], v[110:113]
	v_mfma_f32_16x16x32_bf16 v[102:105], v[158:161], v[174:177], v[102:105]
	v_mfma_f32_16x16x32_bf16 v[94:97], v[150:153], v[194:197], v[94:97]
	v_mfma_f32_16x16x32_bf16 v[86:89], v[158:161], v[194:197], v[86:89]
	v_mfma_f32_16x16x32_bf16 v[78:81], v[150:153], v[202:205], v[78:81]
	v_mfma_f32_16x16x32_bf16 v[70:73], v[158:161], v[202:205], v[70:73]
	s_barrier
	s_add_i32 s54, 0, 0x14000
	s_add_i32 s49, s49, s35
	v_add_u32_e32 v145, s54, v142
	s_add_u32 s64, s22, 0x80
	s_addc_u32 s65, s23, 0
	s_mov_b32 m0, s49
	ds_read_b128 v[206:209], v145
	ds_read_b128 v[210:213], v145 offset:1024
	ds_read_b128 v[214:217], v145 offset:2048
	ds_read_b128 v[218:221], v145 offset:3072
	global_load_lds_dwordx4 v134, s[22:23]
	s_add_i32 m0, s49, 0x2000
	s_nop 0
	global_load_lds_dwordx4 v130, s[22:23]
	s_barrier
	s_waitcnt lgkmcnt(0)
	s_waitcnt lgkmcnt(0)
	v_mfma_f32_16x16x32_bf16 v[122:125], v[206:209], v[162:165], v[122:125]
	v_mfma_f32_16x16x32_bf16 v[114:117], v[214:217], v[162:165], v[114:117]
	v_mfma_f32_16x16x32_bf16 v[106:109], v[206:209], v[170:173], v[106:109]
	v_mfma_f32_16x16x32_bf16 v[98:101], v[214:217], v[170:173], v[98:101]
	v_mfma_f32_16x16x32_bf16 v[90:93], v[206:209], v[190:193], v[90:93]
	v_mfma_f32_16x16x32_bf16 v[82:85], v[214:217], v[190:193], v[82:85]
	v_mfma_f32_16x16x32_bf16 v[74:77], v[206:209], v[198:201], v[74:77]
	v_mfma_f32_16x16x32_bf16 v[66:69], v[214:217], v[198:201], v[66:69]
	ds_read_b128 v[162:165], v144 offset:16384
	v_mfma_f32_16x16x32_bf16 v[122:125], v[210:213], v[166:169], v[122:125]
	v_mfma_f32_16x16x32_bf16 v[114:117], v[218:221], v[166:169], v[114:117]
	ds_read_b128 v[170:173], v144 offset:18432
	v_mfma_f32_16x16x32_bf16 v[106:109], v[210:213], v[174:177], v[106:109]
	v_mfma_f32_16x16x32_bf16 v[98:101], v[218:221], v[174:177], v[98:101]
	ds_read_b128 v[190:193], v144 offset:20480
	v_mfma_f32_16x16x32_bf16 v[90:93], v[210:213], v[194:197], v[90:93]
	v_mfma_f32_16x16x32_bf16 v[82:85], v[218:221], v[194:197], v[82:85]
	ds_read_b128 v[198:201], v144 offset:22528
	v_mfma_f32_16x16x32_bf16 v[74:77], v[210:213], v[202:205], v[74:77]
	v_mfma_f32_16x16x32_bf16 v[66:69], v[218:221], v[202:205], v[66:69]
	s_barrier
	s_mov_b32 m0, s19
	s_add_u32 s62, s24, 0x80
	s_addc_u32 s63, s25, 0
	ds_read_b128 v[166:169], v144 offset:17408
	ds_read_b128 v[174:177], v144 offset:19456
	ds_read_b128 v[194:197], v144 offset:21504
	ds_read_b128 v[202:205], v144 offset:23552
	global_load_lds_dwordx4 v136, s[24:25]
	s_mov_b32 m0, s36
	s_nop 0
	global_load_lds_dwordx4 v132, s[24:25]
	s_waitcnt vmcnt(10)
	s_barrier
	s_waitcnt lgkmcnt(0)
	s_waitcnt lgkmcnt(0)
	v_mfma_f32_16x16x32_bf16 v[62:65], v[146:149], v[162:165], v[62:65]
	v_mfma_f32_16x16x32_bf16 v[54:57], v[154:157], v[162:165], v[54:57]
	v_mfma_f32_16x16x32_bf16 v[46:49], v[146:149], v[170:173], v[46:49]
	v_mfma_f32_16x16x32_bf16 v[38:41], v[154:157], v[170:173], v[38:41]
	v_mfma_f32_16x16x32_bf16 v[30:33], v[146:149], v[190:193], v[30:33]
	v_mfma_f32_16x16x32_bf16 v[22:25], v[154:157], v[190:193], v[22:25]
	v_mfma_f32_16x16x32_bf16 v[14:17], v[146:149], v[198:201], v[14:17]
	v_mfma_f32_16x16x32_bf16 v[6:9], v[154:157], v[198:201], v[6:9]
	v_mfma_f32_16x16x32_bf16 v[62:65], v[150:153], v[166:169], v[62:65]
	v_mfma_f32_16x16x32_bf16 v[54:57], v[158:161], v[166:169], v[54:57]
	v_mfma_f32_16x16x32_bf16 v[46:49], v[150:153], v[174:177], v[46:49]
	v_mfma_f32_16x16x32_bf16 v[38:41], v[158:161], v[174:177], v[38:41]
	v_mfma_f32_16x16x32_bf16 v[30:33], v[150:153], v[194:197], v[30:33]
	v_mfma_f32_16x16x32_bf16 v[22:25], v[158:161], v[194:197], v[22:25]
	v_mfma_f32_16x16x32_bf16 v[14:17], v[150:153], v[202:205], v[14:17]
	v_mfma_f32_16x16x32_bf16 v[6:9], v[158:161], v[202:205], v[6:9]
	s_barrier
	v_add_u32_e32 v158, 0x18000, v142
	ds_read_b128 v[146:149], v158
	ds_read_b128 v[150:153], v158 offset:1024
	ds_read_b128 v[154:157], v158 offset:2048
	ds_read_b128 v[158:161], v158 offset:3072
	s_add_u32 s50, s22, 0x40000
	s_addc_u32 s51, s23, 0
	s_add_i32 s49, s54, s35
	s_mov_b32 m0, s49
	s_nop 0
	global_load_lds_dwordx4 v134, s[50:51]
	s_add_i32 m0, s49, 0x2000
	s_nop 0
	global_load_lds_dwordx4 v130, s[50:51]
	s_waitcnt vmcnt(6)
	s_barrier
	v_mfma_f32_16x16x32_bf16 v[58:61], v[206:209], v[162:165], v[58:61]
	v_mfma_f32_16x16x32_bf16 v[50:53], v[214:217], v[162:165], v[50:53]
	v_mfma_f32_16x16x32_bf16 v[42:45], v[206:209], v[170:173], v[42:45]
	v_mfma_f32_16x16x32_bf16 v[34:37], v[214:217], v[170:173], v[34:37]
	v_mfma_f32_16x16x32_bf16 v[26:29], v[206:209], v[190:193], v[26:29]
	v_mfma_f32_16x16x32_bf16 v[18:21], v[214:217], v[190:193], v[18:21]
	v_mfma_f32_16x16x32_bf16 v[10:13], v[206:209], v[198:201], v[10:13]
	v_mfma_f32_16x16x32_bf16 v[2:5], v[214:217], v[198:201], v[2:5]
	v_mfma_f32_16x16x32_bf16 v[58:61], v[210:213], v[166:169], v[58:61]
	v_mfma_f32_16x16x32_bf16 v[50:53], v[218:221], v[166:169], v[50:53]
	v_mfma_f32_16x16x32_bf16 v[42:45], v[210:213], v[174:177], v[42:45]
	v_mfma_f32_16x16x32_bf16 v[34:37], v[218:221], v[174:177], v[34:37]
	v_mfma_f32_16x16x32_bf16 v[26:29], v[210:213], v[194:197], v[26:29]
	v_mfma_f32_16x16x32_bf16 v[18:21], v[218:221], v[194:197], v[18:21]
	v_mfma_f32_16x16x32_bf16 v[10:13], v[210:213], v[202:205], v[10:13]
	v_mfma_f32_16x16x32_bf16 v[2:5], v[218:221], v[202:205], v[2:5]
	s_barrier
	s_add_i32 s49, 0, 0x18000
	v_add_u32_e32 v145, s49, v142
	s_add_u32 s24, s24, 0x40000
	s_addc_u32 s25, s25, 0
	s_mov_b32 m0, s37
	ds_read_b128 v[162:165], v144 offset:32768
	ds_read_b128 v[166:169], v144 offset:33792
	ds_read_b128 v[170:173], v144 offset:34816
	ds_read_b128 v[174:177], v144 offset:35840
	ds_read_b128 v[190:193], v144 offset:36864
	ds_read_b128 v[194:197], v144 offset:37888
	ds_read_b128 v[198:201], v144 offset:38912
	ds_read_b128 v[202:205], v144 offset:39936
	global_load_lds_dwordx4 v136, s[24:25]
	s_mov_b32 m0, s38
	s_nop 0
	global_load_lds_dwordx4 v132, s[24:25]
	s_waitcnt lgkmcnt(8)
	s_barrier
	s_waitcnt lgkmcnt(0)
	s_waitcnt lgkmcnt(0)
	v_mfma_f32_16x16x32_bf16 v[126:129], v[146:149], v[162:165], v[126:129]
	v_mfma_f32_16x16x32_bf16 v[118:121], v[154:157], v[162:165], v[118:121]
	v_mfma_f32_16x16x32_bf16 v[110:113], v[146:149], v[170:173], v[110:113]
	v_mfma_f32_16x16x32_bf16 v[102:105], v[154:157], v[170:173], v[102:105]
	v_mfma_f32_16x16x32_bf16 v[94:97], v[146:149], v[190:193], v[94:97]
	v_mfma_f32_16x16x32_bf16 v[86:89], v[154:157], v[190:193], v[86:89]
	v_mfma_f32_16x16x32_bf16 v[78:81], v[146:149], v[198:201], v[78:81]
	v_mfma_f32_16x16x32_bf16 v[70:73], v[154:157], v[198:201], v[70:73]
	v_mfma_f32_16x16x32_bf16 v[126:129], v[150:153], v[166:169], v[126:129]
	v_mfma_f32_16x16x32_bf16 v[118:121], v[158:161], v[166:169], v[118:121]
	v_mfma_f32_16x16x32_bf16 v[110:113], v[150:153], v[174:177], v[110:113]
	v_mfma_f32_16x16x32_bf16 v[102:105], v[158:161], v[174:177], v[102:105]
	v_mfma_f32_16x16x32_bf16 v[94:97], v[150:153], v[194:197], v[94:97]
	v_mfma_f32_16x16x32_bf16 v[86:89], v[158:161], v[194:197], v[86:89]
	v_mfma_f32_16x16x32_bf16 v[78:81], v[150:153], v[202:205], v[78:81]
	v_mfma_f32_16x16x32_bf16 v[70:73], v[158:161], v[202:205], v[70:73]
	s_barrier
	s_add_i32 s24, 0, 0x1c000
	s_add_i32 s25, s49, s35
	v_add_u32_e32 v145, s24, v142
	s_mov_b32 m0, s25
	ds_read_b128 v[206:209], v145
	ds_read_b128 v[210:213], v145 offset:1024
	ds_read_b128 v[214:217], v145 offset:2048
	ds_read_b128 v[218:221], v145 offset:3072
	global_load_lds_dwordx4 v134, s[64:65]
	s_add_i32 m0, s25, 0x2000
	s_nop 0
	global_load_lds_dwordx4 v130, s[64:65]
	s_barrier
	s_waitcnt lgkmcnt(0)
	s_waitcnt lgkmcnt(0)
	v_mfma_f32_16x16x32_bf16 v[122:125], v[206:209], v[162:165], v[122:125]
	v_mfma_f32_16x16x32_bf16 v[114:117], v[214:217], v[162:165], v[114:117]
	v_mfma_f32_16x16x32_bf16 v[106:109], v[206:209], v[170:173], v[106:109]
	v_mfma_f32_16x16x32_bf16 v[98:101], v[214:217], v[170:173], v[98:101]
	v_mfma_f32_16x16x32_bf16 v[90:93], v[206:209], v[190:193], v[90:93]
	v_mfma_f32_16x16x32_bf16 v[82:85], v[214:217], v[190:193], v[82:85]
	v_mfma_f32_16x16x32_bf16 v[74:77], v[206:209], v[198:201], v[74:77]
	v_mfma_f32_16x16x32_bf16 v[66:69], v[214:217], v[198:201], v[66:69]
	ds_read_b128 v[162:165], v144 offset:49152
	v_mfma_f32_16x16x32_bf16 v[122:125], v[210:213], v[166:169], v[122:125]
	v_mfma_f32_16x16x32_bf16 v[114:117], v[218:221], v[166:169], v[114:117]
	ds_read_b128 v[170:173], v144 offset:51200
	v_mfma_f32_16x16x32_bf16 v[106:109], v[210:213], v[174:177], v[106:109]
	v_mfma_f32_16x16x32_bf16 v[98:101], v[218:221], v[174:177], v[98:101]
	ds_read_b128 v[190:193], v144 offset:53248
	v_mfma_f32_16x16x32_bf16 v[90:93], v[210:213], v[194:197], v[90:93]
	v_mfma_f32_16x16x32_bf16 v[82:85], v[218:221], v[194:197], v[82:85]
	ds_read_b128 v[198:201], v144 offset:55296
	v_mfma_f32_16x16x32_bf16 v[74:77], v[210:213], v[202:205], v[74:77]
	v_mfma_f32_16x16x32_bf16 v[66:69], v[218:221], v[202:205], v[66:69]
	s_barrier
	s_mov_b32 m0, s39
	ds_read_b128 v[166:169], v144 offset:50176
	ds_read_b128 v[174:177], v144 offset:52224
	ds_read_b128 v[194:197], v144 offset:54272
	ds_read_b128 v[202:205], v144 offset:56320
	global_load_lds_dwordx4 v136, s[62:63]
	s_mov_b32 m0, s40
	s_nop 0
	global_load_lds_dwordx4 v132, s[62:63]
	s_waitcnt vmcnt(10)
	s_barrier
	s_waitcnt lgkmcnt(0)
	s_waitcnt lgkmcnt(0)
	v_mfma_f32_16x16x32_bf16 v[62:65], v[146:149], v[162:165], v[62:65]
	v_mfma_f32_16x16x32_bf16 v[54:57], v[154:157], v[162:165], v[54:57]
	v_mfma_f32_16x16x32_bf16 v[46:49], v[146:149], v[170:173], v[46:49]
	v_mfma_f32_16x16x32_bf16 v[38:41], v[154:157], v[170:173], v[38:41]
	v_mfma_f32_16x16x32_bf16 v[30:33], v[146:149], v[190:193], v[30:33]
	v_mfma_f32_16x16x32_bf16 v[22:25], v[154:157], v[190:193], v[22:25]
	v_mfma_f32_16x16x32_bf16 v[14:17], v[146:149], v[198:201], v[14:17]
	v_mfma_f32_16x16x32_bf16 v[6:9], v[154:157], v[198:201], v[6:9]
	v_mfma_f32_16x16x32_bf16 v[62:65], v[150:153], v[166:169], v[62:65]
	v_mfma_f32_16x16x32_bf16 v[54:57], v[158:161], v[166:169], v[54:57]
	v_mfma_f32_16x16x32_bf16 v[46:49], v[150:153], v[174:177], v[46:49]
	v_mfma_f32_16x16x32_bf16 v[38:41], v[158:161], v[174:177], v[38:41]
	v_mfma_f32_16x16x32_bf16 v[30:33], v[150:153], v[194:197], v[30:33]
	v_mfma_f32_16x16x32_bf16 v[22:25], v[158:161], v[194:197], v[22:25]
	v_mfma_f32_16x16x32_bf16 v[14:17], v[150:153], v[202:205], v[14:17]
	v_mfma_f32_16x16x32_bf16 v[6:9], v[158:161], v[202:205], v[6:9]
	s_barrier
	v_add_u32_e32 v158, 0x10000, v142
	ds_read_b128 v[146:149], v158
	ds_read_b128 v[150:153], v158 offset:1024
	ds_read_b128 v[154:157], v158 offset:2048
	ds_read_b128 v[158:161], v158 offset:3072
	s_add_u32 s22, s22, 0x40080
	s_addc_u32 s23, s23, 0
	s_add_i32 s24, s24, s35
	s_mov_b32 m0, s24
	s_nop 0
	global_load_lds_dwordx4 v134, s[22:23]
	s_add_i32 m0, s24, 0x2000
	s_nop 0
	global_load_lds_dwordx4 v130, s[22:23]
	s_waitcnt vmcnt(6)
	s_barrier
	v_mfma_f32_16x16x32_bf16 v[58:61], v[206:209], v[162:165], v[58:61]
	v_mfma_f32_16x16x32_bf16 v[50:53], v[214:217], v[162:165], v[50:53]
	v_mfma_f32_16x16x32_bf16 v[42:45], v[206:209], v[170:173], v[42:45]
	v_mfma_f32_16x16x32_bf16 v[34:37], v[214:217], v[170:173], v[34:37]
	v_mfma_f32_16x16x32_bf16 v[26:29], v[206:209], v[190:193], v[26:29]
	v_mfma_f32_16x16x32_bf16 v[18:21], v[214:217], v[190:193], v[18:21]
	v_mfma_f32_16x16x32_bf16 v[10:13], v[206:209], v[198:201], v[10:13]
	v_mfma_f32_16x16x32_bf16 v[2:5], v[214:217], v[198:201], v[2:5]
	v_mfma_f32_16x16x32_bf16 v[58:61], v[210:213], v[166:169], v[58:61]
	v_mfma_f32_16x16x32_bf16 v[50:53], v[218:221], v[166:169], v[50:53]
	v_mfma_f32_16x16x32_bf16 v[42:45], v[210:213], v[174:177], v[42:45]
	v_mfma_f32_16x16x32_bf16 v[34:37], v[218:221], v[174:177], v[34:37]
	v_mfma_f32_16x16x32_bf16 v[26:29], v[210:213], v[194:197], v[26:29]
	v_mfma_f32_16x16x32_bf16 v[18:21], v[218:221], v[194:197], v[18:21]
	v_mfma_f32_16x16x32_bf16 v[10:13], v[210:213], v[202:205], v[10:13]
	v_mfma_f32_16x16x32_bf16 v[2:5], v[218:221], v[202:205], v[2:5]
	s_barrier
	s_add_i32 s48, s48, 2
	s_add_u32 s20, s20, 0x100
	s_addc_u32 s21, s21, 0
	s_add_u32 s46, s46, 0x100
	s_addc_u32 s47, s47, 0
	s_cmp_gt_u32 s48, 13
	s_cbranch_scc0 .LBB0_297
	s_waitcnt lgkmcnt(0)
	v_mov_b32_e32 v226, 0xbfb8aa3b
	v_mov_b32_e32 v227, 0xbfb8aa3b
	v_mov_b32_e32 v228, 1.0
	v_mov_b32_e32 v229, 1.0
	v_pk_mul_f32 v[222:223], v[126:127], v[226:227]
	v_exp_f32_e32 v222, v222
	v_exp_f32_e32 v223, v223
	s_nop 0
	v_pk_add_f32 v[222:223], v[222:223], v[228:229]
	v_rcp_f32_e32 v222, v222
	v_rcp_f32_e32 v223, v223
	v_pk_mul_f32 v[224:225], v[128:129], v[226:227]
	v_exp_f32_e32 v224, v224
	v_exp_f32_e32 v225, v225
	v_pk_mul_f32 v[222:223], v[126:127], v[222:223]
	v_pk_add_f32 v[224:225], v[224:225], v[228:229]
	v_rcp_f32_e32 v224, v224
	v_rcp_f32_e32 v225, v225
	v_pk_mul_f32 v[122:123], v[222:223], v[122:123]
	v_pk_mul_f32 v[222:223], v[118:119], v[226:227]
	v_exp_f32_e32 v222, v222
	v_exp_f32_e32 v223, v223
	v_pk_mul_f32 v[224:225], v[128:129], v[224:225]
	v_pk_add_f32 v[222:223], v[222:223], v[228:229]
	v_rcp_f32_e32 v222, v222
	v_rcp_f32_e32 v223, v223
	v_pk_mul_f32 v[124:125], v[224:225], v[124:125]
	v_pk_mul_f32 v[224:225], v[120:121], v[226:227]
	v_exp_f32_e32 v224, v224
	v_exp_f32_e32 v225, v225
	v_pk_mul_f32 v[222:223], v[118:119], v[222:223]
	v_pk_add_f32 v[224:225], v[224:225], v[228:229]
	v_rcp_f32_e32 v224, v224
	v_rcp_f32_e32 v225, v225
	v_pk_mul_f32 v[114:115], v[222:223], v[114:115]
	v_pk_mul_f32 v[222:223], v[110:111], v[226:227]
	v_exp_f32_e32 v222, v222
	v_exp_f32_e32 v223, v223
	v_pk_mul_f32 v[224:225], v[120:121], v[224:225]
	v_pk_add_f32 v[222:223], v[222:223], v[228:229]
	v_rcp_f32_e32 v222, v222
	v_rcp_f32_e32 v223, v223
	v_pk_mul_f32 v[116:117], v[224:225], v[116:117]
	v_lshl_or_b32 v146, s43, 7, v143
	v_lshl_add_u32 v145, s18, 8, v1
	v_ashrrev_i32_e32 v147, 31, v146
	s_movk_i32 s7, 0x1700
	s_and_b64 vcc, exec, s[4:5]
	s_mov_b32 s43, s6
	s_mov_b32 s18, s8
	s_mov_b64 s[22:23], s[14:15]
	v_cvt_pk_bf16_f32 v120, v114, v115
	v_mov_b64_e32 v[114:115], s[2:3]
	v_cvt_pk_bf16_f32 v118, v122, v123
	v_cvt_pk_bf16_f32 v121, v116, v117
	v_mad_i64_i32 v[122:123], s[20:21], v145, s7, v[114:115]
	v_lshlrev_b64 v[116:117], 1, v[146:147]
	v_cvt_pk_bf16_f32 v119, v124, v125
	v_lshl_add_u64 v[122:123], v[122:123], 0, v[116:117]
	global_store_dwordx4 v[122:123], v[118:121], off
	s_nop 1
	v_pk_mul_f32 v[224:225], v[112:113], v[226:227]
	v_exp_f32_e32 v224, v224
	v_exp_f32_e32 v225, v225
	v_pk_mul_f32 v[222:223], v[110:111], v[222:223]
	v_pk_add_f32 v[224:225], v[224:225], v[228:229]
	v_rcp_f32_e32 v224, v224
	v_rcp_f32_e32 v225, v225
	v_pk_mul_f32 v[106:107], v[222:223], v[106:107]
	v_pk_mul_f32 v[222:223], v[102:103], v[226:227]
	v_exp_f32_e32 v222, v222
	v_exp_f32_e32 v223, v223
	v_pk_mul_f32 v[224:225], v[112:113], v[224:225]
	v_pk_add_f32 v[222:223], v[222:223], v[228:229]
	v_rcp_f32_e32 v222, v222
	v_rcp_f32_e32 v223, v223
	v_pk_mul_f32 v[108:109], v[224:225], v[108:109]
	v_pk_mul_f32 v[224:225], v[104:105], v[226:227]
	v_exp_f32_e32 v224, v224
	v_exp_f32_e32 v225, v225
	v_pk_mul_f32 v[222:223], v[102:103], v[222:223]
	v_pk_add_f32 v[224:225], v[224:225], v[228:229]
	v_rcp_f32_e32 v224, v224
	v_rcp_f32_e32 v225, v225
	v_pk_mul_f32 v[102:103], v[222:223], v[98:99]
	v_pk_mul_f32 v[222:223], v[94:95], v[226:227]
	v_exp_f32_e32 v222, v222
	v_exp_f32_e32 v223, v223
	v_pk_mul_f32 v[224:225], v[104:105], v[224:225]
	v_pk_add_f32 v[222:223], v[222:223], v[228:229]
	v_rcp_f32_e32 v222, v222
	v_rcp_f32_e32 v223, v223
	v_pk_mul_f32 v[104:105], v[224:225], v[100:101]
	v_cvt_pk_bf16_f32 v100, v102, v103
	v_or_b32_e32 v102, 16, v145
	v_mad_i64_i32 v[102:103], s[20:21], v102, s7, v[114:115]
	v_cvt_pk_bf16_f32 v98, v106, v107
	v_cvt_pk_bf16_f32 v99, v108, v109
	v_cvt_pk_bf16_f32 v101, v104, v105
	v_lshl_add_u64 v[102:103], v[102:103], 0, v[116:117]
	global_store_dwordx4 v[102:103], v[98:101], off
	s_nop 1
	v_pk_mul_f32 v[224:225], v[96:97], v[226:227]
	v_exp_f32_e32 v224, v224
	v_exp_f32_e32 v225, v225
	v_pk_mul_f32 v[222:223], v[94:95], v[222:223]
	v_pk_add_f32 v[224:225], v[224:225], v[228:229]
	v_rcp_f32_e32 v224, v224
	v_rcp_f32_e32 v225, v225
	v_pk_mul_f32 v[90:91], v[222:223], v[90:91]
	v_pk_mul_f32 v[222:223], v[86:87], v[226:227]
	v_exp_f32_e32 v222, v222
	v_exp_f32_e32 v223, v223
	v_pk_mul_f32 v[224:225], v[96:97], v[224:225]
	v_pk_add_f32 v[222:223], v[222:223], v[228:229]
	v_rcp_f32_e32 v222, v222
	v_rcp_f32_e32 v223, v223
	v_pk_mul_f32 v[92:93], v[224:225], v[92:93]
	v_pk_mul_f32 v[224:225], v[88:89], v[226:227]
	v_exp_f32_e32 v224, v224
	v_exp_f32_e32 v225, v225
	v_pk_mul_f32 v[222:223], v[86:87], v[222:223]
	v_pk_add_f32 v[224:225], v[224:225], v[228:229]
	v_rcp_f32_e32 v224, v224
	v_rcp_f32_e32 v225, v225
	v_pk_mul_f32 v[86:87], v[222:223], v[82:83]
	v_pk_mul_f32 v[222:223], v[78:79], v[226:227]
	v_exp_f32_e32 v222, v222
	v_exp_f32_e32 v223, v223
	v_pk_mul_f32 v[224:225], v[88:89], v[224:225]
	v_pk_add_f32 v[222:223], v[222:223], v[228:229]
	v_rcp_f32_e32 v222, v222
	v_rcp_f32_e32 v223, v223
	v_pk_mul_f32 v[88:89], v[224:225], v[84:85]
	v_cvt_pk_bf16_f32 v84, v86, v87
	v_or_b32_e32 v86, 32, v145
	v_mad_i64_i32 v[86:87], s[20:21], v86, s7, v[114:115]
	v_cvt_pk_bf16_f32 v82, v90, v91
	v_cvt_pk_bf16_f32 v83, v92, v93
	v_cvt_pk_bf16_f32 v85, v88, v89
	v_lshl_add_u64 v[86:87], v[86:87], 0, v[116:117]
	global_store_dwordx4 v[86:87], v[82:85], off
	s_nop 1
	v_pk_mul_f32 v[224:225], v[80:81], v[226:227]
	v_exp_f32_e32 v224, v224
	v_exp_f32_e32 v225, v225
	v_pk_mul_f32 v[222:223], v[78:79], v[222:223]
	v_pk_add_f32 v[224:225], v[224:225], v[228:229]
	v_rcp_f32_e32 v224, v224
	v_rcp_f32_e32 v225, v225
	v_pk_mul_f32 v[74:75], v[222:223], v[74:75]
	v_pk_mul_f32 v[222:223], v[70:71], v[226:227]
	v_exp_f32_e32 v222, v222
	v_exp_f32_e32 v223, v223
	v_pk_mul_f32 v[224:225], v[80:81], v[224:225]
	v_pk_add_f32 v[222:223], v[222:223], v[228:229]
	v_rcp_f32_e32 v222, v222
	v_rcp_f32_e32 v223, v223
	v_pk_mul_f32 v[76:77], v[224:225], v[76:77]
	v_pk_mul_f32 v[224:225], v[72:73], v[226:227]
	v_exp_f32_e32 v224, v224
	v_exp_f32_e32 v225, v225
	v_pk_mul_f32 v[222:223], v[70:71], v[222:223]
	v_pk_add_f32 v[224:225], v[224:225], v[228:229]
	v_rcp_f32_e32 v224, v224
	v_rcp_f32_e32 v225, v225
	v_pk_mul_f32 v[70:71], v[222:223], v[66:67]
	v_pk_mul_f32 v[222:223], v[62:63], v[226:227]
	v_exp_f32_e32 v222, v222
	v_exp_f32_e32 v223, v223
	v_pk_mul_f32 v[224:225], v[72:73], v[224:225]
	v_pk_add_f32 v[222:223], v[222:223], v[228:229]
	v_rcp_f32_e32 v222, v222
	v_rcp_f32_e32 v223, v223
	v_pk_mul_f32 v[72:73], v[224:225], v[68:69]
	v_cvt_pk_bf16_f32 v68, v70, v71
	v_or_b32_e32 v70, 48, v145
	v_mad_i64_i32 v[70:71], s[20:21], v70, s7, v[114:115]
	v_cvt_pk_bf16_f32 v66, v74, v75
	v_cvt_pk_bf16_f32 v67, v76, v77
	v_cvt_pk_bf16_f32 v69, v72, v73
	v_lshl_add_u64 v[70:71], v[70:71], 0, v[116:117]
	global_store_dwordx4 v[70:71], v[66:69], off
	s_nop 1
	v_pk_mul_f32 v[224:225], v[64:65], v[226:227]
	v_exp_f32_e32 v224, v224
	v_exp_f32_e32 v225, v225
	v_pk_mul_f32 v[222:223], v[62:63], v[222:223]
	v_pk_add_f32 v[224:225], v[224:225], v[228:229]
	v_rcp_f32_e32 v224, v224
	v_rcp_f32_e32 v225, v225
	v_pk_mul_f32 v[58:59], v[222:223], v[58:59]
	v_pk_mul_f32 v[222:223], v[54:55], v[226:227]
	v_exp_f32_e32 v222, v222
	v_exp_f32_e32 v223, v223
	v_pk_mul_f32 v[224:225], v[64:65], v[224:225]
	v_pk_add_f32 v[222:223], v[222:223], v[228:229]
	v_rcp_f32_e32 v222, v222
	v_rcp_f32_e32 v223, v223
	v_pk_mul_f32 v[60:61], v[224:225], v[60:61]
	v_pk_mul_f32 v[224:225], v[56:57], v[226:227]
	v_exp_f32_e32 v224, v224
	v_exp_f32_e32 v225, v225
	v_pk_mul_f32 v[222:223], v[54:55], v[222:223]
	v_pk_add_f32 v[224:225], v[224:225], v[228:229]
	v_rcp_f32_e32 v224, v224
	v_rcp_f32_e32 v225, v225
	v_pk_mul_f32 v[54:55], v[222:223], v[50:51]
	v_pk_mul_f32 v[222:223], v[46:47], v[226:227]
	v_exp_f32_e32 v222, v222
	v_exp_f32_e32 v223, v223
	v_pk_mul_f32 v[224:225], v[56:57], v[224:225]
	v_pk_add_f32 v[222:223], v[222:223], v[228:229]
	v_rcp_f32_e32 v222, v222
	v_rcp_f32_e32 v223, v223
	v_pk_mul_f32 v[56:57], v[224:225], v[52:53]
	v_add_u32_e32 v68, 0x80, v145
	v_cvt_pk_bf16_f32 v52, v54, v55
	v_mad_i64_i32 v[54:55], s[20:21], v68, s7, v[114:115]
	v_cvt_pk_bf16_f32 v50, v58, v59
	v_cvt_pk_bf16_f32 v51, v60, v61
	v_cvt_pk_bf16_f32 v53, v56, v57
	v_lshl_add_u64 v[54:55], v[54:55], 0, v[116:117]
	global_store_dwordx4 v[54:55], v[50:53], off
	s_nop 1
	v_pk_mul_f32 v[224:225], v[48:49], v[226:227]
	v_exp_f32_e32 v224, v224
	v_exp_f32_e32 v225, v225
	v_pk_mul_f32 v[222:223], v[46:47], v[222:223]
	v_pk_add_f32 v[224:225], v[224:225], v[228:229]
	v_rcp_f32_e32 v224, v224
	v_rcp_f32_e32 v225, v225
	v_pk_mul_f32 v[42:43], v[222:223], v[42:43]
	v_pk_mul_f32 v[222:223], v[38:39], v[226:227]
	v_exp_f32_e32 v222, v222
	v_exp_f32_e32 v223, v223
	v_pk_mul_f32 v[224:225], v[48:49], v[224:225]
	v_pk_add_f32 v[222:223], v[222:223], v[228:229]
	v_rcp_f32_e32 v222, v222
	v_rcp_f32_e32 v223, v223
	v_pk_mul_f32 v[44:45], v[224:225], v[44:45]
	v_pk_mul_f32 v[224:225], v[40:41], v[226:227]
	v_exp_f32_e32 v224, v224
	v_exp_f32_e32 v225, v225
	v_pk_mul_f32 v[222:223], v[38:39], v[222:223]
	v_pk_add_f32 v[224:225], v[224:225], v[228:229]
	v_rcp_f32_e32 v224, v224
	v_rcp_f32_e32 v225, v225
	v_pk_mul_f32 v[38:39], v[222:223], v[34:35]
	v_pk_mul_f32 v[222:223], v[30:31], v[226:227]
	v_exp_f32_e32 v222, v222
	v_exp_f32_e32 v223, v223
	v_pk_mul_f32 v[224:225], v[40:41], v[224:225]
	v_pk_add_f32 v[222:223], v[222:223], v[228:229]
	v_rcp_f32_e32 v222, v222
	v_rcp_f32_e32 v223, v223
	v_pk_mul_f32 v[40:41], v[224:225], v[36:37]
	v_cvt_pk_bf16_f32 v36, v38, v39
	v_add_u32_e32 v38, 0x90, v145
	v_mad_i64_i32 v[38:39], s[20:21], v38, s7, v[114:115]
	v_cvt_pk_bf16_f32 v34, v42, v43
	v_cvt_pk_bf16_f32 v35, v44, v45
	v_cvt_pk_bf16_f32 v37, v40, v41
	v_lshl_add_u64 v[38:39], v[38:39], 0, v[116:117]
	global_store_dwordx4 v[38:39], v[34:37], off
	s_nop 1
	v_pk_mul_f32 v[224:225], v[32:33], v[226:227]
	v_exp_f32_e32 v224, v224
	v_exp_f32_e32 v225, v225
	v_pk_mul_f32 v[222:223], v[30:31], v[222:223]
	v_pk_add_f32 v[224:225], v[224:225], v[228:229]
	v_rcp_f32_e32 v224, v224
	v_rcp_f32_e32 v225, v225
	v_pk_mul_f32 v[26:27], v[222:223], v[26:27]
	v_pk_mul_f32 v[222:223], v[22:23], v[226:227]
	v_exp_f32_e32 v222, v222
	v_exp_f32_e32 v223, v223
	v_pk_mul_f32 v[224:225], v[32:33], v[224:225]
	v_pk_add_f32 v[222:223], v[222:223], v[228:229]
	v_rcp_f32_e32 v222, v222
	v_rcp_f32_e32 v223, v223
	v_pk_mul_f32 v[28:29], v[224:225], v[28:29]
	v_pk_mul_f32 v[224:225], v[24:25], v[226:227]
	v_exp_f32_e32 v224, v224
	v_exp_f32_e32 v225, v225
	v_pk_mul_f32 v[222:223], v[22:23], v[222:223]
	v_pk_add_f32 v[224:225], v[224:225], v[228:229]
	v_rcp_f32_e32 v224, v224
	v_rcp_f32_e32 v225, v225
	v_pk_mul_f32 v[22:23], v[222:223], v[18:19]
	v_pk_mul_f32 v[222:223], v[14:15], v[226:227]
	v_exp_f32_e32 v222, v222
	v_exp_f32_e32 v223, v223
	v_pk_mul_f32 v[224:225], v[24:25], v[224:225]
	v_pk_add_f32 v[222:223], v[222:223], v[228:229]
	v_rcp_f32_e32 v222, v222
	v_rcp_f32_e32 v223, v223
	v_pk_mul_f32 v[24:25], v[224:225], v[20:21]
	v_cvt_pk_bf16_f32 v20, v22, v23
	v_add_u32_e32 v22, 0xa0, v145
	v_mad_i64_i32 v[22:23], s[20:21], v22, s7, v[114:115]
	v_cvt_pk_bf16_f32 v18, v26, v27
	v_cvt_pk_bf16_f32 v19, v28, v29
	v_cvt_pk_bf16_f32 v21, v24, v25
	v_lshl_add_u64 v[22:23], v[22:23], 0, v[116:117]
	global_store_dwordx4 v[22:23], v[18:21], off
	s_nop 1
	v_pk_mul_f32 v[224:225], v[16:17], v[226:227]
	v_exp_f32_e32 v224, v224
	v_exp_f32_e32 v225, v225
	v_pk_mul_f32 v[222:223], v[14:15], v[222:223]
	v_pk_add_f32 v[224:225], v[224:225], v[228:229]
	v_rcp_f32_e32 v224, v224
	v_rcp_f32_e32 v225, v225
	v_pk_mul_f32 v[10:11], v[222:223], v[10:11]
	v_pk_mul_f32 v[222:223], v[6:7], v[226:227]
	v_exp_f32_e32 v222, v222
	v_exp_f32_e32 v223, v223
	v_pk_mul_f32 v[224:225], v[16:17], v[224:225]
	v_pk_add_f32 v[222:223], v[222:223], v[228:229]
	v_rcp_f32_e32 v222, v222
	v_rcp_f32_e32 v223, v223
	v_pk_mul_f32 v[12:13], v[224:225], v[12:13]
	v_pk_mul_f32 v[224:225], v[8:9], v[226:227]
	v_exp_f32_e32 v224, v224
	v_exp_f32_e32 v225, v225
	v_pk_mul_f32 v[222:223], v[6:7], v[222:223]
	v_pk_add_f32 v[224:225], v[224:225], v[228:229]
	v_rcp_f32_e32 v224, v224
	v_rcp_f32_e32 v225, v225
	v_pk_mul_f32 v[6:7], v[222:223], v[2:3]
	v_pk_mul_f32 v[224:225], v[8:9], v[224:225]
	v_pk_mul_f32 v[8:9], v[224:225], v[4:5]
	v_cvt_pk_bf16_f32 v4, v6, v7
	v_add_u32_e32 v6, 0xb0, v145
	v_mad_i64_i32 v[6:7], s[20:21], v6, s7, v[114:115]
	v_cvt_pk_bf16_f32 v2, v10, v11
	v_cvt_pk_bf16_f32 v3, v12, v13
	v_cvt_pk_bf16_f32 v5, v8, v9
	v_lshl_add_u64 v[6:7], v[6:7], 0, v[116:117]
	s_mov_b64 s[20:21], s[12:13]
	global_store_dwordx4 v[6:7], v[2:5], off
	s_cbranch_vccz .LBB0_294
	s_waitcnt vmcnt(0)
	s_cmpk_gt_u32 s28, 0xff
	s_cbranch_scc1 .LBB0_301
	s_barrier

.LBB0_373:
	s_add_u32 s46, s16, 0x100
	s_addc_u32 s47, s17, 0
	s_mov_b32 s48, -2
	s_add_u32 s16, s14, 0x100
	s_addc_u32 s17, s15, 0
	s_add_i32 s49, 0, 0x10000
	v_add_u32_e32 v154, s49, v164
	ds_read_b128 v[142:145], v154
	ds_read_b128 v[146:149], v154 offset:1024
	ds_read_b128 v[150:153], v154 offset:2048
	ds_read_b128 v[154:157], v154 offset:3072
	s_cmp_eq_u32 s48, 40
	s_cselect_b32 s21, s7, s17
	s_cselect_b32 s20, s6, s16
	s_cselect_b32 s19, s9, s47
	s_cselect_b32 s18, s8, s46
	v_lshl_add_u64 v[162:163], s[14:15], 0, v[138:139]
	s_add_i32 m0, s35, 0xc000
	ds_read_b128 v[158:161], v166
	ds_read_b128 v[168:171], v166 offset:1024
	ds_read_b128 v[172:175], v166 offset:2048
	ds_read_b128 v[190:193], v166 offset:3072
	ds_read_b128 v[194:197], v166 offset:4096
	ds_read_b128 v[198:201], v166 offset:5120
	ds_read_b128 v[202:205], v166 offset:6144
	ds_read_b128 v[206:209], v166 offset:7168
	global_load_lds_dwordx4 v[162:163], off
	v_lshl_add_u64 v[162:163], s[14:15], 0, v[140:141]
	s_add_i32 m0, s35, 0xe000
	s_nop 0
	global_load_lds_dwordx4 v[162:163], off
	s_waitcnt lgkmcnt(8)
	s_barrier
	s_waitcnt lgkmcnt(0)
	s_waitcnt lgkmcnt(0)
	v_mfma_f32_16x16x32_bf16 v[126:129], v[142:145], v[158:161], 0
	v_mfma_f32_16x16x32_bf16 v[122:125], v[150:153], v[158:161], 0
	v_mfma_f32_16x16x32_bf16 v[110:113], v[142:145], v[172:175], 0
	v_mfma_f32_16x16x32_bf16 v[106:109], v[150:153], v[172:175], 0
	v_mfma_f32_16x16x32_bf16 v[94:97], v[142:145], v[194:197], 0
	v_mfma_f32_16x16x32_bf16 v[90:93], v[150:153], v[194:197], 0
	v_mfma_f32_16x16x32_bf16 v[78:81], v[142:145], v[202:205], 0
	v_mfma_f32_16x16x32_bf16 v[74:77], v[150:153], v[202:205], 0
	v_mfma_f32_16x16x32_bf16 v[126:129], v[146:149], v[168:171], v[126:129]
	v_mfma_f32_16x16x32_bf16 v[122:125], v[154:157], v[168:171], v[122:125]
	v_mfma_f32_16x16x32_bf16 v[110:113], v[146:149], v[190:193], v[110:113]
	v_mfma_f32_16x16x32_bf16 v[106:109], v[154:157], v[190:193], v[106:109]
	v_mfma_f32_16x16x32_bf16 v[94:97], v[146:149], v[198:201], v[94:97]
	v_mfma_f32_16x16x32_bf16 v[90:93], v[154:157], v[198:201], v[90:93]
	v_mfma_f32_16x16x32_bf16 v[78:81], v[146:149], v[206:209], v[78:81]
	v_mfma_f32_16x16x32_bf16 v[74:77], v[154:157], v[206:209], v[74:77]
	s_barrier
	s_add_i32 s50, 0, 0x14000
	v_add_u32_e32 v162, s50, v164
	s_add_i32 s14, s49, s34
	ds_read_b128 v[210:213], v162
	ds_read_b128 v[214:217], v162 offset:1024
	ds_read_b128 v[218:221], v162 offset:2048
	ds_read_b128 v[222:225], v162 offset:3072
	s_add_u32 s64, s18, 0x80
	s_addc_u32 s65, s19, 0
	s_mov_b32 m0, s14
	s_nop 0
	global_load_lds_dwordx4 v132, s[18:19]
	s_add_i32 m0, s14, 0x2000
	s_nop 0
	global_load_lds_dwordx4 v136, s[18:19]
	s_barrier
	s_waitcnt lgkmcnt(0)
	s_waitcnt lgkmcnt(0)
	v_mfma_f32_16x16x32_bf16 v[118:121], v[210:213], v[158:161], 0
	v_mfma_f32_16x16x32_bf16 v[114:117], v[218:221], v[158:161], 0
	v_mfma_f32_16x16x32_bf16 v[102:105], v[210:213], v[172:175], 0
	v_mfma_f32_16x16x32_bf16 v[98:101], v[218:221], v[172:175], 0
	v_mfma_f32_16x16x32_bf16 v[86:89], v[210:213], v[194:197], 0
	v_mfma_f32_16x16x32_bf16 v[82:85], v[218:221], v[194:197], 0
	v_mfma_f32_16x16x32_bf16 v[70:73], v[210:213], v[202:205], 0
	v_mfma_f32_16x16x32_bf16 v[66:69], v[218:221], v[202:205], 0
	ds_read_b128 v[158:161], v166 offset:16384
	v_mfma_f32_16x16x32_bf16 v[118:121], v[214:217], v[168:171], v[118:121]
	v_mfma_f32_16x16x32_bf16 v[114:117], v[222:225], v[168:171], v[114:117]
	ds_read_b128 v[172:175], v166 offset:18432
	v_mfma_f32_16x16x32_bf16 v[102:105], v[214:217], v[190:193], v[102:105]
	v_mfma_f32_16x16x32_bf16 v[98:101], v[222:225], v[190:193], v[98:101]
	ds_read_b128 v[194:197], v166 offset:20480
	v_mfma_f32_16x16x32_bf16 v[86:89], v[214:217], v[198:201], v[86:89]
	v_mfma_f32_16x16x32_bf16 v[82:85], v[222:225], v[198:201], v[82:85]
	ds_read_b128 v[202:205], v166 offset:22528
	v_mfma_f32_16x16x32_bf16 v[70:73], v[214:217], v[206:209], v[70:73]
	v_mfma_f32_16x16x32_bf16 v[66:69], v[222:225], v[206:209], v[66:69]
	s_barrier
	s_mov_b32 m0, s35
	s_add_u32 s62, s20, 0x80
	s_addc_u32 s63, s21, 0
	ds_read_b128 v[168:171], v166 offset:17408
	ds_read_b128 v[190:193], v166 offset:19456
	ds_read_b128 v[198:201], v166 offset:21504
	ds_read_b128 v[206:209], v166 offset:23552
	global_load_lds_dwordx4 v130, s[20:21]
	s_mov_b32 m0, s36
	s_nop 0
	global_load_lds_dwordx4 v134, s[20:21]
	s_waitcnt vmcnt(10)
	s_barrier
	s_waitcnt lgkmcnt(0)
	s_waitcnt lgkmcnt(0)
	v_mfma_f32_16x16x32_bf16 v[62:65], v[142:145], v[158:161], 0
	v_mfma_f32_16x16x32_bf16 v[58:61], v[150:153], v[158:161], 0
	v_mfma_f32_16x16x32_bf16 v[46:49], v[142:145], v[172:175], 0
	v_mfma_f32_16x16x32_bf16 v[42:45], v[150:153], v[172:175], 0
	v_mfma_f32_16x16x32_bf16 v[30:33], v[142:145], v[194:197], 0
	v_mfma_f32_16x16x32_bf16 v[26:29], v[150:153], v[194:197], 0
	v_mfma_f32_16x16x32_bf16 v[14:17], v[142:145], v[202:205], 0
	v_mfma_f32_16x16x32_bf16 v[10:13], v[150:153], v[202:205], 0
	v_mfma_f32_16x16x32_bf16 v[62:65], v[146:149], v[168:171], v[62:65]
	v_mfma_f32_16x16x32_bf16 v[58:61], v[154:157], v[168:171], v[58:61]
	v_mfma_f32_16x16x32_bf16 v[46:49], v[146:149], v[190:193], v[46:49]
	v_mfma_f32_16x16x32_bf16 v[42:45], v[154:157], v[190:193], v[42:45]
	v_mfma_f32_16x16x32_bf16 v[30:33], v[146:149], v[198:201], v[30:33]
	v_mfma_f32_16x16x32_bf16 v[26:29], v[154:157], v[198:201], v[26:29]
	v_mfma_f32_16x16x32_bf16 v[14:17], v[146:149], v[206:209], v[14:17]
	v_mfma_f32_16x16x32_bf16 v[10:13], v[154:157], v[206:209], v[10:13]
	s_barrier
	v_add_u32_e32 v154, 0x18000, v164
	ds_read_b128 v[142:145], v154
	ds_read_b128 v[146:149], v154 offset:1024
	ds_read_b128 v[150:153], v154 offset:2048
	ds_read_b128 v[154:157], v154 offset:3072
	s_add_u32 s14, s18, 0xb0000
	s_addc_u32 s15, s19, 0
	s_add_i32 s49, s50, s34
	s_mov_b32 m0, s49
	s_nop 0
	global_load_lds_dwordx4 v132, s[14:15]
	s_add_i32 m0, s49, 0x2000
	s_nop 0
	global_load_lds_dwordx4 v136, s[14:15]
	s_waitcnt vmcnt(6)
	s_barrier
	v_mfma_f32_16x16x32_bf16 v[54:57], v[210:213], v[158:161], 0
	v_mfma_f32_16x16x32_bf16 v[50:53], v[218:221], v[158:161], 0
	v_mfma_f32_16x16x32_bf16 v[38:41], v[210:213], v[172:175], 0
	v_mfma_f32_16x16x32_bf16 v[34:37], v[218:221], v[172:175], 0
	v_mfma_f32_16x16x32_bf16 v[22:25], v[210:213], v[194:197], 0
	v_mfma_f32_16x16x32_bf16 v[18:21], v[218:221], v[194:197], 0
	v_mfma_f32_16x16x32_bf16 v[6:9], v[210:213], v[202:205], 0
	v_mfma_f32_16x16x32_bf16 v[2:5], v[218:221], v[202:205], 0
	v_mfma_f32_16x16x32_bf16 v[54:57], v[214:217], v[168:171], v[54:57]
	v_mfma_f32_16x16x32_bf16 v[50:53], v[222:225], v[168:171], v[50:53]
	v_mfma_f32_16x16x32_bf16 v[38:41], v[214:217], v[190:193], v[38:41]
	v_mfma_f32_16x16x32_bf16 v[34:37], v[222:225], v[190:193], v[34:37]
	v_mfma_f32_16x16x32_bf16 v[22:25], v[214:217], v[198:201], v[22:25]
	v_mfma_f32_16x16x32_bf16 v[18:21], v[222:225], v[198:201], v[18:21]
	v_mfma_f32_16x16x32_bf16 v[6:9], v[214:217], v[206:209], v[6:9]
	v_mfma_f32_16x16x32_bf16 v[2:5], v[222:225], v[206:209], v[2:5]
	s_barrier
	s_add_i32 s49, 0, 0x18000
	s_add_u32 s14, s20, 0xb8000
	s_addc_u32 s15, s21, 0
	s_mov_b32 m0, s37
	ds_read_b128 v[158:161], v166 offset:32768
	ds_read_b128 v[168:171], v166 offset:33792
	ds_read_b128 v[172:175], v166 offset:34816
	ds_read_b128 v[190:193], v166 offset:35840
	ds_read_b128 v[194:197], v166 offset:36864
	ds_read_b128 v[198:201], v166 offset:37888
	ds_read_b128 v[202:205], v166 offset:38912
	ds_read_b128 v[206:209], v166 offset:39936
	global_load_lds_dwordx4 v130, s[14:15]
	s_mov_b32 m0, s38
	s_nop 0
	global_load_lds_dwordx4 v134, s[14:15]
	s_waitcnt lgkmcnt(8)
	s_barrier
	s_waitcnt lgkmcnt(0)
	s_waitcnt lgkmcnt(0)
	v_mfma_f32_16x16x32_bf16 v[126:129], v[142:145], v[158:161], v[126:129]
	v_mfma_f32_16x16x32_bf16 v[122:125], v[150:153], v[158:161], v[122:125]
	v_mfma_f32_16x16x32_bf16 v[110:113], v[142:145], v[172:175], v[110:113]
	v_mfma_f32_16x16x32_bf16 v[106:109], v[150:153], v[172:175], v[106:109]
	v_mfma_f32_16x16x32_bf16 v[94:97], v[142:145], v[194:197], v[94:97]
	v_mfma_f32_16x16x32_bf16 v[90:93], v[150:153], v[194:197], v[90:93]
	v_mfma_f32_16x16x32_bf16 v[78:81], v[142:145], v[202:205], v[78:81]
	v_mfma_f32_16x16x32_bf16 v[74:77], v[150:153], v[202:205], v[74:77]
	v_mfma_f32_16x16x32_bf16 v[126:129], v[146:149], v[168:171], v[126:129]
	v_mfma_f32_16x16x32_bf16 v[122:125], v[154:157], v[168:171], v[122:125]
	v_mfma_f32_16x16x32_bf16 v[110:113], v[146:149], v[190:193], v[110:113]
	v_mfma_f32_16x16x32_bf16 v[106:109], v[154:157], v[190:193], v[106:109]
	v_mfma_f32_16x16x32_bf16 v[94:97], v[146:149], v[198:201], v[94:97]
	v_mfma_f32_16x16x32_bf16 v[90:93], v[154:157], v[198:201], v[90:93]
	v_mfma_f32_16x16x32_bf16 v[78:81], v[146:149], v[206:209], v[78:81]
	v_mfma_f32_16x16x32_bf16 v[74:77], v[154:157], v[206:209], v[74:77]
	s_barrier
	s_add_i32 s20, 0, 0x1c000
	s_add_i32 s14, s49, s34
	v_add_u32_e32 v167, s20, v164
	s_mov_b32 m0, s14
	ds_read_b128 v[210:213], v167
	ds_read_b128 v[214:217], v167 offset:1024
	ds_read_b128 v[218:221], v167 offset:2048
	ds_read_b128 v[222:225], v167 offset:3072
	global_load_lds_dwordx4 v132, s[64:65]
	s_add_i32 m0, s14, 0x2000
	s_nop 0
	global_load_lds_dwordx4 v136, s[64:65]
	s_barrier
	s_waitcnt lgkmcnt(0)
	s_waitcnt lgkmcnt(0)
	v_mfma_f32_16x16x32_bf16 v[118:121], v[210:213], v[158:161], v[118:121]
	v_mfma_f32_16x16x32_bf16 v[114:117], v[218:221], v[158:161], v[114:117]
	v_mfma_f32_16x16x32_bf16 v[102:105], v[210:213], v[172:175], v[102:105]
	v_mfma_f32_16x16x32_bf16 v[98:101], v[218:221], v[172:175], v[98:101]
	v_mfma_f32_16x16x32_bf16 v[86:89], v[210:213], v[194:197], v[86:89]
	v_mfma_f32_16x16x32_bf16 v[82:85], v[218:221], v[194:197], v[82:85]
	v_mfma_f32_16x16x32_bf16 v[70:73], v[210:213], v[202:205], v[70:73]
	v_mfma_f32_16x16x32_bf16 v[66:69], v[218:221], v[202:205], v[66:69]
	ds_read_b128 v[158:161], v166 offset:49152
	v_mfma_f32_16x16x32_bf16 v[118:121], v[214:217], v[168:171], v[118:121]
	v_mfma_f32_16x16x32_bf16 v[114:117], v[222:225], v[168:171], v[114:117]
	ds_read_b128 v[172:175], v166 offset:51200
	v_mfma_f32_16x16x32_bf16 v[102:105], v[214:217], v[190:193], v[102:105]
	v_mfma_f32_16x16x32_bf16 v[98:101], v[222:225], v[190:193], v[98:101]
	ds_read_b128 v[194:197], v166 offset:53248
	v_mfma_f32_16x16x32_bf16 v[86:89], v[214:217], v[198:201], v[86:89]
	v_mfma_f32_16x16x32_bf16 v[82:85], v[222:225], v[198:201], v[82:85]
	ds_read_b128 v[202:205], v166 offset:55296
	v_mfma_f32_16x16x32_bf16 v[70:73], v[214:217], v[206:209], v[70:73]
	v_mfma_f32_16x16x32_bf16 v[66:69], v[222:225], v[206:209], v[66:69]
	s_barrier
	s_mov_b32 m0, s39
	ds_read_b128 v[168:171], v166 offset:50176
	ds_read_b128 v[190:193], v166 offset:52224
	ds_read_b128 v[198:201], v166 offset:54272
	ds_read_b128 v[206:209], v166 offset:56320
	global_load_lds_dwordx4 v130, s[62:63]
	s_mov_b32 m0, s40
	s_nop 0
	global_load_lds_dwordx4 v134, s[62:63]
	s_waitcnt vmcnt(10)
	s_barrier
	s_waitcnt lgkmcnt(0)
	s_waitcnt lgkmcnt(0)
	v_mfma_f32_16x16x32_bf16 v[62:65], v[142:145], v[158:161], v[62:65]
	v_mfma_f32_16x16x32_bf16 v[58:61], v[150:153], v[158:161], v[58:61]
	v_mfma_f32_16x16x32_bf16 v[46:49], v[142:145], v[172:175], v[46:49]
	v_mfma_f32_16x16x32_bf16 v[42:45], v[150:153], v[172:175], v[42:45]
	v_mfma_f32_16x16x32_bf16 v[30:33], v[142:145], v[194:197], v[30:33]
	v_mfma_f32_16x16x32_bf16 v[26:29], v[150:153], v[194:197], v[26:29]
	v_mfma_f32_16x16x32_bf16 v[14:17], v[142:145], v[202:205], v[14:17]
	v_mfma_f32_16x16x32_bf16 v[10:13], v[150:153], v[202:205], v[10:13]
	v_mfma_f32_16x16x32_bf16 v[62:65], v[146:149], v[168:171], v[62:65]
	v_mfma_f32_16x16x32_bf16 v[58:61], v[154:157], v[168:171], v[58:61]
	v_mfma_f32_16x16x32_bf16 v[46:49], v[146:149], v[190:193], v[46:49]
	v_mfma_f32_16x16x32_bf16 v[42:45], v[154:157], v[190:193], v[42:45]
	v_mfma_f32_16x16x32_bf16 v[30:33], v[146:149], v[198:201], v[30:33]
	v_mfma_f32_16x16x32_bf16 v[26:29], v[154:157], v[198:201], v[26:29]
	v_mfma_f32_16x16x32_bf16 v[14:17], v[146:149], v[206:209], v[14:17]
	v_mfma_f32_16x16x32_bf16 v[10:13], v[154:157], v[206:209], v[10:13]
	s_barrier
	v_add_u32_e32 v154, 0x10000, v164
	ds_read_b128 v[142:145], v154
	ds_read_b128 v[146:149], v154 offset:1024
	ds_read_b128 v[150:153], v154 offset:2048
	ds_read_b128 v[154:157], v154 offset:3072
	s_add_u32 s14, s18, 0xb0080
	s_addc_u32 s15, s19, 0
	s_add_i32 s18, s20, s34
	s_mov_b32 m0, s18
	s_nop 0
	global_load_lds_dwordx4 v132, s[14:15]
	s_add_i32 m0, s18, 0x2000
	s_nop 0
	global_load_lds_dwordx4 v136, s[14:15]
	s_waitcnt vmcnt(6)
	s_barrier
	v_mfma_f32_16x16x32_bf16 v[54:57], v[210:213], v[158:161], v[54:57]
	v_mfma_f32_16x16x32_bf16 v[50:53], v[218:221], v[158:161], v[50:53]
	v_mfma_f32_16x16x32_bf16 v[38:41], v[210:213], v[172:175], v[38:41]
	v_mfma_f32_16x16x32_bf16 v[34:37], v[218:221], v[172:175], v[34:37]
	v_mfma_f32_16x16x32_bf16 v[22:25], v[210:213], v[194:197], v[22:25]
	v_mfma_f32_16x16x32_bf16 v[18:21], v[218:221], v[194:197], v[18:21]
	v_mfma_f32_16x16x32_bf16 v[6:9], v[210:213], v[202:205], v[6:9]
	v_mfma_f32_16x16x32_bf16 v[2:5], v[218:221], v[202:205], v[2:5]
	v_mfma_f32_16x16x32_bf16 v[54:57], v[214:217], v[168:171], v[54:57]
	v_mfma_f32_16x16x32_bf16 v[50:53], v[222:225], v[168:171], v[50:53]
	v_mfma_f32_16x16x32_bf16 v[38:41], v[214:217], v[190:193], v[38:41]
	v_mfma_f32_16x16x32_bf16 v[34:37], v[222:225], v[190:193], v[34:37]
	v_mfma_f32_16x16x32_bf16 v[22:25], v[214:217], v[198:201], v[22:25]
	v_mfma_f32_16x16x32_bf16 v[18:21], v[222:225], v[198:201], v[18:21]
	v_mfma_f32_16x16x32_bf16 v[6:9], v[214:217], v[206:209], v[6:9]
	v_mfma_f32_16x16x32_bf16 v[2:5], v[222:225], v[206:209], v[2:5]
	s_barrier
	s_add_i32 s48, s48, 2
	s_add_u32 s46, s46, 0x100
	s_addc_u32 s47, s47, 0
	s_mov_b64 s[14:15], s[16:17]
.LBB0_374:
	s_add_u32 s16, s14, 0x100
	s_addc_u32 s17, s15, 0
	s_add_i32 s49, 0, 0x10000
	s_cmp_eq_u32 s48, 40
	s_cselect_b32 s21, s7, s17
	s_cselect_b32 s20, s6, s16
	s_cselect_b32 s19, s9, s47
	s_cselect_b32 s18, s8, s46
	v_lshl_add_u64 v[162:163], s[14:15], 0, v[138:139]
	s_add_i32 m0, s35, 0xc000
	ds_read_b128 v[158:161], v166
	ds_read_b128 v[168:171], v166 offset:1024
	ds_read_b128 v[172:175], v166 offset:2048
	ds_read_b128 v[190:193], v166 offset:3072
	ds_read_b128 v[194:197], v166 offset:4096
	ds_read_b128 v[198:201], v166 offset:5120
	ds_read_b128 v[202:205], v166 offset:6144
	ds_read_b128 v[206:209], v166 offset:7168
	global_load_lds_dwordx4 v[162:163], off
	v_lshl_add_u64 v[162:163], s[14:15], 0, v[140:141]
	s_add_i32 m0, s35, 0xe000
	s_nop 0
	global_load_lds_dwordx4 v[162:163], off
	s_waitcnt lgkmcnt(8)
	s_barrier
	s_waitcnt lgkmcnt(0)
	s_waitcnt lgkmcnt(0)
	v_mfma_f32_16x16x32_bf16 v[126:129], v[142:145], v[158:161], v[126:129]
	v_mfma_f32_16x16x32_bf16 v[122:125], v[150:153], v[158:161], v[122:125]
	v_mfma_f32_16x16x32_bf16 v[110:113], v[142:145], v[172:175], v[110:113]
	v_mfma_f32_16x16x32_bf16 v[106:109], v[150:153], v[172:175], v[106:109]
	v_mfma_f32_16x16x32_bf16 v[94:97], v[142:145], v[194:197], v[94:97]
	v_mfma_f32_16x16x32_bf16 v[90:93], v[150:153], v[194:197], v[90:93]
	v_mfma_f32_16x16x32_bf16 v[78:81], v[142:145], v[202:205], v[78:81]
	v_mfma_f32_16x16x32_bf16 v[74:77], v[150:153], v[202:205], v[74:77]
	v_mfma_f32_16x16x32_bf16 v[126:129], v[146:149], v[168:171], v[126:129]
	v_mfma_f32_16x16x32_bf16 v[122:125], v[154:157], v[168:171], v[122:125]
	v_mfma_f32_16x16x32_bf16 v[110:113], v[146:149], v[190:193], v[110:113]
	v_mfma_f32_16x16x32_bf16 v[106:109], v[154:157], v[190:193], v[106:109]
	v_mfma_f32_16x16x32_bf16 v[94:97], v[146:149], v[198:201], v[94:97]
	v_mfma_f32_16x16x32_bf16 v[90:93], v[154:157], v[198:201], v[90:93]
	v_mfma_f32_16x16x32_bf16 v[78:81], v[146:149], v[206:209], v[78:81]
	v_mfma_f32_16x16x32_bf16 v[74:77], v[154:157], v[206:209], v[74:77]
	s_barrier
	s_add_i32 s50, 0, 0x14000
	v_add_u32_e32 v162, s50, v164
	s_add_i32 s14, s49, s34
	ds_read_b128 v[210:213], v162
	ds_read_b128 v[214:217], v162 offset:1024
	ds_read_b128 v[218:221], v162 offset:2048
	ds_read_b128 v[222:225], v162 offset:3072
	s_add_u32 s64, s18, 0x80
	s_addc_u32 s65, s19, 0
	s_mov_b32 m0, s14
	s_nop 0
	global_load_lds_dwordx4 v132, s[18:19]
	s_add_i32 m0, s14, 0x2000
	s_nop 0
	global_load_lds_dwordx4 v136, s[18:19]
	s_barrier
	s_waitcnt lgkmcnt(0)
	s_waitcnt lgkmcnt(0)
	v_mfma_f32_16x16x32_bf16 v[118:121], v[210:213], v[158:161], v[118:121]
	v_mfma_f32_16x16x32_bf16 v[114:117], v[218:221], v[158:161], v[114:117]
	v_mfma_f32_16x16x32_bf16 v[102:105], v[210:213], v[172:175], v[102:105]
	v_mfma_f32_16x16x32_bf16 v[98:101], v[218:221], v[172:175], v[98:101]
	v_mfma_f32_16x16x32_bf16 v[86:89], v[210:213], v[194:197], v[86:89]
	v_mfma_f32_16x16x32_bf16 v[82:85], v[218:221], v[194:197], v[82:85]
	v_mfma_f32_16x16x32_bf16 v[70:73], v[210:213], v[202:205], v[70:73]
	v_mfma_f32_16x16x32_bf16 v[66:69], v[218:221], v[202:205], v[66:69]
	ds_read_b128 v[158:161], v166 offset:16384
	v_mfma_f32_16x16x32_bf16 v[118:121], v[214:217], v[168:171], v[118:121]
	v_mfma_f32_16x16x32_bf16 v[114:117], v[222:225], v[168:171], v[114:117]
	ds_read_b128 v[172:175], v166 offset:18432
	v_mfma_f32_16x16x32_bf16 v[102:105], v[214:217], v[190:193], v[102:105]
	v_mfma_f32_16x16x32_bf16 v[98:101], v[222:225], v[190:193], v[98:101]
	ds_read_b128 v[194:197], v166 offset:20480
	v_mfma_f32_16x16x32_bf16 v[86:89], v[214:217], v[198:201], v[86:89]
	v_mfma_f32_16x16x32_bf16 v[82:85], v[222:225], v[198:201], v[82:85]
	ds_read_b128 v[202:205], v166 offset:22528
	v_mfma_f32_16x16x32_bf16 v[70:73], v[214:217], v[206:209], v[70:73]
	v_mfma_f32_16x16x32_bf16 v[66:69], v[222:225], v[206:209], v[66:69]
	s_barrier
	s_mov_b32 m0, s35
	s_add_u32 s62, s20, 0x80
	s_addc_u32 s63, s21, 0
	ds_read_b128 v[168:171], v166 offset:17408
	ds_read_b128 v[190:193], v166 offset:19456
	ds_read_b128 v[198:201], v166 offset:21504
	ds_read_b128 v[206:209], v166 offset:23552
	global_load_lds_dwordx4 v130, s[20:21]
	s_mov_b32 m0, s36
	s_nop 0
	global_load_lds_dwordx4 v134, s[20:21]
	s_waitcnt vmcnt(10)
	s_barrier
	s_waitcnt lgkmcnt(0)
	s_waitcnt lgkmcnt(0)
	v_mfma_f32_16x16x32_bf16 v[62:65], v[142:145], v[158:161], v[62:65]
	v_mfma_f32_16x16x32_bf16 v[58:61], v[150:153], v[158:161], v[58:61]
	v_mfma_f32_16x16x32_bf16 v[46:49], v[142:145], v[172:175], v[46:49]
	v_mfma_f32_16x16x32_bf16 v[42:45], v[150:153], v[172:175], v[42:45]
	v_mfma_f32_16x16x32_bf16 v[30:33], v[142:145], v[194:197], v[30:33]
	v_mfma_f32_16x16x32_bf16 v[26:29], v[150:153], v[194:197], v[26:29]
	v_mfma_f32_16x16x32_bf16 v[14:17], v[142:145], v[202:205], v[14:17]
	v_mfma_f32_16x16x32_bf16 v[10:13], v[150:153], v[202:205], v[10:13]
	v_mfma_f32_16x16x32_bf16 v[62:65], v[146:149], v[168:171], v[62:65]
	v_mfma_f32_16x16x32_bf16 v[58:61], v[154:157], v[168:171], v[58:61]
	v_mfma_f32_16x16x32_bf16 v[46:49], v[146:149], v[190:193], v[46:49]
	v_mfma_f32_16x16x32_bf16 v[42:45], v[154:157], v[190:193], v[42:45]
	v_mfma_f32_16x16x32_bf16 v[30:33], v[146:149], v[198:201], v[30:33]
	v_mfma_f32_16x16x32_bf16 v[26:29], v[154:157], v[198:201], v[26:29]
	v_mfma_f32_16x16x32_bf16 v[14:17], v[146:149], v[206:209], v[14:17]
	v_mfma_f32_16x16x32_bf16 v[10:13], v[154:157], v[206:209], v[10:13]
	s_barrier
	v_add_u32_e32 v154, 0x18000, v164
	ds_read_b128 v[142:145], v154
	ds_read_b128 v[146:149], v154 offset:1024
	ds_read_b128 v[150:153], v154 offset:2048
	ds_read_b128 v[154:157], v154 offset:3072
	s_add_u32 s14, s18, 0xb0000
	s_addc_u32 s15, s19, 0
	s_add_i32 s49, s50, s34
	s_mov_b32 m0, s49
	s_nop 0
	global_load_lds_dwordx4 v132, s[14:15]
	s_add_i32 m0, s49, 0x2000
	s_nop 0
	global_load_lds_dwordx4 v136, s[14:15]
	s_waitcnt vmcnt(6)
	s_barrier
	v_mfma_f32_16x16x32_bf16 v[54:57], v[210:213], v[158:161], v[54:57]
	v_mfma_f32_16x16x32_bf16 v[50:53], v[218:221], v[158:161], v[50:53]
	v_mfma_f32_16x16x32_bf16 v[38:41], v[210:213], v[172:175], v[38:41]
	v_mfma_f32_16x16x32_bf16 v[34:37], v[218:221], v[172:175], v[34:37]
	v_mfma_f32_16x16x32_bf16 v[22:25], v[210:213], v[194:197], v[22:25]
	v_mfma_f32_16x16x32_bf16 v[18:21], v[218:221], v[194:197], v[18:21]
	v_mfma_f32_16x16x32_bf16 v[6:9], v[210:213], v[202:205], v[6:9]
	v_mfma_f32_16x16x32_bf16 v[2:5], v[218:221], v[202:205], v[2:5]
	v_mfma_f32_16x16x32_bf16 v[54:57], v[214:217], v[168:171], v[54:57]
	v_mfma_f32_16x16x32_bf16 v[50:53], v[222:225], v[168:171], v[50:53]
	v_mfma_f32_16x16x32_bf16 v[38:41], v[214:217], v[190:193], v[38:41]
	v_mfma_f32_16x16x32_bf16 v[34:37], v[222:225], v[190:193], v[34:37]
	v_mfma_f32_16x16x32_bf16 v[22:25], v[214:217], v[198:201], v[22:25]
	v_mfma_f32_16x16x32_bf16 v[18:21], v[222:225], v[198:201], v[18:21]
	v_mfma_f32_16x16x32_bf16 v[6:9], v[214:217], v[206:209], v[6:9]
	v_mfma_f32_16x16x32_bf16 v[2:5], v[222:225], v[206:209], v[2:5]
	s_barrier
	s_add_i32 s49, 0, 0x18000
	s_add_u32 s14, s20, 0xb8000
	s_addc_u32 s15, s21, 0
	s_mov_b32 m0, s37
	ds_read_b128 v[158:161], v166 offset:32768
	ds_read_b128 v[168:171], v166 offset:33792
	ds_read_b128 v[172:175], v166 offset:34816
	ds_read_b128 v[190:193], v166 offset:35840
	ds_read_b128 v[194:197], v166 offset:36864
	ds_read_b128 v[198:201], v166 offset:37888
	ds_read_b128 v[202:205], v166 offset:38912
	ds_read_b128 v[206:209], v166 offset:39936
	global_load_lds_dwordx4 v130, s[14:15]
	s_mov_b32 m0, s38
	s_nop 0
	global_load_lds_dwordx4 v134, s[14:15]
	s_waitcnt lgkmcnt(8)
	s_barrier
	s_waitcnt lgkmcnt(0)
	s_waitcnt lgkmcnt(0)
	v_mfma_f32_16x16x32_bf16 v[126:129], v[142:145], v[158:161], v[126:129]
	v_mfma_f32_16x16x32_bf16 v[122:125], v[150:153], v[158:161], v[122:125]
	v_mfma_f32_16x16x32_bf16 v[110:113], v[142:145], v[172:175], v[110:113]
	v_mfma_f32_16x16x32_bf16 v[106:109], v[150:153], v[172:175], v[106:109]
	v_mfma_f32_16x16x32_bf16 v[94:97], v[142:145], v[194:197], v[94:97]
	v_mfma_f32_16x16x32_bf16 v[90:93], v[150:153], v[194:197], v[90:93]
	v_mfma_f32_16x16x32_bf16 v[78:81], v[142:145], v[202:205], v[78:81]
	v_mfma_f32_16x16x32_bf16 v[74:77], v[150:153], v[202:205], v[74:77]
	v_mfma_f32_16x16x32_bf16 v[126:129], v[146:149], v[168:171], v[126:129]
	v_mfma_f32_16x16x32_bf16 v[122:125], v[154:157], v[168:171], v[122:125]
	v_mfma_f32_16x16x32_bf16 v[110:113], v[146:149], v[190:193], v[110:113]
	v_mfma_f32_16x16x32_bf16 v[106:109], v[154:157], v[190:193], v[106:109]
	v_mfma_f32_16x16x32_bf16 v[94:97], v[146:149], v[198:201], v[94:97]
	v_mfma_f32_16x16x32_bf16 v[90:93], v[154:157], v[198:201], v[90:93]
	v_mfma_f32_16x16x32_bf16 v[78:81], v[146:149], v[206:209], v[78:81]
	v_mfma_f32_16x16x32_bf16 v[74:77], v[154:157], v[206:209], v[74:77]
	s_barrier
	s_add_i32 s20, 0, 0x1c000
	s_add_i32 s14, s49, s34
	v_add_u32_e32 v167, s20, v164
	s_mov_b32 m0, s14
	ds_read_b128 v[210:213], v167
	ds_read_b128 v[214:217], v167 offset:1024
	ds_read_b128 v[218:221], v167 offset:2048
	ds_read_b128 v[222:225], v167 offset:3072
	global_load_lds_dwordx4 v132, s[64:65]
	s_add_i32 m0, s14, 0x2000
	s_nop 0
	global_load_lds_dwordx4 v136, s[64:65]
	s_barrier
	s_waitcnt lgkmcnt(0)
	s_waitcnt lgkmcnt(0)
	v_mfma_f32_16x16x32_bf16 v[118:121], v[210:213], v[158:161], v[118:121]
	v_mfma_f32_16x16x32_bf16 v[114:117], v[218:221], v[158:161], v[114:117]
	v_mfma_f32_16x16x32_bf16 v[102:105], v[210:213], v[172:175], v[102:105]
	v_mfma_f32_16x16x32_bf16 v[98:101], v[218:221], v[172:175], v[98:101]
	v_mfma_f32_16x16x32_bf16 v[86:89], v[210:213], v[194:197], v[86:89]
	v_mfma_f32_16x16x32_bf16 v[82:85], v[218:221], v[194:197], v[82:85]
	v_mfma_f32_16x16x32_bf16 v[70:73], v[210:213], v[202:205], v[70:73]
	v_mfma_f32_16x16x32_bf16 v[66:69], v[218:221], v[202:205], v[66:69]
	ds_read_b128 v[158:161], v166 offset:49152
	v_mfma_f32_16x16x32_bf16 v[118:121], v[214:217], v[168:171], v[118:121]
	v_mfma_f32_16x16x32_bf16 v[114:117], v[222:225], v[168:171], v[114:117]
	ds_read_b128 v[172:175], v166 offset:51200
	v_mfma_f32_16x16x32_bf16 v[102:105], v[214:217], v[190:193], v[102:105]
	v_mfma_f32_16x16x32_bf16 v[98:101], v[222:225], v[190:193], v[98:101]
	ds_read_b128 v[194:197], v166 offset:53248
	v_mfma_f32_16x16x32_bf16 v[86:89], v[214:217], v[198:201], v[86:89]
	v_mfma_f32_16x16x32_bf16 v[82:85], v[222:225], v[198:201], v[82:85]
	ds_read_b128 v[202:205], v166 offset:55296
	v_mfma_f32_16x16x32_bf16 v[70:73], v[214:217], v[206:209], v[70:73]
	v_mfma_f32_16x16x32_bf16 v[66:69], v[222:225], v[206:209], v[66:69]
	s_barrier
	s_mov_b32 m0, s39
	ds_read_b128 v[168:171], v166 offset:50176
	ds_read_b128 v[190:193], v166 offset:52224
	ds_read_b128 v[198:201], v166 offset:54272
	ds_read_b128 v[206:209], v166 offset:56320
	global_load_lds_dwordx4 v130, s[62:63]
	s_mov_b32 m0, s40
	s_nop 0
	global_load_lds_dwordx4 v134, s[62:63]
	s_waitcnt vmcnt(10)
	s_barrier
	s_waitcnt lgkmcnt(0)
	s_waitcnt lgkmcnt(0)
	v_mfma_f32_16x16x32_bf16 v[62:65], v[142:145], v[158:161], v[62:65]
	v_mfma_f32_16x16x32_bf16 v[58:61], v[150:153], v[158:161], v[58:61]
	v_mfma_f32_16x16x32_bf16 v[46:49], v[142:145], v[172:175], v[46:49]
	v_mfma_f32_16x16x32_bf16 v[42:45], v[150:153], v[172:175], v[42:45]
	v_mfma_f32_16x16x32_bf16 v[30:33], v[142:145], v[194:197], v[30:33]
	v_mfma_f32_16x16x32_bf16 v[26:29], v[150:153], v[194:197], v[26:29]
	v_mfma_f32_16x16x32_bf16 v[14:17], v[142:145], v[202:205], v[14:17]
	v_mfma_f32_16x16x32_bf16 v[10:13], v[150:153], v[202:205], v[10:13]
	v_mfma_f32_16x16x32_bf16 v[62:65], v[146:149], v[168:171], v[62:65]
	v_mfma_f32_16x16x32_bf16 v[58:61], v[154:157], v[168:171], v[58:61]
	v_mfma_f32_16x16x32_bf16 v[46:49], v[146:149], v[190:193], v[46:49]
	v_mfma_f32_16x16x32_bf16 v[42:45], v[154:157], v[190:193], v[42:45]
	v_mfma_f32_16x16x32_bf16 v[30:33], v[146:149], v[198:201], v[30:33]
	v_mfma_f32_16x16x32_bf16 v[26:29], v[154:157], v[198:201], v[26:29]
	v_mfma_f32_16x16x32_bf16 v[14:17], v[146:149], v[206:209], v[14:17]
	v_mfma_f32_16x16x32_bf16 v[10:13], v[154:157], v[206:209], v[10:13]
	s_barrier
	v_add_u32_e32 v154, 0x10000, v164
	ds_read_b128 v[142:145], v154
	ds_read_b128 v[146:149], v154 offset:1024
	ds_read_b128 v[150:153], v154 offset:2048
	ds_read_b128 v[154:157], v154 offset:3072
	s_add_u32 s14, s18, 0xb0080
	s_addc_u32 s15, s19, 0
	s_add_i32 s18, s20, s34
	s_mov_b32 m0, s18
	s_nop 0
	global_load_lds_dwordx4 v132, s[14:15]
	s_add_i32 m0, s18, 0x2000
	s_nop 0
	global_load_lds_dwordx4 v136, s[14:15]
	s_waitcnt vmcnt(6)
	s_barrier
	v_mfma_f32_16x16x32_bf16 v[54:57], v[210:213], v[158:161], v[54:57]
	v_mfma_f32_16x16x32_bf16 v[50:53], v[218:221], v[158:161], v[50:53]
	v_mfma_f32_16x16x32_bf16 v[38:41], v[210:213], v[172:175], v[38:41]
	v_mfma_f32_16x16x32_bf16 v[34:37], v[218:221], v[172:175], v[34:37]
	v_mfma_f32_16x16x32_bf16 v[22:25], v[210:213], v[194:197], v[22:25]
	v_mfma_f32_16x16x32_bf16 v[18:21], v[218:221], v[194:197], v[18:21]
	v_mfma_f32_16x16x32_bf16 v[6:9], v[210:213], v[202:205], v[6:9]
	v_mfma_f32_16x16x32_bf16 v[2:5], v[218:221], v[202:205], v[2:5]
	v_mfma_f32_16x16x32_bf16 v[54:57], v[214:217], v[168:171], v[54:57]
	v_mfma_f32_16x16x32_bf16 v[50:53], v[222:225], v[168:171], v[50:53]
	v_mfma_f32_16x16x32_bf16 v[38:41], v[214:217], v[190:193], v[38:41]
	v_mfma_f32_16x16x32_bf16 v[34:37], v[222:225], v[190:193], v[34:37]
	v_mfma_f32_16x16x32_bf16 v[22:25], v[214:217], v[198:201], v[22:25]
	v_mfma_f32_16x16x32_bf16 v[18:21], v[222:225], v[198:201], v[18:21]
	v_mfma_f32_16x16x32_bf16 v[6:9], v[214:217], v[206:209], v[6:9]
	v_mfma_f32_16x16x32_bf16 v[2:5], v[222:225], v[206:209], v[2:5]
	s_barrier
	s_add_i32 s48, s48, 2
	s_add_u32 s46, s46, 0x100
	s_addc_u32 s47, s47, 0
	s_cmp_gt_u32 s48, 41
	s_mov_b64 s[14:15], s[16:17]
	s_cbranch_scc0 .LBB0_374
	s_waitcnt lgkmcnt(0)
	s_ashr_i32 s14, s33, 5
	s_mul_hi_i32 s15, s14, 0x9000
	s_mul_i32 s14, s14, 0x9000
	v_lshl_or_b32 v158, s45, 8, v165
	s_add_u32 s14, s26, s14
	s_addc_u32 s15, s27, s15
	v_ashrrev_i32_e32 v159, 31, v158
	v_lshl_add_u64 v[160:161], v[158:159], 2, s[14:15]
	global_load_dwordx4 v[142:145], v[160:161], off offset:16
	global_load_dwordx4 v[146:149], v[160:161], off
	v_lshl_add_u32 v162, s33, 8, v1
	v_ashrrev_i32_e32 v163, 31, v162
	v_lshlrev_b64 v[150:151], 12, v[162:163]
	v_lshl_add_u64 v[150:151], s[12:13], 0, v[150:151]
	v_lshl_add_u64 v[150:151], v[158:159], 1, v[150:151]
	v_mov_b32_e32 v152, 0x10000
	v_mov_b32_e32 v153, 0
	global_load_dwordx4 v[174:177], v[150:151], off offset:2048
	global_load_dwordx4 v[186:189], v[150:151], off offset:2304
	v_lshl_add_u64 v[150:151], v[150:151], 0, v[152:153]
	global_load_dwordx4 v[190:193], v[150:151], off offset:2048
	global_load_dwordx4 v[194:197], v[150:151], off offset:2304
	v_lshl_add_u64 v[150:151], v[150:151], 0, v[152:153]
	global_load_dwordx4 v[198:201], v[150:151], off offset:2048
	global_load_dwordx4 v[202:205], v[150:151], off offset:2304
	v_lshl_add_u64 v[150:151], v[150:151], 0, v[152:153]
	global_load_dwordx4 v[206:209], v[150:151], off offset:2048
	global_load_dwordx4 v[210:213], v[150:151], off offset:2304
	v_mov_b32_e32 v152, 0x50000
	v_lshl_add_u64 v[150:151], v[150:151], 0, v[152:153]
	v_mov_b32_e32 v152, 0x10000
	global_load_dwordx4 v[214:217], v[150:151], off offset:2048
	global_load_dwordx4 v[218:221], v[150:151], off offset:2304
	v_lshl_add_u64 v[150:151], v[150:151], 0, v[152:153]
	global_load_dwordx4 v[222:225], v[150:151], off offset:2048
	global_load_dwordx4 v[226:229], v[150:151], off offset:2304
	v_lshl_add_u64 v[150:151], v[150:151], 0, v[152:153]
	global_load_dwordx4 v[230:233], v[150:151], off offset:2048
	global_load_dwordx4 v[236:239], v[150:151], off offset:2304
	v_lshl_add_u64 v[150:151], v[150:151], 0, v[152:153]
	global_load_dwordx4 v[246:249], v[150:151], off offset:2048
	global_load_dwordx4 v[250:253], v[150:151], off offset:2304
	s_mov_b64 s[14:15], 0x80000
	s_and_b64 vcc, exec, s[4:5]
	s_mov_b32 s45, s43
	s_mov_b32 s33, s44
	s_mov_b64 s[16:17], s[8:9]
	s_waitcnt vmcnt(16)
	v_pk_add_f32 v[144:145], v[144:145], 1.0 op_sel_hi:[1,0]
	v_pk_add_f32 v[148:149], v[148:149], 1.0 op_sel_hi:[1,0]
	v_pk_add_f32 v[146:147], v[146:147], 1.0 op_sel_hi:[1,0]
	v_pk_add_f32 v[142:143], v[142:143], 1.0 op_sel_hi:[1,0]
	v_pk_mul_f32 v[152:153], v[148:149], 0.5 op_sel_hi:[1,0]
	v_pk_mul_f32 v[156:157], v[146:147], 0.5 op_sel_hi:[1,0]
	v_pk_mul_f32 v[150:151], v[144:145], 0.5 op_sel_hi:[1,0]
	v_pk_mul_f32 v[154:155], v[142:143], 0.5 op_sel_hi:[1,0]
	global_load_dwordx4 v[142:145], v[160:161], off offset:528
	global_load_dwordx4 v[146:149], v[160:161], off offset:512
	s_waitcnt vmcnt(0)
	v_pk_add_f32 v[144:145], v[144:145], 1.0 op_sel_hi:[1,0]
	v_pk_add_f32 v[148:149], v[148:149], 1.0 op_sel_hi:[1,0]
	v_pk_add_f32 v[160:161], v[146:147], 1.0 op_sel_hi:[1,0]
	v_pk_mul_f32 v[146:147], v[148:149], 0.5 op_sel_hi:[1,0]
	v_pk_mul_f32 v[148:149], v[160:161], 0.5 op_sel_hi:[1,0]
	v_pk_add_f32 v[160:161], v[142:143], 1.0 op_sel_hi:[1,0]
	v_pk_mul_f32 v[142:143], v[144:145], 0.5 op_sel_hi:[1,0]
	v_pk_mul_f32 v[144:145], v[160:161], 0.5 op_sel_hi:[1,0]
	v_lshlrev_b64 v[160:161], 12, v[162:163]
	v_lshl_add_u64 v[168:169], s[12:13], 0, v[160:161]
	v_lshlrev_b64 v[160:161], 1, v[158:159]
	v_lshl_add_u64 v[158:159], v[168:169], 0, v[160:161]
	v_mov_b32_e32 v168, v174
	v_mov_b32_e32 v169, v175
	v_mov_b32_e32 v170, v176
	v_mov_b32_e32 v171, v177
	s_nop 0
	v_lshlrev_b32_e32 v172, 16, v168
	v_and_b32_e32 v173, 0xffff0000, v168
	v_lshlrev_b32_e32 v168, 16, v169
	v_and_b32_e32 v169, 0xffff0000, v169
	v_pk_fma_f32 v[128:129], v[128:129], v[152:153], v[168:169]
	v_lshlrev_b32_e32 v168, 16, v170
	v_and_b32_e32 v169, 0xffff0000, v170
	v_pk_fma_f32 v[168:169], v[122:123], v[154:155], v[168:169]
	v_lshlrev_b32_e32 v122, 16, v171
	v_and_b32_e32 v123, 0xffff0000, v171
	v_pk_fma_f32 v[126:127], v[126:127], v[156:157], v[172:173]
	v_pk_fma_f32 v[170:171], v[124:125], v[150:151], v[122:123]
	v_cvt_pk_bf16_f32 v122, v126, v127
	v_cvt_pk_bf16_f32 v123, v128, v129
	v_cvt_pk_bf16_f32 v124, v168, v169
	v_cvt_pk_bf16_f32 v125, v170, v171
	global_store_dwordx4 v[158:159], v[122:125], off offset:2048
	s_nop 1
	v_mov_b32_e32 v122, v186
	v_mov_b32_e32 v123, v187
	v_mov_b32_e32 v124, v188
	v_mov_b32_e32 v125, v189
	s_nop 0
	v_lshlrev_b32_e32 v126, 16, v122
	v_and_b32_e32 v127, 0xffff0000, v122
	v_lshlrev_b32_e32 v122, 16, v123
	v_and_b32_e32 v123, 0xffff0000, v123
	v_pk_fma_f32 v[120:121], v[120:121], v[146:147], v[122:123]
	v_lshlrev_b32_e32 v122, 16, v124
	v_and_b32_e32 v123, 0xffff0000, v124
	v_pk_fma_f32 v[122:123], v[114:115], v[144:145], v[122:123]
	v_lshlrev_b32_e32 v114, 16, v125
	v_and_b32_e32 v115, 0xffff0000, v125
	v_pk_fma_f32 v[118:119], v[118:119], v[148:149], v[126:127]
	v_pk_fma_f32 v[124:125], v[116:117], v[142:143], v[114:115]
	v_cvt_pk_bf16_f32 v114, v118, v119
	v_cvt_pk_bf16_f32 v115, v120, v121
	v_cvt_pk_bf16_f32 v116, v122, v123
	v_cvt_pk_bf16_f32 v117, v124, v125
	global_store_dwordx4 v[158:159], v[114:117], off offset:2304
	s_nop 1
	v_or_b32_e32 v114, 16, v162
	v_ashrrev_i32_e32 v115, 31, v114
	v_lshlrev_b64 v[114:115], 12, v[114:115]
	v_lshl_add_u64 v[114:115], s[12:13], 0, v[114:115]
	v_lshl_add_u64 v[118:119], v[114:115], 0, v[160:161]
	v_mov_b32_e32 v114, v190
	v_mov_b32_e32 v115, v191
	v_mov_b32_e32 v116, v192
	v_mov_b32_e32 v117, v193
	s_nop 0
	v_lshlrev_b32_e32 v120, 16, v114
	v_and_b32_e32 v121, 0xffff0000, v114
	v_lshlrev_b32_e32 v114, 16, v115
	v_and_b32_e32 v115, 0xffff0000, v115
	v_pk_fma_f32 v[112:113], v[112:113], v[152:153], v[114:115]
	v_lshlrev_b32_e32 v114, 16, v116
	v_and_b32_e32 v115, 0xffff0000, v116
	v_pk_fma_f32 v[114:115], v[106:107], v[154:155], v[114:115]
	v_lshlrev_b32_e32 v106, 16, v117
	v_and_b32_e32 v107, 0xffff0000, v117
	v_pk_fma_f32 v[110:111], v[110:111], v[156:157], v[120:121]
	v_pk_fma_f32 v[116:117], v[108:109], v[150:151], v[106:107]
	v_cvt_pk_bf16_f32 v106, v110, v111
	v_cvt_pk_bf16_f32 v107, v112, v113
	v_cvt_pk_bf16_f32 v108, v114, v115
	v_cvt_pk_bf16_f32 v109, v116, v117
	global_store_dwordx4 v[118:119], v[106:109], off offset:2048
	s_nop 1
	v_mov_b32_e32 v106, v194
	v_mov_b32_e32 v107, v195
	v_mov_b32_e32 v108, v196
	v_mov_b32_e32 v109, v197
	s_nop 0
	v_lshlrev_b32_e32 v110, 16, v106
	v_and_b32_e32 v111, 0xffff0000, v106
	v_lshlrev_b32_e32 v106, 16, v107
	v_and_b32_e32 v107, 0xffff0000, v107
	v_pk_fma_f32 v[104:105], v[104:105], v[146:147], v[106:107]
	v_lshlrev_b32_e32 v106, 16, v108
	v_and_b32_e32 v107, 0xffff0000, v108
	v_pk_fma_f32 v[106:107], v[98:99], v[144:145], v[106:107]
	v_lshlrev_b32_e32 v98, 16, v109
	v_and_b32_e32 v99, 0xffff0000, v109
	v_pk_fma_f32 v[102:103], v[102:103], v[148:149], v[110:111]
	v_pk_fma_f32 v[108:109], v[100:101], v[142:143], v[98:99]
	v_cvt_pk_bf16_f32 v98, v102, v103
	v_cvt_pk_bf16_f32 v99, v104, v105
	v_cvt_pk_bf16_f32 v100, v106, v107
	v_cvt_pk_bf16_f32 v101, v108, v109
	global_store_dwordx4 v[118:119], v[98:101], off offset:2304
	s_nop 1
	v_or_b32_e32 v98, 32, v162
	v_ashrrev_i32_e32 v99, 31, v98
	v_lshlrev_b64 v[98:99], 12, v[98:99]
	v_lshl_add_u64 v[98:99], s[12:13], 0, v[98:99]
	v_lshl_add_u64 v[102:103], v[98:99], 0, v[160:161]
	v_mov_b32_e32 v98, v198
	v_mov_b32_e32 v99, v199
	v_mov_b32_e32 v100, v200
	v_mov_b32_e32 v101, v201
	s_nop 0
	v_lshlrev_b32_e32 v104, 16, v98
	v_and_b32_e32 v105, 0xffff0000, v98
	v_lshlrev_b32_e32 v98, 16, v99
	v_and_b32_e32 v99, 0xffff0000, v99
	v_pk_fma_f32 v[96:97], v[96:97], v[152:153], v[98:99]
	v_lshlrev_b32_e32 v98, 16, v100
	v_and_b32_e32 v99, 0xffff0000, v100
	v_pk_fma_f32 v[98:99], v[90:91], v[154:155], v[98:99]
	v_lshlrev_b32_e32 v90, 16, v101
	v_and_b32_e32 v91, 0xffff0000, v101
	v_pk_fma_f32 v[94:95], v[94:95], v[156:157], v[104:105]
	v_pk_fma_f32 v[100:101], v[92:93], v[150:151], v[90:91]
	v_cvt_pk_bf16_f32 v90, v94, v95
	v_cvt_pk_bf16_f32 v91, v96, v97
	v_cvt_pk_bf16_f32 v92, v98, v99
	v_cvt_pk_bf16_f32 v93, v100, v101
	global_store_dwordx4 v[102:103], v[90:93], off offset:2048
	s_nop 1
	v_mov_b32_e32 v90, v202
	v_mov_b32_e32 v91, v203
	v_mov_b32_e32 v92, v204
	v_mov_b32_e32 v93, v205
	s_nop 0
	v_lshlrev_b32_e32 v94, 16, v90
	v_and_b32_e32 v95, 0xffff0000, v90
	v_lshlrev_b32_e32 v90, 16, v91
	v_and_b32_e32 v91, 0xffff0000, v91
	v_pk_fma_f32 v[88:89], v[88:89], v[146:147], v[90:91]
	v_lshlrev_b32_e32 v90, 16, v92
	v_and_b32_e32 v91, 0xffff0000, v92
	v_pk_fma_f32 v[90:91], v[82:83], v[144:145], v[90:91]
	v_lshlrev_b32_e32 v82, 16, v93
	v_and_b32_e32 v83, 0xffff0000, v93
	v_pk_fma_f32 v[86:87], v[86:87], v[148:149], v[94:95]
	v_pk_fma_f32 v[92:93], v[84:85], v[142:143], v[82:83]
	v_cvt_pk_bf16_f32 v82, v86, v87
	v_cvt_pk_bf16_f32 v83, v88, v89
	v_cvt_pk_bf16_f32 v84, v90, v91
	v_cvt_pk_bf16_f32 v85, v92, v93
	global_store_dwordx4 v[102:103], v[82:85], off offset:2304
	s_nop 1
	v_or_b32_e32 v82, 48, v162
	v_ashrrev_i32_e32 v83, 31, v82
	v_lshlrev_b64 v[82:83], 12, v[82:83]
	v_lshl_add_u64 v[82:83], s[12:13], 0, v[82:83]
	v_lshl_add_u64 v[82:83], v[82:83], 0, v[160:161]
	v_mov_b32_e32 v84, v206
	v_mov_b32_e32 v85, v207
	v_mov_b32_e32 v86, v208
	v_mov_b32_e32 v87, v209
	s_nop 0
	v_lshlrev_b32_e32 v88, 16, v84
	v_and_b32_e32 v89, 0xffff0000, v84
	v_lshlrev_b32_e32 v84, 16, v85
	v_and_b32_e32 v85, 0xffff0000, v85
	v_pk_fma_f32 v[80:81], v[80:81], v[152:153], v[84:85]
	v_lshlrev_b32_e32 v84, 16, v86
	v_and_b32_e32 v85, 0xffff0000, v86
	v_pk_fma_f32 v[84:85], v[74:75], v[154:155], v[84:85]
	v_lshlrev_b32_e32 v74, 16, v87
	v_and_b32_e32 v75, 0xffff0000, v87
	v_pk_fma_f32 v[78:79], v[78:79], v[156:157], v[88:89]
	v_pk_fma_f32 v[86:87], v[76:77], v[150:151], v[74:75]
	v_cvt_pk_bf16_f32 v74, v78, v79
	v_cvt_pk_bf16_f32 v75, v80, v81
	v_cvt_pk_bf16_f32 v76, v84, v85
	v_cvt_pk_bf16_f32 v77, v86, v87
	global_store_dwordx4 v[82:83], v[74:77], off offset:2048
	s_nop 1
	v_mov_b32_e32 v74, v210
	v_mov_b32_e32 v75, v211
	v_mov_b32_e32 v76, v212
	v_mov_b32_e32 v77, v213
	s_nop 0
	v_lshlrev_b32_e32 v78, 16, v74
	v_and_b32_e32 v79, 0xffff0000, v74
	v_lshlrev_b32_e32 v74, 16, v75
	v_and_b32_e32 v75, 0xffff0000, v75
	v_pk_fma_f32 v[72:73], v[72:73], v[146:147], v[74:75]
	v_lshlrev_b32_e32 v74, 16, v76
	v_and_b32_e32 v75, 0xffff0000, v76
	v_pk_fma_f32 v[74:75], v[66:67], v[144:145], v[74:75]
	v_lshlrev_b32_e32 v66, 16, v77
	v_and_b32_e32 v67, 0xffff0000, v77
	v_pk_fma_f32 v[70:71], v[70:71], v[148:149], v[78:79]
	v_pk_fma_f32 v[76:77], v[68:69], v[142:143], v[66:67]
	v_cvt_pk_bf16_f32 v66, v70, v71
	v_cvt_pk_bf16_f32 v67, v72, v73
	v_cvt_pk_bf16_f32 v68, v74, v75
	v_cvt_pk_bf16_f32 v69, v76, v77
	v_lshl_add_u64 v[70:71], v[158:159], 0, s[14:15]
	global_store_dwordx4 v[82:83], v[66:69], off offset:2304
	s_nop 1
	v_mov_b32_e32 v66, v214
	v_mov_b32_e32 v67, v215
	v_mov_b32_e32 v68, v216
	v_mov_b32_e32 v69, v217
	s_mov_b64 s[14:15], 0x90000
	s_nop 0
	v_lshlrev_b32_e32 v72, 16, v66
	v_and_b32_e32 v73, 0xffff0000, v66
	v_lshlrev_b32_e32 v66, 16, v67
	v_and_b32_e32 v67, 0xffff0000, v67
	v_pk_fma_f32 v[64:65], v[64:65], v[152:153], v[66:67]
	v_lshlrev_b32_e32 v66, 16, v68
	v_and_b32_e32 v67, 0xffff0000, v68
	v_pk_fma_f32 v[66:67], v[58:59], v[154:155], v[66:67]
	v_lshlrev_b32_e32 v58, 16, v69
	v_and_b32_e32 v59, 0xffff0000, v69
	v_pk_fma_f32 v[62:63], v[62:63], v[156:157], v[72:73]
	v_pk_fma_f32 v[68:69], v[60:61], v[150:151], v[58:59]
	v_cvt_pk_bf16_f32 v58, v62, v63
	v_cvt_pk_bf16_f32 v59, v64, v65
	v_cvt_pk_bf16_f32 v60, v66, v67
	v_cvt_pk_bf16_f32 v61, v68, v69
	global_store_dwordx4 v[70:71], v[58:61], off offset:2048
	s_nop 1
	v_mov_b32_e32 v58, v218
	v_mov_b32_e32 v59, v219
	v_mov_b32_e32 v60, v220
	v_mov_b32_e32 v61, v221
	s_nop 0
	v_lshlrev_b32_e32 v62, 16, v58
	v_and_b32_e32 v63, 0xffff0000, v58
	v_lshlrev_b32_e32 v58, 16, v59
	v_and_b32_e32 v59, 0xffff0000, v59
	v_pk_fma_f32 v[56:57], v[56:57], v[146:147], v[58:59]
	v_lshlrev_b32_e32 v58, 16, v60
	v_and_b32_e32 v59, 0xffff0000, v60
	v_pk_fma_f32 v[58:59], v[50:51], v[144:145], v[58:59]
	v_lshlrev_b32_e32 v50, 16, v61
	v_and_b32_e32 v51, 0xffff0000, v61
	v_pk_fma_f32 v[54:55], v[54:55], v[148:149], v[62:63]
	v_pk_fma_f32 v[60:61], v[52:53], v[142:143], v[50:51]
	v_cvt_pk_bf16_f32 v50, v54, v55
	v_cvt_pk_bf16_f32 v51, v56, v57
	v_cvt_pk_bf16_f32 v52, v58, v59
	v_cvt_pk_bf16_f32 v53, v60, v61
	v_lshl_add_u64 v[54:55], v[158:159], 0, s[14:15]
	global_store_dwordx4 v[70:71], v[50:53], off offset:2304
	s_nop 1
	v_mov_b32_e32 v50, v222
	v_mov_b32_e32 v51, v223
	v_mov_b32_e32 v52, v224
	v_mov_b32_e32 v53, v225
	s_mov_b64 s[14:15], 0xa0000
	s_nop 0
	v_lshlrev_b32_e32 v56, 16, v50
	v_and_b32_e32 v57, 0xffff0000, v50
	v_lshlrev_b32_e32 v50, 16, v51
	v_and_b32_e32 v51, 0xffff0000, v51
	v_pk_fma_f32 v[48:49], v[48:49], v[152:153], v[50:51]
	v_lshlrev_b32_e32 v50, 16, v52
	v_and_b32_e32 v51, 0xffff0000, v52
	v_pk_fma_f32 v[50:51], v[42:43], v[154:155], v[50:51]
	v_lshlrev_b32_e32 v42, 16, v53
	v_and_b32_e32 v43, 0xffff0000, v53
	v_pk_fma_f32 v[46:47], v[46:47], v[156:157], v[56:57]
	v_pk_fma_f32 v[52:53], v[44:45], v[150:151], v[42:43]
	v_cvt_pk_bf16_f32 v42, v46, v47
	v_cvt_pk_bf16_f32 v43, v48, v49
	v_cvt_pk_bf16_f32 v44, v50, v51
	v_cvt_pk_bf16_f32 v45, v52, v53
	global_store_dwordx4 v[54:55], v[42:45], off offset:2048
	s_nop 1
	v_mov_b32_e32 v42, v226
	v_mov_b32_e32 v43, v227
	v_mov_b32_e32 v44, v228
	v_mov_b32_e32 v45, v229
	s_nop 0
	v_lshlrev_b32_e32 v46, 16, v42
	v_and_b32_e32 v47, 0xffff0000, v42
	v_lshlrev_b32_e32 v42, 16, v43
	v_and_b32_e32 v43, 0xffff0000, v43
	v_pk_fma_f32 v[40:41], v[40:41], v[146:147], v[42:43]
	v_lshlrev_b32_e32 v42, 16, v44
	v_and_b32_e32 v43, 0xffff0000, v44
	v_pk_fma_f32 v[42:43], v[34:35], v[144:145], v[42:43]
	v_lshlrev_b32_e32 v34, 16, v45
	v_and_b32_e32 v35, 0xffff0000, v45
	v_pk_fma_f32 v[38:39], v[38:39], v[148:149], v[46:47]
	v_pk_fma_f32 v[44:45], v[36:37], v[142:143], v[34:35]
	v_cvt_pk_bf16_f32 v34, v38, v39
	v_cvt_pk_bf16_f32 v35, v40, v41
	v_cvt_pk_bf16_f32 v36, v42, v43
	v_cvt_pk_bf16_f32 v37, v44, v45
	v_lshl_add_u64 v[38:39], v[158:159], 0, s[14:15]
	global_store_dwordx4 v[54:55], v[34:37], off offset:2304
	s_nop 1
	v_mov_b32_e32 v34, v230
	v_mov_b32_e32 v35, v231
	v_mov_b32_e32 v36, v232
	v_mov_b32_e32 v37, v233
	s_mov_b64 s[14:15], 0xb0000
	s_nop 0
	v_lshlrev_b32_e32 v40, 16, v34
	v_and_b32_e32 v41, 0xffff0000, v34
	v_lshlrev_b32_e32 v34, 16, v35
	v_and_b32_e32 v35, 0xffff0000, v35
	v_pk_fma_f32 v[32:33], v[32:33], v[152:153], v[34:35]
	v_lshlrev_b32_e32 v34, 16, v36
	v_and_b32_e32 v35, 0xffff0000, v36
	v_pk_fma_f32 v[34:35], v[26:27], v[154:155], v[34:35]
	v_lshlrev_b32_e32 v26, 16, v37
	v_and_b32_e32 v27, 0xffff0000, v37
	v_pk_fma_f32 v[30:31], v[30:31], v[156:157], v[40:41]
	v_pk_fma_f32 v[36:37], v[28:29], v[150:151], v[26:27]
	v_cvt_pk_bf16_f32 v26, v30, v31
	v_cvt_pk_bf16_f32 v27, v32, v33
	v_cvt_pk_bf16_f32 v28, v34, v35
	v_cvt_pk_bf16_f32 v29, v36, v37
	global_store_dwordx4 v[38:39], v[26:29], off offset:2048
	s_nop 1
	v_mov_b32_e32 v26, v236
	v_mov_b32_e32 v27, v237
	v_mov_b32_e32 v28, v238
	v_mov_b32_e32 v29, v239
	s_nop 0
	v_lshlrev_b32_e32 v30, 16, v26
	v_and_b32_e32 v31, 0xffff0000, v26
	v_lshlrev_b32_e32 v26, 16, v27
	v_and_b32_e32 v27, 0xffff0000, v27
	v_pk_fma_f32 v[24:25], v[24:25], v[146:147], v[26:27]
	v_lshlrev_b32_e32 v26, 16, v28
	v_and_b32_e32 v27, 0xffff0000, v28
	v_pk_fma_f32 v[26:27], v[18:19], v[144:145], v[26:27]
	v_lshlrev_b32_e32 v18, 16, v29
	v_and_b32_e32 v19, 0xffff0000, v29
	v_pk_fma_f32 v[22:23], v[22:23], v[148:149], v[30:31]
	v_pk_fma_f32 v[28:29], v[20:21], v[142:143], v[18:19]
	v_cvt_pk_bf16_f32 v18, v22, v23
	v_cvt_pk_bf16_f32 v19, v24, v25
	v_cvt_pk_bf16_f32 v20, v26, v27
	v_cvt_pk_bf16_f32 v21, v28, v29
	global_store_dwordx4 v[38:39], v[18:21], off offset:2304
	s_nop 1
	v_lshl_add_u64 v[18:19], v[158:159], 0, s[14:15]
	v_mov_b32_e32 v20, v246
	v_mov_b32_e32 v21, v247
	v_mov_b32_e32 v22, v248
	v_mov_b32_e32 v23, v249
	s_mov_b64 s[14:15], s[6:7]
	s_nop 0
	v_lshlrev_b32_e32 v24, 16, v20
	v_and_b32_e32 v25, 0xffff0000, v20
	v_lshlrev_b32_e32 v20, 16, v21
	v_and_b32_e32 v21, 0xffff0000, v21
	v_pk_fma_f32 v[16:17], v[16:17], v[152:153], v[20:21]
	v_lshlrev_b32_e32 v20, 16, v22
	v_and_b32_e32 v21, 0xffff0000, v22
	v_pk_fma_f32 v[20:21], v[10:11], v[154:155], v[20:21]
	v_lshlrev_b32_e32 v10, 16, v23
	v_and_b32_e32 v11, 0xffff0000, v23
	v_pk_fma_f32 v[14:15], v[14:15], v[156:157], v[24:25]
	v_pk_fma_f32 v[22:23], v[12:13], v[150:151], v[10:11]
	v_cvt_pk_bf16_f32 v10, v14, v15
	v_cvt_pk_bf16_f32 v11, v16, v17
	v_cvt_pk_bf16_f32 v12, v20, v21
	v_cvt_pk_bf16_f32 v13, v22, v23
	global_store_dwordx4 v[18:19], v[10:13], off offset:2048
	s_nop 1
	v_mov_b32_e32 v10, v250
	v_mov_b32_e32 v11, v251
	v_mov_b32_e32 v12, v252
	v_mov_b32_e32 v13, v253
	s_nop 0
	v_lshlrev_b32_e32 v14, 16, v10
	v_and_b32_e32 v15, 0xffff0000, v10
	v_lshlrev_b32_e32 v10, 16, v11
	v_and_b32_e32 v11, 0xffff0000, v11
	v_pk_fma_f32 v[8:9], v[8:9], v[146:147], v[10:11]
	v_lshlrev_b32_e32 v10, 16, v12
	v_and_b32_e32 v11, 0xffff0000, v12
	v_pk_fma_f32 v[10:11], v[2:3], v[144:145], v[10:11]
	v_lshlrev_b32_e32 v2, 16, v13
	v_and_b32_e32 v3, 0xffff0000, v13
	v_pk_fma_f32 v[6:7], v[6:7], v[148:149], v[14:15]
	v_pk_fma_f32 v[12:13], v[4:5], v[142:143], v[2:3]
	v_cvt_pk_bf16_f32 v2, v6, v7
	v_cvt_pk_bf16_f32 v3, v8, v9
	v_cvt_pk_bf16_f32 v4, v10, v11
	v_cvt_pk_bf16_f32 v5, v12, v13
	global_store_dwordx4 v[18:19], v[2:5], off offset:2304
	s_cbranch_vccz .LBB0_363
	s_waitcnt vmcnt(0)
	s_cmpk_gt_u32 s30, 0xff
	s_cbranch_scc1 .LBB0_378
	s_barrier

.LBB0_399:
	s_add_u32 s46, s16, 0x100
	s_addc_u32 s47, s17, 0
	s_mov_b32 s48, -2
	s_add_u32 s16, s14, 0x100
	s_addc_u32 s17, s15, 0
	s_add_i32 s49, 0, 0x10000
	v_add_u32_e32 v154, s49, v164
	ds_read_b128 v[142:145], v154
	ds_read_b128 v[146:149], v154 offset:1024
	ds_read_b128 v[150:153], v154 offset:2048
	ds_read_b128 v[154:157], v154 offset:3072
	s_cmp_eq_u32 s48, 40
	s_cselect_b32 s21, s7, s17
	s_cselect_b32 s20, s6, s16
	s_cselect_b32 s19, s9, s47
	s_cselect_b32 s18, s8, s46
	v_lshl_add_u64 v[162:163], s[14:15], 0, v[138:139]
	s_add_i32 m0, s34, 0xc000
	ds_read_b128 v[158:161], v166
	ds_read_b128 v[168:171], v166 offset:1024
	ds_read_b128 v[172:175], v166 offset:2048
	ds_read_b128 v[190:193], v166 offset:3072
	ds_read_b128 v[194:197], v166 offset:4096
	ds_read_b128 v[198:201], v166 offset:5120
	ds_read_b128 v[202:205], v166 offset:6144
	ds_read_b128 v[206:209], v166 offset:7168
	global_load_lds_dwordx4 v[162:163], off
	v_lshl_add_u64 v[162:163], s[14:15], 0, v[140:141]
	s_add_i32 m0, s34, 0xe000
	s_nop 0
	global_load_lds_dwordx4 v[162:163], off
	s_waitcnt lgkmcnt(8)
	s_barrier
	s_waitcnt lgkmcnt(0)
	s_waitcnt lgkmcnt(0)
	v_mfma_f32_16x16x32_bf16 v[126:129], v[142:145], v[158:161], 0
	v_mfma_f32_16x16x32_bf16 v[122:125], v[150:153], v[158:161], 0
	v_mfma_f32_16x16x32_bf16 v[110:113], v[142:145], v[172:175], 0
	v_mfma_f32_16x16x32_bf16 v[106:109], v[150:153], v[172:175], 0
	v_mfma_f32_16x16x32_bf16 v[94:97], v[142:145], v[194:197], 0
	v_mfma_f32_16x16x32_bf16 v[90:93], v[150:153], v[194:197], 0
	v_mfma_f32_16x16x32_bf16 v[78:81], v[142:145], v[202:205], 0
	v_mfma_f32_16x16x32_bf16 v[74:77], v[150:153], v[202:205], 0
	v_mfma_f32_16x16x32_bf16 v[126:129], v[146:149], v[168:171], v[126:129]
	v_mfma_f32_16x16x32_bf16 v[122:125], v[154:157], v[168:171], v[122:125]
	v_mfma_f32_16x16x32_bf16 v[110:113], v[146:149], v[190:193], v[110:113]
	v_mfma_f32_16x16x32_bf16 v[106:109], v[154:157], v[190:193], v[106:109]
	v_mfma_f32_16x16x32_bf16 v[94:97], v[146:149], v[198:201], v[94:97]
	v_mfma_f32_16x16x32_bf16 v[90:93], v[154:157], v[198:201], v[90:93]
	v_mfma_f32_16x16x32_bf16 v[78:81], v[146:149], v[206:209], v[78:81]
	v_mfma_f32_16x16x32_bf16 v[74:77], v[154:157], v[206:209], v[74:77]
	s_barrier
	s_add_i32 s50, 0, 0x14000
	v_add_u32_e32 v162, s50, v164
	s_add_i32 s14, s49, s33
	ds_read_b128 v[210:213], v162
	ds_read_b128 v[214:217], v162 offset:1024
	ds_read_b128 v[218:221], v162 offset:2048
	ds_read_b128 v[222:225], v162 offset:3072
	s_add_u32 s64, s18, 0x80
	s_addc_u32 s65, s19, 0
	s_mov_b32 m0, s14
	s_nop 0
	global_load_lds_dwordx4 v132, s[18:19]
	s_add_i32 m0, s14, 0x2000
	s_nop 0
	global_load_lds_dwordx4 v136, s[18:19]
	s_barrier
	s_waitcnt lgkmcnt(0)
	s_waitcnt lgkmcnt(0)
	v_mfma_f32_16x16x32_bf16 v[118:121], v[210:213], v[158:161], 0
	v_mfma_f32_16x16x32_bf16 v[114:117], v[218:221], v[158:161], 0
	v_mfma_f32_16x16x32_bf16 v[102:105], v[210:213], v[172:175], 0
	v_mfma_f32_16x16x32_bf16 v[98:101], v[218:221], v[172:175], 0
	v_mfma_f32_16x16x32_bf16 v[86:89], v[210:213], v[194:197], 0
	v_mfma_f32_16x16x32_bf16 v[82:85], v[218:221], v[194:197], 0
	v_mfma_f32_16x16x32_bf16 v[70:73], v[210:213], v[202:205], 0
	v_mfma_f32_16x16x32_bf16 v[66:69], v[218:221], v[202:205], 0
	ds_read_b128 v[158:161], v166 offset:16384
	v_mfma_f32_16x16x32_bf16 v[118:121], v[214:217], v[168:171], v[118:121]
	v_mfma_f32_16x16x32_bf16 v[114:117], v[222:225], v[168:171], v[114:117]
	ds_read_b128 v[172:175], v166 offset:18432
	v_mfma_f32_16x16x32_bf16 v[102:105], v[214:217], v[190:193], v[102:105]
	v_mfma_f32_16x16x32_bf16 v[98:101], v[222:225], v[190:193], v[98:101]
	ds_read_b128 v[194:197], v166 offset:20480
	v_mfma_f32_16x16x32_bf16 v[86:89], v[214:217], v[198:201], v[86:89]
	v_mfma_f32_16x16x32_bf16 v[82:85], v[222:225], v[198:201], v[82:85]
	ds_read_b128 v[202:205], v166 offset:22528
	v_mfma_f32_16x16x32_bf16 v[70:73], v[214:217], v[206:209], v[70:73]
	v_mfma_f32_16x16x32_bf16 v[66:69], v[222:225], v[206:209], v[66:69]
	s_barrier
	s_mov_b32 m0, s34
	s_add_u32 s62, s20, 0x80
	s_addc_u32 s63, s21, 0
	ds_read_b128 v[168:171], v166 offset:17408
	ds_read_b128 v[190:193], v166 offset:19456
	ds_read_b128 v[198:201], v166 offset:21504
	ds_read_b128 v[206:209], v166 offset:23552
	global_load_lds_dwordx4 v130, s[20:21]
	s_mov_b32 m0, s35
	s_nop 0
	global_load_lds_dwordx4 v134, s[20:21]
	s_waitcnt vmcnt(10)
	s_barrier
	s_waitcnt lgkmcnt(0)
	s_waitcnt lgkmcnt(0)
	v_mfma_f32_16x16x32_bf16 v[62:65], v[142:145], v[158:161], 0
	v_mfma_f32_16x16x32_bf16 v[58:61], v[150:153], v[158:161], 0
	v_mfma_f32_16x16x32_bf16 v[46:49], v[142:145], v[172:175], 0
	v_mfma_f32_16x16x32_bf16 v[42:45], v[150:153], v[172:175], 0
	v_mfma_f32_16x16x32_bf16 v[30:33], v[142:145], v[194:197], 0
	v_mfma_f32_16x16x32_bf16 v[26:29], v[150:153], v[194:197], 0
	v_mfma_f32_16x16x32_bf16 v[14:17], v[142:145], v[202:205], 0
	v_mfma_f32_16x16x32_bf16 v[10:13], v[150:153], v[202:205], 0
	v_mfma_f32_16x16x32_bf16 v[62:65], v[146:149], v[168:171], v[62:65]
	v_mfma_f32_16x16x32_bf16 v[58:61], v[154:157], v[168:171], v[58:61]
	v_mfma_f32_16x16x32_bf16 v[46:49], v[146:149], v[190:193], v[46:49]
	v_mfma_f32_16x16x32_bf16 v[42:45], v[154:157], v[190:193], v[42:45]
	v_mfma_f32_16x16x32_bf16 v[30:33], v[146:149], v[198:201], v[30:33]
	v_mfma_f32_16x16x32_bf16 v[26:29], v[154:157], v[198:201], v[26:29]
	v_mfma_f32_16x16x32_bf16 v[14:17], v[146:149], v[206:209], v[14:17]
	v_mfma_f32_16x16x32_bf16 v[10:13], v[154:157], v[206:209], v[10:13]
	s_barrier
	v_add_u32_e32 v154, 0x18000, v164
	ds_read_b128 v[142:145], v154
	ds_read_b128 v[146:149], v154 offset:1024
	ds_read_b128 v[150:153], v154 offset:2048
	ds_read_b128 v[154:157], v154 offset:3072
	s_add_u32 s14, s18, 0xb0000
	s_addc_u32 s15, s19, 0
	s_add_i32 s49, s50, s33
	s_mov_b32 m0, s49
	s_nop 0
	global_load_lds_dwordx4 v132, s[14:15]
	s_add_i32 m0, s49, 0x2000
	s_nop 0
	global_load_lds_dwordx4 v136, s[14:15]
	s_waitcnt vmcnt(6)
	s_barrier
	v_mfma_f32_16x16x32_bf16 v[54:57], v[210:213], v[158:161], 0
	v_mfma_f32_16x16x32_bf16 v[50:53], v[218:221], v[158:161], 0
	v_mfma_f32_16x16x32_bf16 v[38:41], v[210:213], v[172:175], 0
	v_mfma_f32_16x16x32_bf16 v[34:37], v[218:221], v[172:175], 0
	v_mfma_f32_16x16x32_bf16 v[22:25], v[210:213], v[194:197], 0
	v_mfma_f32_16x16x32_bf16 v[18:21], v[218:221], v[194:197], 0
	v_mfma_f32_16x16x32_bf16 v[6:9], v[210:213], v[202:205], 0
	v_mfma_f32_16x16x32_bf16 v[2:5], v[218:221], v[202:205], 0
	v_mfma_f32_16x16x32_bf16 v[54:57], v[214:217], v[168:171], v[54:57]
	v_mfma_f32_16x16x32_bf16 v[50:53], v[222:225], v[168:171], v[50:53]
	v_mfma_f32_16x16x32_bf16 v[38:41], v[214:217], v[190:193], v[38:41]
	v_mfma_f32_16x16x32_bf16 v[34:37], v[222:225], v[190:193], v[34:37]
	v_mfma_f32_16x16x32_bf16 v[22:25], v[214:217], v[198:201], v[22:25]
	v_mfma_f32_16x16x32_bf16 v[18:21], v[222:225], v[198:201], v[18:21]
	v_mfma_f32_16x16x32_bf16 v[6:9], v[214:217], v[206:209], v[6:9]
	v_mfma_f32_16x16x32_bf16 v[2:5], v[222:225], v[206:209], v[2:5]
	s_barrier
	s_add_i32 s49, 0, 0x18000
	s_add_u32 s14, s20, 0xb8000
	s_addc_u32 s15, s21, 0
	s_mov_b32 m0, s36
	ds_read_b128 v[158:161], v166 offset:32768
	ds_read_b128 v[168:171], v166 offset:33792
	ds_read_b128 v[172:175], v166 offset:34816
	ds_read_b128 v[190:193], v166 offset:35840
	ds_read_b128 v[194:197], v166 offset:36864
	ds_read_b128 v[198:201], v166 offset:37888
	ds_read_b128 v[202:205], v166 offset:38912
	ds_read_b128 v[206:209], v166 offset:39936
	global_load_lds_dwordx4 v130, s[14:15]
	s_mov_b32 m0, s37
	s_nop 0
	global_load_lds_dwordx4 v134, s[14:15]
	s_waitcnt lgkmcnt(8)
	s_barrier
	s_waitcnt lgkmcnt(0)
	s_waitcnt lgkmcnt(0)
	v_mfma_f32_16x16x32_bf16 v[126:129], v[142:145], v[158:161], v[126:129]
	v_mfma_f32_16x16x32_bf16 v[122:125], v[150:153], v[158:161], v[122:125]
	v_mfma_f32_16x16x32_bf16 v[110:113], v[142:145], v[172:175], v[110:113]
	v_mfma_f32_16x16x32_bf16 v[106:109], v[150:153], v[172:175], v[106:109]
	v_mfma_f32_16x16x32_bf16 v[94:97], v[142:145], v[194:197], v[94:97]
	v_mfma_f32_16x16x32_bf16 v[90:93], v[150:153], v[194:197], v[90:93]
	v_mfma_f32_16x16x32_bf16 v[78:81], v[142:145], v[202:205], v[78:81]
	v_mfma_f32_16x16x32_bf16 v[74:77], v[150:153], v[202:205], v[74:77]
	v_mfma_f32_16x16x32_bf16 v[126:129], v[146:149], v[168:171], v[126:129]
	v_mfma_f32_16x16x32_bf16 v[122:125], v[154:157], v[168:171], v[122:125]
	v_mfma_f32_16x16x32_bf16 v[110:113], v[146:149], v[190:193], v[110:113]
	v_mfma_f32_16x16x32_bf16 v[106:109], v[154:157], v[190:193], v[106:109]
	v_mfma_f32_16x16x32_bf16 v[94:97], v[146:149], v[198:201], v[94:97]
	v_mfma_f32_16x16x32_bf16 v[90:93], v[154:157], v[198:201], v[90:93]
	v_mfma_f32_16x16x32_bf16 v[78:81], v[146:149], v[206:209], v[78:81]
	v_mfma_f32_16x16x32_bf16 v[74:77], v[154:157], v[206:209], v[74:77]
	s_barrier
	s_add_i32 s20, 0, 0x1c000
	s_add_i32 s14, s49, s33
	v_add_u32_e32 v167, s20, v164
	s_mov_b32 m0, s14
	ds_read_b128 v[210:213], v167
	ds_read_b128 v[214:217], v167 offset:1024
	ds_read_b128 v[218:221], v167 offset:2048
	ds_read_b128 v[222:225], v167 offset:3072
	global_load_lds_dwordx4 v132, s[64:65]
	s_add_i32 m0, s14, 0x2000
	s_nop 0
	global_load_lds_dwordx4 v136, s[64:65]
	s_barrier
	s_waitcnt lgkmcnt(0)
	s_waitcnt lgkmcnt(0)
	v_mfma_f32_16x16x32_bf16 v[118:121], v[210:213], v[158:161], v[118:121]
	v_mfma_f32_16x16x32_bf16 v[114:117], v[218:221], v[158:161], v[114:117]
	v_mfma_f32_16x16x32_bf16 v[102:105], v[210:213], v[172:175], v[102:105]
	v_mfma_f32_16x16x32_bf16 v[98:101], v[218:221], v[172:175], v[98:101]
	v_mfma_f32_16x16x32_bf16 v[86:89], v[210:213], v[194:197], v[86:89]
	v_mfma_f32_16x16x32_bf16 v[82:85], v[218:221], v[194:197], v[82:85]
	v_mfma_f32_16x16x32_bf16 v[70:73], v[210:213], v[202:205], v[70:73]
	v_mfma_f32_16x16x32_bf16 v[66:69], v[218:221], v[202:205], v[66:69]
	ds_read_b128 v[158:161], v166 offset:49152
	v_mfma_f32_16x16x32_bf16 v[118:121], v[214:217], v[168:171], v[118:121]
	v_mfma_f32_16x16x32_bf16 v[114:117], v[222:225], v[168:171], v[114:117]
	ds_read_b128 v[172:175], v166 offset:51200
	v_mfma_f32_16x16x32_bf16 v[102:105], v[214:217], v[190:193], v[102:105]
	v_mfma_f32_16x16x32_bf16 v[98:101], v[222:225], v[190:193], v[98:101]
	ds_read_b128 v[194:197], v166 offset:53248
	v_mfma_f32_16x16x32_bf16 v[86:89], v[214:217], v[198:201], v[86:89]
	v_mfma_f32_16x16x32_bf16 v[82:85], v[222:225], v[198:201], v[82:85]
	ds_read_b128 v[202:205], v166 offset:55296
	v_mfma_f32_16x16x32_bf16 v[70:73], v[214:217], v[206:209], v[70:73]
	v_mfma_f32_16x16x32_bf16 v[66:69], v[222:225], v[206:209], v[66:69]
	s_barrier
	s_mov_b32 m0, s38
	ds_read_b128 v[168:171], v166 offset:50176
	ds_read_b128 v[190:193], v166 offset:52224
	ds_read_b128 v[198:201], v166 offset:54272
	ds_read_b128 v[206:209], v166 offset:56320
	global_load_lds_dwordx4 v130, s[62:63]
	s_mov_b32 m0, s39
	s_nop 0
	global_load_lds_dwordx4 v134, s[62:63]
	s_waitcnt vmcnt(10)
	s_barrier
	s_waitcnt lgkmcnt(0)
	s_waitcnt lgkmcnt(0)
	v_mfma_f32_16x16x32_bf16 v[62:65], v[142:145], v[158:161], v[62:65]
	v_mfma_f32_16x16x32_bf16 v[58:61], v[150:153], v[158:161], v[58:61]
	v_mfma_f32_16x16x32_bf16 v[46:49], v[142:145], v[172:175], v[46:49]
	v_mfma_f32_16x16x32_bf16 v[42:45], v[150:153], v[172:175], v[42:45]
	v_mfma_f32_16x16x32_bf16 v[30:33], v[142:145], v[194:197], v[30:33]
	v_mfma_f32_16x16x32_bf16 v[26:29], v[150:153], v[194:197], v[26:29]
	v_mfma_f32_16x16x32_bf16 v[14:17], v[142:145], v[202:205], v[14:17]
	v_mfma_f32_16x16x32_bf16 v[10:13], v[150:153], v[202:205], v[10:13]
	v_mfma_f32_16x16x32_bf16 v[62:65], v[146:149], v[168:171], v[62:65]
	v_mfma_f32_16x16x32_bf16 v[58:61], v[154:157], v[168:171], v[58:61]
	v_mfma_f32_16x16x32_bf16 v[46:49], v[146:149], v[190:193], v[46:49]
	v_mfma_f32_16x16x32_bf16 v[42:45], v[154:157], v[190:193], v[42:45]
	v_mfma_f32_16x16x32_bf16 v[30:33], v[146:149], v[198:201], v[30:33]
	v_mfma_f32_16x16x32_bf16 v[26:29], v[154:157], v[198:201], v[26:29]
	v_mfma_f32_16x16x32_bf16 v[14:17], v[146:149], v[206:209], v[14:17]
	v_mfma_f32_16x16x32_bf16 v[10:13], v[154:157], v[206:209], v[10:13]
	s_barrier
	v_add_u32_e32 v154, 0x10000, v164
	ds_read_b128 v[142:145], v154
	ds_read_b128 v[146:149], v154 offset:1024
	ds_read_b128 v[150:153], v154 offset:2048
	ds_read_b128 v[154:157], v154 offset:3072
	s_add_u32 s14, s18, 0xb0080
	s_addc_u32 s15, s19, 0
	s_add_i32 s18, s20, s33
	s_mov_b32 m0, s18
	s_nop 0
	global_load_lds_dwordx4 v132, s[14:15]
	s_add_i32 m0, s18, 0x2000
	s_nop 0
	global_load_lds_dwordx4 v136, s[14:15]
	s_waitcnt vmcnt(6)
	s_barrier
	v_mfma_f32_16x16x32_bf16 v[54:57], v[210:213], v[158:161], v[54:57]
	v_mfma_f32_16x16x32_bf16 v[50:53], v[218:221], v[158:161], v[50:53]
	v_mfma_f32_16x16x32_bf16 v[38:41], v[210:213], v[172:175], v[38:41]
	v_mfma_f32_16x16x32_bf16 v[34:37], v[218:221], v[172:175], v[34:37]
	v_mfma_f32_16x16x32_bf16 v[22:25], v[210:213], v[194:197], v[22:25]
	v_mfma_f32_16x16x32_bf16 v[18:21], v[218:221], v[194:197], v[18:21]
	v_mfma_f32_16x16x32_bf16 v[6:9], v[210:213], v[202:205], v[6:9]
	v_mfma_f32_16x16x32_bf16 v[2:5], v[218:221], v[202:205], v[2:5]
	v_mfma_f32_16x16x32_bf16 v[54:57], v[214:217], v[168:171], v[54:57]
	v_mfma_f32_16x16x32_bf16 v[50:53], v[222:225], v[168:171], v[50:53]
	v_mfma_f32_16x16x32_bf16 v[38:41], v[214:217], v[190:193], v[38:41]
	v_mfma_f32_16x16x32_bf16 v[34:37], v[222:225], v[190:193], v[34:37]
	v_mfma_f32_16x16x32_bf16 v[22:25], v[214:217], v[198:201], v[22:25]
	v_mfma_f32_16x16x32_bf16 v[18:21], v[222:225], v[198:201], v[18:21]
	v_mfma_f32_16x16x32_bf16 v[6:9], v[214:217], v[206:209], v[6:9]
	v_mfma_f32_16x16x32_bf16 v[2:5], v[222:225], v[206:209], v[2:5]
	s_barrier
	s_add_i32 s48, s48, 2
	s_add_u32 s46, s46, 0x100
	s_addc_u32 s47, s47, 0
	s_mov_b64 s[14:15], s[16:17]
.LBB0_400:
	s_add_u32 s16, s14, 0x100
	s_addc_u32 s17, s15, 0
	s_add_i32 s49, 0, 0x10000
	s_cmp_eq_u32 s48, 40
	s_cselect_b32 s21, s7, s17
	s_cselect_b32 s20, s6, s16
	s_cselect_b32 s19, s9, s47
	s_cselect_b32 s18, s8, s46
	v_lshl_add_u64 v[162:163], s[14:15], 0, v[138:139]
	s_add_i32 m0, s34, 0xc000
	ds_read_b128 v[158:161], v166
	ds_read_b128 v[168:171], v166 offset:1024
	ds_read_b128 v[172:175], v166 offset:2048
	ds_read_b128 v[190:193], v166 offset:3072
	ds_read_b128 v[194:197], v166 offset:4096
	ds_read_b128 v[198:201], v166 offset:5120
	ds_read_b128 v[202:205], v166 offset:6144
	ds_read_b128 v[206:209], v166 offset:7168
	global_load_lds_dwordx4 v[162:163], off
	v_lshl_add_u64 v[162:163], s[14:15], 0, v[140:141]
	s_add_i32 m0, s34, 0xe000
	s_nop 0
	global_load_lds_dwordx4 v[162:163], off
	s_waitcnt lgkmcnt(8)
	s_barrier
	s_waitcnt lgkmcnt(0)
	s_waitcnt lgkmcnt(0)
	v_mfma_f32_16x16x32_bf16 v[126:129], v[142:145], v[158:161], v[126:129]
	v_mfma_f32_16x16x32_bf16 v[122:125], v[150:153], v[158:161], v[122:125]
	v_mfma_f32_16x16x32_bf16 v[110:113], v[142:145], v[172:175], v[110:113]
	v_mfma_f32_16x16x32_bf16 v[106:109], v[150:153], v[172:175], v[106:109]
	v_mfma_f32_16x16x32_bf16 v[94:97], v[142:145], v[194:197], v[94:97]
	v_mfma_f32_16x16x32_bf16 v[90:93], v[150:153], v[194:197], v[90:93]
	v_mfma_f32_16x16x32_bf16 v[78:81], v[142:145], v[202:205], v[78:81]
	v_mfma_f32_16x16x32_bf16 v[74:77], v[150:153], v[202:205], v[74:77]
	v_mfma_f32_16x16x32_bf16 v[126:129], v[146:149], v[168:171], v[126:129]
	v_mfma_f32_16x16x32_bf16 v[122:125], v[154:157], v[168:171], v[122:125]
	v_mfma_f32_16x16x32_bf16 v[110:113], v[146:149], v[190:193], v[110:113]
	v_mfma_f32_16x16x32_bf16 v[106:109], v[154:157], v[190:193], v[106:109]
	v_mfma_f32_16x16x32_bf16 v[94:97], v[146:149], v[198:201], v[94:97]
	v_mfma_f32_16x16x32_bf16 v[90:93], v[154:157], v[198:201], v[90:93]
	v_mfma_f32_16x16x32_bf16 v[78:81], v[146:149], v[206:209], v[78:81]
	v_mfma_f32_16x16x32_bf16 v[74:77], v[154:157], v[206:209], v[74:77]
	s_barrier
	s_add_i32 s50, 0, 0x14000
	v_add_u32_e32 v162, s50, v164
	s_add_i32 s14, s49, s33
	ds_read_b128 v[210:213], v162
	ds_read_b128 v[214:217], v162 offset:1024
	ds_read_b128 v[218:221], v162 offset:2048
	ds_read_b128 v[222:225], v162 offset:3072
	s_add_u32 s64, s18, 0x80
	s_addc_u32 s65, s19, 0
	s_mov_b32 m0, s14
	s_nop 0
	global_load_lds_dwordx4 v132, s[18:19]
	s_add_i32 m0, s14, 0x2000
	s_nop 0
	global_load_lds_dwordx4 v136, s[18:19]
	s_barrier
	s_waitcnt lgkmcnt(0)
	s_waitcnt lgkmcnt(0)
	v_mfma_f32_16x16x32_bf16 v[118:121], v[210:213], v[158:161], v[118:121]
	v_mfma_f32_16x16x32_bf16 v[114:117], v[218:221], v[158:161], v[114:117]
	v_mfma_f32_16x16x32_bf16 v[102:105], v[210:213], v[172:175], v[102:105]
	v_mfma_f32_16x16x32_bf16 v[98:101], v[218:221], v[172:175], v[98:101]
	v_mfma_f32_16x16x32_bf16 v[86:89], v[210:213], v[194:197], v[86:89]
	v_mfma_f32_16x16x32_bf16 v[82:85], v[218:221], v[194:197], v[82:85]
	v_mfma_f32_16x16x32_bf16 v[70:73], v[210:213], v[202:205], v[70:73]
	v_mfma_f32_16x16x32_bf16 v[66:69], v[218:221], v[202:205], v[66:69]
	ds_read_b128 v[158:161], v166 offset:16384
	v_mfma_f32_16x16x32_bf16 v[118:121], v[214:217], v[168:171], v[118:121]
	v_mfma_f32_16x16x32_bf16 v[114:117], v[222:225], v[168:171], v[114:117]
	ds_read_b128 v[172:175], v166 offset:18432
	v_mfma_f32_16x16x32_bf16 v[102:105], v[214:217], v[190:193], v[102:105]
	v_mfma_f32_16x16x32_bf16 v[98:101], v[222:225], v[190:193], v[98:101]
	ds_read_b128 v[194:197], v166 offset:20480
	v_mfma_f32_16x16x32_bf16 v[86:89], v[214:217], v[198:201], v[86:89]
	v_mfma_f32_16x16x32_bf16 v[82:85], v[222:225], v[198:201], v[82:85]
	ds_read_b128 v[202:205], v166 offset:22528
	v_mfma_f32_16x16x32_bf16 v[70:73], v[214:217], v[206:209], v[70:73]
	v_mfma_f32_16x16x32_bf16 v[66:69], v[222:225], v[206:209], v[66:69]
	s_barrier
	s_mov_b32 m0, s34
	s_add_u32 s62, s20, 0x80
	s_addc_u32 s63, s21, 0
	ds_read_b128 v[168:171], v166 offset:17408
	ds_read_b128 v[190:193], v166 offset:19456
	ds_read_b128 v[198:201], v166 offset:21504
	ds_read_b128 v[206:209], v166 offset:23552
	global_load_lds_dwordx4 v130, s[20:21]
	s_mov_b32 m0, s35
	s_nop 0
	global_load_lds_dwordx4 v134, s[20:21]
	s_waitcnt vmcnt(10)
	s_barrier
	s_waitcnt lgkmcnt(0)
	s_waitcnt lgkmcnt(0)
	v_mfma_f32_16x16x32_bf16 v[62:65], v[142:145], v[158:161], v[62:65]
	v_mfma_f32_16x16x32_bf16 v[58:61], v[150:153], v[158:161], v[58:61]
	v_mfma_f32_16x16x32_bf16 v[46:49], v[142:145], v[172:175], v[46:49]
	v_mfma_f32_16x16x32_bf16 v[42:45], v[150:153], v[172:175], v[42:45]
	v_mfma_f32_16x16x32_bf16 v[30:33], v[142:145], v[194:197], v[30:33]
	v_mfma_f32_16x16x32_bf16 v[26:29], v[150:153], v[194:197], v[26:29]
	v_mfma_f32_16x16x32_bf16 v[14:17], v[142:145], v[202:205], v[14:17]
	v_mfma_f32_16x16x32_bf16 v[10:13], v[150:153], v[202:205], v[10:13]
	v_mfma_f32_16x16x32_bf16 v[62:65], v[146:149], v[168:171], v[62:65]
	v_mfma_f32_16x16x32_bf16 v[58:61], v[154:157], v[168:171], v[58:61]
	v_mfma_f32_16x16x32_bf16 v[46:49], v[146:149], v[190:193], v[46:49]
	v_mfma_f32_16x16x32_bf16 v[42:45], v[154:157], v[190:193], v[42:45]
	v_mfma_f32_16x16x32_bf16 v[30:33], v[146:149], v[198:201], v[30:33]
	v_mfma_f32_16x16x32_bf16 v[26:29], v[154:157], v[198:201], v[26:29]
	v_mfma_f32_16x16x32_bf16 v[14:17], v[146:149], v[206:209], v[14:17]
	v_mfma_f32_16x16x32_bf16 v[10:13], v[154:157], v[206:209], v[10:13]
	s_barrier
	v_add_u32_e32 v154, 0x18000, v164
	ds_read_b128 v[142:145], v154
	ds_read_b128 v[146:149], v154 offset:1024
	ds_read_b128 v[150:153], v154 offset:2048
	ds_read_b128 v[154:157], v154 offset:3072
	s_add_u32 s14, s18, 0xb0000
	s_addc_u32 s15, s19, 0
	s_add_i32 s49, s50, s33
	s_mov_b32 m0, s49
	s_nop 0
	global_load_lds_dwordx4 v132, s[14:15]
	s_add_i32 m0, s49, 0x2000
	s_nop 0
	global_load_lds_dwordx4 v136, s[14:15]
	s_waitcnt vmcnt(6)
	s_barrier
	v_mfma_f32_16x16x32_bf16 v[54:57], v[210:213], v[158:161], v[54:57]
	v_mfma_f32_16x16x32_bf16 v[50:53], v[218:221], v[158:161], v[50:53]
	v_mfma_f32_16x16x32_bf16 v[38:41], v[210:213], v[172:175], v[38:41]
	v_mfma_f32_16x16x32_bf16 v[34:37], v[218:221], v[172:175], v[34:37]
	v_mfma_f32_16x16x32_bf16 v[22:25], v[210:213], v[194:197], v[22:25]
	v_mfma_f32_16x16x32_bf16 v[18:21], v[218:221], v[194:197], v[18:21]
	v_mfma_f32_16x16x32_bf16 v[6:9], v[210:213], v[202:205], v[6:9]
	v_mfma_f32_16x16x32_bf16 v[2:5], v[218:221], v[202:205], v[2:5]
	v_mfma_f32_16x16x32_bf16 v[54:57], v[214:217], v[168:171], v[54:57]
	v_mfma_f32_16x16x32_bf16 v[50:53], v[222:225], v[168:171], v[50:53]
	v_mfma_f32_16x16x32_bf16 v[38:41], v[214:217], v[190:193], v[38:41]
	v_mfma_f32_16x16x32_bf16 v[34:37], v[222:225], v[190:193], v[34:37]
	v_mfma_f32_16x16x32_bf16 v[22:25], v[214:217], v[198:201], v[22:25]
	v_mfma_f32_16x16x32_bf16 v[18:21], v[222:225], v[198:201], v[18:21]
	v_mfma_f32_16x16x32_bf16 v[6:9], v[214:217], v[206:209], v[6:9]
	v_mfma_f32_16x16x32_bf16 v[2:5], v[222:225], v[206:209], v[2:5]
	s_barrier
	s_add_i32 s49, 0, 0x18000
	s_add_u32 s14, s20, 0xb8000
	s_addc_u32 s15, s21, 0
	s_mov_b32 m0, s36
	ds_read_b128 v[158:161], v166 offset:32768
	ds_read_b128 v[168:171], v166 offset:33792
	ds_read_b128 v[172:175], v166 offset:34816
	ds_read_b128 v[190:193], v166 offset:35840
	ds_read_b128 v[194:197], v166 offset:36864
	ds_read_b128 v[198:201], v166 offset:37888
	ds_read_b128 v[202:205], v166 offset:38912
	ds_read_b128 v[206:209], v166 offset:39936
	global_load_lds_dwordx4 v130, s[14:15]
	s_mov_b32 m0, s37
	s_nop 0
	global_load_lds_dwordx4 v134, s[14:15]
	s_waitcnt lgkmcnt(8)
	s_barrier
	s_waitcnt lgkmcnt(0)
	s_waitcnt lgkmcnt(0)
	v_mfma_f32_16x16x32_bf16 v[126:129], v[142:145], v[158:161], v[126:129]
	v_mfma_f32_16x16x32_bf16 v[122:125], v[150:153], v[158:161], v[122:125]
	v_mfma_f32_16x16x32_bf16 v[110:113], v[142:145], v[172:175], v[110:113]
	v_mfma_f32_16x16x32_bf16 v[106:109], v[150:153], v[172:175], v[106:109]
	v_mfma_f32_16x16x32_bf16 v[94:97], v[142:145], v[194:197], v[94:97]
	v_mfma_f32_16x16x32_bf16 v[90:93], v[150:153], v[194:197], v[90:93]
	v_mfma_f32_16x16x32_bf16 v[78:81], v[142:145], v[202:205], v[78:81]
	v_mfma_f32_16x16x32_bf16 v[74:77], v[150:153], v[202:205], v[74:77]
	v_mfma_f32_16x16x32_bf16 v[126:129], v[146:149], v[168:171], v[126:129]
	v_mfma_f32_16x16x32_bf16 v[122:125], v[154:157], v[168:171], v[122:125]
	v_mfma_f32_16x16x32_bf16 v[110:113], v[146:149], v[190:193], v[110:113]
	v_mfma_f32_16x16x32_bf16 v[106:109], v[154:157], v[190:193], v[106:109]
	v_mfma_f32_16x16x32_bf16 v[94:97], v[146:149], v[198:201], v[94:97]
	v_mfma_f32_16x16x32_bf16 v[90:93], v[154:157], v[198:201], v[90:93]
	v_mfma_f32_16x16x32_bf16 v[78:81], v[146:149], v[206:209], v[78:81]
	v_mfma_f32_16x16x32_bf16 v[74:77], v[154:157], v[206:209], v[74:77]
	s_barrier
	s_add_i32 s20, 0, 0x1c000
	s_add_i32 s14, s49, s33
	v_add_u32_e32 v167, s20, v164
	s_mov_b32 m0, s14
	ds_read_b128 v[210:213], v167
	ds_read_b128 v[214:217], v167 offset:1024
	ds_read_b128 v[218:221], v167 offset:2048
	ds_read_b128 v[222:225], v167 offset:3072
	global_load_lds_dwordx4 v132, s[64:65]
	s_add_i32 m0, s14, 0x2000
	s_nop 0
	global_load_lds_dwordx4 v136, s[64:65]
	s_barrier
	s_waitcnt lgkmcnt(0)
	s_waitcnt lgkmcnt(0)
	v_mfma_f32_16x16x32_bf16 v[118:121], v[210:213], v[158:161], v[118:121]
	v_mfma_f32_16x16x32_bf16 v[114:117], v[218:221], v[158:161], v[114:117]
	v_mfma_f32_16x16x32_bf16 v[102:105], v[210:213], v[172:175], v[102:105]
	v_mfma_f32_16x16x32_bf16 v[98:101], v[218:221], v[172:175], v[98:101]
	v_mfma_f32_16x16x32_bf16 v[86:89], v[210:213], v[194:197], v[86:89]
	v_mfma_f32_16x16x32_bf16 v[82:85], v[218:221], v[194:197], v[82:85]
	v_mfma_f32_16x16x32_bf16 v[70:73], v[210:213], v[202:205], v[70:73]
	v_mfma_f32_16x16x32_bf16 v[66:69], v[218:221], v[202:205], v[66:69]
	ds_read_b128 v[158:161], v166 offset:49152
	v_mfma_f32_16x16x32_bf16 v[118:121], v[214:217], v[168:171], v[118:121]
	v_mfma_f32_16x16x32_bf16 v[114:117], v[222:225], v[168:171], v[114:117]
	ds_read_b128 v[172:175], v166 offset:51200
	v_mfma_f32_16x16x32_bf16 v[102:105], v[214:217], v[190:193], v[102:105]
	v_mfma_f32_16x16x32_bf16 v[98:101], v[222:225], v[190:193], v[98:101]
	ds_read_b128 v[194:197], v166 offset:53248
	v_mfma_f32_16x16x32_bf16 v[86:89], v[214:217], v[198:201], v[86:89]
	v_mfma_f32_16x16x32_bf16 v[82:85], v[222:225], v[198:201], v[82:85]
	ds_read_b128 v[202:205], v166 offset:55296
	v_mfma_f32_16x16x32_bf16 v[70:73], v[214:217], v[206:209], v[70:73]
	v_mfma_f32_16x16x32_bf16 v[66:69], v[222:225], v[206:209], v[66:69]
	s_barrier
	s_mov_b32 m0, s38
	ds_read_b128 v[168:171], v166 offset:50176
	ds_read_b128 v[190:193], v166 offset:52224
	ds_read_b128 v[198:201], v166 offset:54272
	ds_read_b128 v[206:209], v166 offset:56320
	global_load_lds_dwordx4 v130, s[62:63]
	s_mov_b32 m0, s39
	s_nop 0
	global_load_lds_dwordx4 v134, s[62:63]
	s_waitcnt vmcnt(10)
	s_barrier
	s_waitcnt lgkmcnt(0)
	s_waitcnt lgkmcnt(0)
	v_mfma_f32_16x16x32_bf16 v[62:65], v[142:145], v[158:161], v[62:65]
	v_mfma_f32_16x16x32_bf16 v[58:61], v[150:153], v[158:161], v[58:61]
	v_mfma_f32_16x16x32_bf16 v[46:49], v[142:145], v[172:175], v[46:49]
	v_mfma_f32_16x16x32_bf16 v[42:45], v[150:153], v[172:175], v[42:45]
	v_mfma_f32_16x16x32_bf16 v[30:33], v[142:145], v[194:197], v[30:33]
	v_mfma_f32_16x16x32_bf16 v[26:29], v[150:153], v[194:197], v[26:29]
	v_mfma_f32_16x16x32_bf16 v[14:17], v[142:145], v[202:205], v[14:17]
	v_mfma_f32_16x16x32_bf16 v[10:13], v[150:153], v[202:205], v[10:13]
	v_mfma_f32_16x16x32_bf16 v[62:65], v[146:149], v[168:171], v[62:65]
	v_mfma_f32_16x16x32_bf16 v[58:61], v[154:157], v[168:171], v[58:61]
	v_mfma_f32_16x16x32_bf16 v[46:49], v[146:149], v[190:193], v[46:49]
	v_mfma_f32_16x16x32_bf16 v[42:45], v[154:157], v[190:193], v[42:45]
	v_mfma_f32_16x16x32_bf16 v[30:33], v[146:149], v[198:201], v[30:33]
	v_mfma_f32_16x16x32_bf16 v[26:29], v[154:157], v[198:201], v[26:29]
	v_mfma_f32_16x16x32_bf16 v[14:17], v[146:149], v[206:209], v[14:17]
	v_mfma_f32_16x16x32_bf16 v[10:13], v[154:157], v[206:209], v[10:13]
	s_barrier
	v_add_u32_e32 v154, 0x10000, v164
	ds_read_b128 v[142:145], v154
	ds_read_b128 v[146:149], v154 offset:1024
	ds_read_b128 v[150:153], v154 offset:2048
	ds_read_b128 v[154:157], v154 offset:3072
	s_add_u32 s14, s18, 0xb0080
	s_addc_u32 s15, s19, 0
	s_add_i32 s18, s20, s33
	s_mov_b32 m0, s18
	s_nop 0
	global_load_lds_dwordx4 v132, s[14:15]
	s_add_i32 m0, s18, 0x2000
	s_nop 0
	global_load_lds_dwordx4 v136, s[14:15]
	s_waitcnt vmcnt(6)
	s_barrier
	v_mfma_f32_16x16x32_bf16 v[54:57], v[210:213], v[158:161], v[54:57]
	v_mfma_f32_16x16x32_bf16 v[50:53], v[218:221], v[158:161], v[50:53]
	v_mfma_f32_16x16x32_bf16 v[38:41], v[210:213], v[172:175], v[38:41]
	v_mfma_f32_16x16x32_bf16 v[34:37], v[218:221], v[172:175], v[34:37]
	v_mfma_f32_16x16x32_bf16 v[22:25], v[210:213], v[194:197], v[22:25]
	v_mfma_f32_16x16x32_bf16 v[18:21], v[218:221], v[194:197], v[18:21]
	v_mfma_f32_16x16x32_bf16 v[6:9], v[210:213], v[202:205], v[6:9]
	v_mfma_f32_16x16x32_bf16 v[2:5], v[218:221], v[202:205], v[2:5]
	v_mfma_f32_16x16x32_bf16 v[54:57], v[214:217], v[168:171], v[54:57]
	v_mfma_f32_16x16x32_bf16 v[50:53], v[222:225], v[168:171], v[50:53]
	v_mfma_f32_16x16x32_bf16 v[38:41], v[214:217], v[190:193], v[38:41]
	v_mfma_f32_16x16x32_bf16 v[34:37], v[222:225], v[190:193], v[34:37]
	v_mfma_f32_16x16x32_bf16 v[22:25], v[214:217], v[198:201], v[22:25]
	v_mfma_f32_16x16x32_bf16 v[18:21], v[222:225], v[198:201], v[18:21]
	v_mfma_f32_16x16x32_bf16 v[6:9], v[214:217], v[206:209], v[6:9]
	v_mfma_f32_16x16x32_bf16 v[2:5], v[222:225], v[206:209], v[2:5]
	s_barrier
	s_add_i32 s48, s48, 2
	s_add_u32 s46, s46, 0x100
	s_addc_u32 s47, s47, 0
	s_cmp_gt_u32 s48, 41
	s_mov_b64 s[14:15], s[16:17]
	s_cbranch_scc0 .LBB0_400
	s_waitcnt lgkmcnt(0)
	s_ashr_i32 s14, s44, 5
	v_lshl_or_b32 v176, s45, 8, v165
	s_mul_hi_i32 s15, s14, 0x9000
	s_mul_i32 s14, s14, 0x9000
	s_add_u32 s14, s26, s14
	v_ashrrev_i32_e32 v177, 31, v176
	s_addc_u32 s15, s27, s15
	v_lshlrev_b64 v[158:159], 2, v[176:177]
	v_lshl_add_u64 v[160:161], s[14:15], 0, v[158:159]
	global_load_dwordx4 v[142:145], v[160:161], off offset:16
	global_load_dwordx4 v[146:149], v[160:161], off
	v_lshl_add_u32 v162, s44, 8, v1
	v_ashrrev_i32_e32 v163, 31, v162
	v_lshl_add_u32 v131, v162, 12, v158
	global_load_dwordx4 v[188:191], v131, s[2:3] offset:16
	global_load_dwordx4 v[192:195], v131, s[2:3]
	global_load_dwordx4 v[196:199], v131, s[2:3] offset:528
	global_load_dwordx4 v[200:203], v131, s[2:3] offset:512
	v_add_u32_e32 v131, 0x10000, v131
	global_load_dwordx4 v[204:207], v131, s[2:3] offset:16
	global_load_dwordx4 v[208:211], v131, s[2:3]
	global_load_dwordx4 v[212:215], v131, s[2:3] offset:528
	global_load_dwordx4 v[216:219], v131, s[2:3] offset:512
	v_add_u32_e32 v131, 0x10000, v131
	global_load_dwordx4 v[220:223], v131, s[2:3] offset:16
	global_load_dwordx4 v[224:227], v131, s[2:3]
	global_load_dwordx4 v[228:231], v131, s[2:3] offset:528
	global_load_dwordx4 v[236:239], v131, s[2:3] offset:512
	v_add_u32_e32 v131, 0x10000, v131
	global_load_dwordx4 v[246:249], v131, s[2:3] offset:16
	global_load_dwordx4 v[250:253], v131, s[2:3]
	v_mov_b32_e32 v133, v131
	s_mov_b64 s[14:15], 0x80000
	s_and_b64 vcc, exec, s[4:5]
	s_mov_b32 s45, s42
	s_mov_b32 s44, s43
	s_mov_b64 s[16:17], s[8:9]
	s_waitcnt vmcnt(14)
	v_pk_add_f32 v[144:145], v[144:145], 1.0 op_sel_hi:[1,0]
	v_pk_add_f32 v[148:149], v[148:149], 1.0 op_sel_hi:[1,0]
	v_pk_add_f32 v[146:147], v[146:147], 1.0 op_sel_hi:[1,0]
	v_pk_add_f32 v[142:143], v[142:143], 1.0 op_sel_hi:[1,0]
	v_pk_mul_f32 v[150:151], v[148:149], 0.5 op_sel_hi:[1,0]
	v_pk_mul_f32 v[152:153], v[146:147], 0.5 op_sel_hi:[1,0]
	v_pk_mul_f32 v[154:155], v[144:145], 0.5 op_sel_hi:[1,0]
	v_pk_mul_f32 v[156:157], v[142:143], 0.5 op_sel_hi:[1,0]
	global_load_dwordx4 v[146:149], v[160:161], off offset:528
	global_load_dwordx4 v[142:145], v[160:161], off offset:512
	s_waitcnt vmcnt(0)
	v_pk_add_f32 v[148:149], v[148:149], 1.0 op_sel_hi:[1,0]
	v_pk_add_f32 v[144:145], v[144:145], 1.0 op_sel_hi:[1,0]
	v_pk_add_f32 v[160:161], v[142:143], 1.0 op_sel_hi:[1,0]
	v_pk_mul_f32 v[142:143], v[144:145], 0.5 op_sel_hi:[1,0]
	v_pk_mul_f32 v[144:145], v[160:161], 0.5 op_sel_hi:[1,0]
	v_pk_add_f32 v[160:161], v[146:147], 1.0 op_sel_hi:[1,0]
	v_pk_mul_f32 v[146:147], v[148:149], 0.5 op_sel_hi:[1,0]
	v_pk_mul_f32 v[148:149], v[160:161], 0.5 op_sel_hi:[1,0]
	v_lshlrev_b64 v[160:161], 12, v[162:163]
	v_lshl_add_u64 v[168:169], s[2:3], 0, v[160:161]
	v_lshl_add_u64 v[186:187], v[168:169], 0, v[158:159]
	v_mov_b32_e32 v168, v188
	v_mov_b32_e32 v169, v189
	v_mov_b32_e32 v170, v190
	v_mov_b32_e32 v171, v191
	v_mov_b32_e32 v172, v192
	v_mov_b32_e32 v173, v193
	v_mov_b32_e32 v174, v194
	v_mov_b32_e32 v175, v195
	global_load_dwordx4 v[188:191], v133, s[2:3] offset:528
	global_load_dwordx4 v[192:195], v133, s[2:3] offset:512
	v_pk_fma_f32 v[122:123], v[122:123], v[156:157], v[168:169]
	v_pk_fma_f32 v[128:129], v[128:129], v[150:151], v[174:175]
	v_pk_fma_f32 v[126:127], v[126:127], v[152:153], v[172:173]
	v_pk_fma_f32 v[170:171], v[124:125], v[154:155], v[170:171]
	v_cvt_pk_bf16_f32 v124, v126, v127
	v_cvt_pk_bf16_f32 v125, v128, v129
	v_cvt_pk_bf16_f32 v126, v122, v123
	v_lshl_add_u64 v[128:129], s[12:13], 0, v[160:161]
	v_lshlrev_b64 v[122:123], 1, v[176:177]
	v_cvt_pk_bf16_f32 v127, v170, v171
	v_lshl_add_u64 v[128:129], v[128:129], 0, v[122:123]
	global_store_dwordx4 v[128:129], v[124:127], off offset:2048
	s_nop 1
	v_mov_b32_e32 v124, v196
	v_mov_b32_e32 v125, v197
	v_mov_b32_e32 v126, v198
	v_mov_b32_e32 v127, v199
	s_nop 0
	v_mov_b32_e32 v168, v200
	v_mov_b32_e32 v169, v201
	v_mov_b32_e32 v170, v202
	v_mov_b32_e32 v171, v203
	v_add_u32_e32 v133, 0x50000, v133
	global_load_dwordx4 v[196:199], v133, s[2:3] offset:16
	global_load_dwordx4 v[200:203], v133, s[2:3]
	v_pk_fma_f32 v[126:127], v[116:117], v[146:147], v[126:127]
	v_pk_fma_f32 v[120:121], v[120:121], v[142:143], v[170:171]
	v_pk_fma_f32 v[118:119], v[118:119], v[144:145], v[168:169]
	v_pk_fma_f32 v[116:117], v[114:115], v[148:149], v[124:125]
	v_cvt_pk_bf16_f32 v114, v118, v119
	v_cvt_pk_bf16_f32 v115, v120, v121
	v_cvt_pk_bf16_f32 v116, v116, v117
	v_cvt_pk_bf16_f32 v117, v126, v127
	global_store_dwordx4 v[128:129], v[114:117], off offset:2304
	s_nop 1
	v_or_b32_e32 v114, 16, v162
	v_ashrrev_i32_e32 v115, 31, v114
	v_lshlrev_b64 v[124:125], 12, v[114:115]
	v_lshl_add_u64 v[114:115], s[2:3], 0, v[124:125]
	v_lshl_add_u64 v[126:127], v[114:115], 0, v[158:159]
	v_mov_b32_e32 v114, v204
	v_mov_b32_e32 v115, v205
	v_mov_b32_e32 v116, v206
	v_mov_b32_e32 v117, v207
	v_mov_b32_e32 v118, v208
	v_mov_b32_e32 v119, v209
	v_mov_b32_e32 v120, v210
	v_mov_b32_e32 v121, v211
	global_load_dwordx4 v[204:207], v133, s[2:3] offset:528
	global_load_dwordx4 v[208:211], v133, s[2:3] offset:512
	v_pk_fma_f32 v[116:117], v[108:109], v[154:155], v[116:117]
	v_pk_fma_f32 v[110:111], v[110:111], v[152:153], v[118:119]
	v_pk_fma_f32 v[112:113], v[112:113], v[150:151], v[120:121]
	v_pk_fma_f32 v[108:109], v[106:107], v[156:157], v[114:115]
	v_cvt_pk_bf16_f32 v106, v110, v111
	v_lshl_add_u64 v[110:111], s[12:13], 0, v[124:125]
	v_cvt_pk_bf16_f32 v107, v112, v113
	v_cvt_pk_bf16_f32 v108, v108, v109
	v_cvt_pk_bf16_f32 v109, v116, v117
	v_lshl_add_u64 v[114:115], v[110:111], 0, v[122:123]
	global_store_dwordx4 v[114:115], v[106:109], off offset:2048
	s_nop 1
	v_mov_b32_e32 v106, v212
	v_mov_b32_e32 v107, v213
	v_mov_b32_e32 v108, v214
	v_mov_b32_e32 v109, v215
	s_nop 0
	v_mov_b32_e32 v110, v216
	v_mov_b32_e32 v111, v217
	v_mov_b32_e32 v112, v218
	v_mov_b32_e32 v113, v219
	v_add_u32_e32 v133, 0x10000, v133
	global_load_dwordx4 v[212:215], v133, s[2:3] offset:16
	global_load_dwordx4 v[216:219], v133, s[2:3]
	v_pk_fma_f32 v[108:109], v[100:101], v[146:147], v[108:109]
	v_pk_fma_f32 v[104:105], v[104:105], v[142:143], v[112:113]
	v_pk_fma_f32 v[102:103], v[102:103], v[144:145], v[110:111]
	v_pk_fma_f32 v[100:101], v[98:99], v[148:149], v[106:107]
	v_cvt_pk_bf16_f32 v98, v102, v103
	v_cvt_pk_bf16_f32 v99, v104, v105
	v_cvt_pk_bf16_f32 v100, v100, v101
	v_cvt_pk_bf16_f32 v101, v108, v109
	global_store_dwordx4 v[114:115], v[98:101], off offset:2304
	s_nop 1
	v_or_b32_e32 v98, 32, v162
	v_ashrrev_i32_e32 v99, 31, v98
	v_lshlrev_b64 v[106:107], 12, v[98:99]
	v_lshl_add_u64 v[98:99], s[2:3], 0, v[106:107]
	v_lshl_add_u64 v[108:109], v[98:99], 0, v[158:159]
	v_mov_b32_e32 v98, v220
	v_mov_b32_e32 v99, v221
	v_mov_b32_e32 v100, v222
	v_mov_b32_e32 v101, v223
	v_mov_b32_e32 v102, v224
	v_mov_b32_e32 v103, v225
	v_mov_b32_e32 v104, v226
	v_mov_b32_e32 v105, v227
	global_load_dwordx4 v[220:223], v133, s[2:3] offset:528
	global_load_dwordx4 v[224:227], v133, s[2:3] offset:512
	v_pk_fma_f32 v[100:101], v[92:93], v[154:155], v[100:101]
	v_pk_fma_f32 v[94:95], v[94:95], v[152:153], v[102:103]
	v_pk_fma_f32 v[96:97], v[96:97], v[150:151], v[104:105]
	v_pk_fma_f32 v[92:93], v[90:91], v[156:157], v[98:99]
	v_cvt_pk_bf16_f32 v90, v94, v95
	v_lshl_add_u64 v[94:95], s[12:13], 0, v[106:107]
	v_cvt_pk_bf16_f32 v91, v96, v97
	v_cvt_pk_bf16_f32 v92, v92, v93
	v_cvt_pk_bf16_f32 v93, v100, v101
	v_lshl_add_u64 v[98:99], v[94:95], 0, v[122:123]
	global_store_dwordx4 v[98:99], v[90:93], off offset:2048
	s_nop 1
	v_mov_b32_e32 v90, v228
	v_mov_b32_e32 v91, v229
	v_mov_b32_e32 v92, v230
	v_mov_b32_e32 v93, v231
	s_nop 0
	v_mov_b32_e32 v94, v236
	v_mov_b32_e32 v95, v237
	v_mov_b32_e32 v96, v238
	v_mov_b32_e32 v97, v239
	v_add_u32_e32 v133, 0x10000, v133
	global_load_dwordx4 v[228:231], v133, s[2:3] offset:16
	global_load_dwordx4 v[236:239], v133, s[2:3]
	v_pk_fma_f32 v[92:93], v[84:85], v[146:147], v[92:93]
	v_pk_fma_f32 v[88:89], v[88:89], v[142:143], v[96:97]
	v_pk_fma_f32 v[86:87], v[86:87], v[144:145], v[94:95]
	v_pk_fma_f32 v[84:85], v[82:83], v[148:149], v[90:91]
	v_cvt_pk_bf16_f32 v82, v86, v87
	v_cvt_pk_bf16_f32 v83, v88, v89
	v_cvt_pk_bf16_f32 v84, v84, v85
	v_cvt_pk_bf16_f32 v85, v92, v93
	global_store_dwordx4 v[98:99], v[82:85], off offset:2304
	s_nop 1
	v_or_b32_e32 v82, 48, v162
	v_ashrrev_i32_e32 v83, 31, v82
	v_lshlrev_b64 v[90:91], 12, v[82:83]
	v_lshl_add_u64 v[82:83], s[2:3], 0, v[90:91]
	v_lshl_add_u64 v[92:93], v[82:83], 0, v[158:159]
	v_mov_b32_e32 v82, v246
	v_mov_b32_e32 v83, v247
	v_mov_b32_e32 v84, v248
	v_mov_b32_e32 v85, v249
	v_mov_b32_e32 v86, v250
	v_mov_b32_e32 v87, v251
	v_mov_b32_e32 v88, v252
	v_mov_b32_e32 v89, v253
	global_load_dwordx4 v[246:249], v133, s[2:3] offset:528
	global_load_dwordx4 v[250:253], v133, s[2:3] offset:512
	v_pk_fma_f32 v[84:85], v[76:77], v[154:155], v[84:85]
	v_pk_fma_f32 v[78:79], v[78:79], v[152:153], v[86:87]
	v_pk_fma_f32 v[80:81], v[80:81], v[150:151], v[88:89]
	v_pk_fma_f32 v[76:77], v[74:75], v[156:157], v[82:83]
	v_cvt_pk_bf16_f32 v74, v78, v79
	v_lshl_add_u64 v[78:79], s[12:13], 0, v[90:91]
	v_cvt_pk_bf16_f32 v75, v80, v81
	v_cvt_pk_bf16_f32 v76, v76, v77
	v_cvt_pk_bf16_f32 v77, v84, v85
	v_lshl_add_u64 v[82:83], v[78:79], 0, v[122:123]
	global_store_dwordx4 v[82:83], v[74:77], off offset:2048
	s_nop 1
	s_waitcnt vmcnt(19)
	v_mov_b32_e32 v74, v188
	v_mov_b32_e32 v75, v189
	v_mov_b32_e32 v76, v190
	v_mov_b32_e32 v77, v191
	s_nop 0
	v_mov_b32_e32 v78, v192
	v_mov_b32_e32 v79, v193
	v_mov_b32_e32 v80, v194
	v_mov_b32_e32 v81, v195
	v_add_u32_e32 v133, 0x10000, v133
	global_load_dwordx4 v[188:191], v133, s[2:3] offset:16
	global_load_dwordx4 v[192:195], v133, s[2:3]
	v_pk_fma_f32 v[76:77], v[68:69], v[146:147], v[76:77]
	v_pk_fma_f32 v[72:73], v[72:73], v[142:143], v[80:81]
	v_pk_fma_f32 v[70:71], v[70:71], v[144:145], v[78:79]
	v_pk_fma_f32 v[68:69], v[66:67], v[148:149], v[74:75]
	v_cvt_pk_bf16_f32 v66, v70, v71
	v_cvt_pk_bf16_f32 v67, v72, v73
	v_cvt_pk_bf16_f32 v68, v68, v69
	v_cvt_pk_bf16_f32 v69, v76, v77
	v_lshl_add_u64 v[74:75], v[160:161], 0, s[14:15]
	global_store_dwordx4 v[82:83], v[66:69], off offset:2304
	s_mov_b64 s[14:15], 0x90000
	s_nop 0
	v_lshl_add_u64 v[66:67], s[2:3], 0, v[74:75]
	v_lshl_add_u64 v[76:77], v[66:67], 0, v[158:159]
	s_waitcnt vmcnt(19)
	v_mov_b32_e32 v66, v196
	v_mov_b32_e32 v67, v197
	v_mov_b32_e32 v68, v198
	v_mov_b32_e32 v69, v199
	v_mov_b32_e32 v70, v200
	v_mov_b32_e32 v71, v201
	v_mov_b32_e32 v72, v202
	v_mov_b32_e32 v73, v203
	global_load_dwordx4 v[196:199], v133, s[2:3] offset:528
	global_load_dwordx4 v[200:203], v133, s[2:3] offset:512
	v_pk_fma_f32 v[68:69], v[60:61], v[154:155], v[68:69]
	v_pk_fma_f32 v[62:63], v[62:63], v[152:153], v[70:71]
	v_pk_fma_f32 v[64:65], v[64:65], v[150:151], v[72:73]
	v_pk_fma_f32 v[60:61], v[58:59], v[156:157], v[66:67]
	v_cvt_pk_bf16_f32 v58, v62, v63
	v_lshl_add_u64 v[62:63], s[12:13], 0, v[74:75]
	v_cvt_pk_bf16_f32 v59, v64, v65
	v_cvt_pk_bf16_f32 v60, v60, v61
	v_cvt_pk_bf16_f32 v61, v68, v69
	v_lshl_add_u64 v[66:67], v[62:63], 0, v[122:123]
	global_store_dwordx4 v[66:67], v[58:61], off offset:2048
	s_nop 1
	s_waitcnt vmcnt(19)
	v_mov_b32_e32 v58, v204
	v_mov_b32_e32 v59, v205
	v_mov_b32_e32 v60, v206
	v_mov_b32_e32 v61, v207
	s_nop 0
	v_mov_b32_e32 v62, v208
	v_mov_b32_e32 v63, v209
	v_mov_b32_e32 v64, v210
	v_mov_b32_e32 v65, v211
	s_nop 0
	v_pk_fma_f32 v[60:61], v[52:53], v[146:147], v[60:61]
	v_pk_fma_f32 v[56:57], v[56:57], v[142:143], v[64:65]
	v_pk_fma_f32 v[54:55], v[54:55], v[144:145], v[62:63]
	v_pk_fma_f32 v[52:53], v[50:51], v[148:149], v[58:59]
	v_cvt_pk_bf16_f32 v50, v54, v55
	v_cvt_pk_bf16_f32 v51, v56, v57
	v_cvt_pk_bf16_f32 v52, v52, v53
	v_cvt_pk_bf16_f32 v53, v60, v61
	v_lshl_add_u64 v[58:59], v[160:161], 0, s[14:15]
	global_store_dwordx4 v[66:67], v[50:53], off offset:2304
	s_mov_b64 s[14:15], 0xa0000
	s_nop 0
	v_lshl_add_u64 v[50:51], s[2:3], 0, v[58:59]
	v_lshl_add_u64 v[60:61], v[50:51], 0, v[158:159]
	s_waitcnt vmcnt(17)
	v_mov_b32_e32 v50, v212
	v_mov_b32_e32 v51, v213
	v_mov_b32_e32 v52, v214
	v_mov_b32_e32 v53, v215
	v_mov_b32_e32 v54, v216
	v_mov_b32_e32 v55, v217
	v_mov_b32_e32 v56, v218
	v_mov_b32_e32 v57, v219
	s_nop 0
	v_pk_fma_f32 v[52:53], v[44:45], v[154:155], v[52:53]
	v_pk_fma_f32 v[46:47], v[46:47], v[152:153], v[54:55]
	v_pk_fma_f32 v[48:49], v[48:49], v[150:151], v[56:57]
	v_pk_fma_f32 v[44:45], v[42:43], v[156:157], v[50:51]
	v_cvt_pk_bf16_f32 v42, v46, v47
	v_lshl_add_u64 v[46:47], s[12:13], 0, v[58:59]
	v_cvt_pk_bf16_f32 v43, v48, v49
	v_cvt_pk_bf16_f32 v44, v44, v45
	v_cvt_pk_bf16_f32 v45, v52, v53
	v_lshl_add_u64 v[50:51], v[46:47], 0, v[122:123]
	global_store_dwordx4 v[50:51], v[42:45], off offset:2048
	s_nop 1
	s_waitcnt vmcnt(15)
	v_mov_b32_e32 v42, v220
	v_mov_b32_e32 v43, v221
	v_mov_b32_e32 v44, v222
	v_mov_b32_e32 v45, v223
	s_nop 0
	v_mov_b32_e32 v46, v224
	v_mov_b32_e32 v47, v225
	v_mov_b32_e32 v48, v226
	v_mov_b32_e32 v49, v227
	s_nop 0
	v_pk_fma_f32 v[44:45], v[36:37], v[146:147], v[44:45]
	v_pk_fma_f32 v[40:41], v[40:41], v[142:143], v[48:49]
	v_pk_fma_f32 v[38:39], v[38:39], v[144:145], v[46:47]
	v_pk_fma_f32 v[36:37], v[34:35], v[148:149], v[42:43]
	v_cvt_pk_bf16_f32 v34, v38, v39
	v_cvt_pk_bf16_f32 v35, v40, v41
	v_cvt_pk_bf16_f32 v36, v36, v37
	v_cvt_pk_bf16_f32 v37, v44, v45
	v_lshl_add_u64 v[42:43], v[160:161], 0, s[14:15]
	global_store_dwordx4 v[50:51], v[34:37], off offset:2304
	s_mov_b64 s[14:15], 0xb0000
	s_nop 0
	v_lshl_add_u64 v[34:35], s[2:3], 0, v[42:43]
	v_lshl_add_u64 v[44:45], v[34:35], 0, v[158:159]
	s_waitcnt vmcnt(13)
	v_mov_b32_e32 v34, v228
	v_mov_b32_e32 v35, v229
	v_mov_b32_e32 v36, v230
	v_mov_b32_e32 v37, v231
	v_mov_b32_e32 v38, v236
	v_mov_b32_e32 v39, v237
	v_mov_b32_e32 v40, v238
	v_mov_b32_e32 v41, v239
	s_nop 0
	v_pk_fma_f32 v[36:37], v[28:29], v[154:155], v[36:37]
	v_pk_fma_f32 v[30:31], v[30:31], v[152:153], v[38:39]
	v_pk_fma_f32 v[32:33], v[32:33], v[150:151], v[40:41]
	v_pk_fma_f32 v[28:29], v[26:27], v[156:157], v[34:35]
	v_cvt_pk_bf16_f32 v26, v30, v31
	v_lshl_add_u64 v[30:31], s[12:13], 0, v[42:43]
	v_cvt_pk_bf16_f32 v27, v32, v33
	v_cvt_pk_bf16_f32 v28, v28, v29
	v_cvt_pk_bf16_f32 v29, v36, v37
	v_lshl_add_u64 v[34:35], v[30:31], 0, v[122:123]
	global_store_dwordx4 v[34:35], v[26:29], off offset:2048
	s_nop 1
	s_waitcnt vmcnt(11)
	v_mov_b32_e32 v26, v246
	v_mov_b32_e32 v27, v247
	v_mov_b32_e32 v28, v248
	v_mov_b32_e32 v29, v249
	s_nop 0
	v_mov_b32_e32 v30, v250
	v_mov_b32_e32 v31, v251
	v_mov_b32_e32 v32, v252
	v_mov_b32_e32 v33, v253
	s_nop 0
	v_pk_fma_f32 v[28:29], v[20:21], v[146:147], v[28:29]
	v_pk_fma_f32 v[24:25], v[24:25], v[142:143], v[32:33]
	v_pk_fma_f32 v[22:23], v[22:23], v[144:145], v[30:31]
	v_pk_fma_f32 v[20:21], v[18:19], v[148:149], v[26:27]
	v_cvt_pk_bf16_f32 v18, v22, v23
	v_cvt_pk_bf16_f32 v19, v24, v25
	v_cvt_pk_bf16_f32 v20, v20, v21
	v_cvt_pk_bf16_f32 v21, v28, v29
	v_lshl_add_u64 v[26:27], v[160:161], 0, s[14:15]
	global_store_dwordx4 v[34:35], v[18:21], off offset:2304
	s_mov_b64 s[14:15], s[6:7]
	s_nop 0
	v_lshl_add_u64 v[18:19], s[2:3], 0, v[26:27]
	v_lshl_add_u64 v[28:29], v[18:19], 0, v[158:159]
	s_waitcnt vmcnt(9)
	v_mov_b32_e32 v18, v188
	v_mov_b32_e32 v19, v189
	v_mov_b32_e32 v20, v190
	v_mov_b32_e32 v21, v191
	v_mov_b32_e32 v22, v192
	v_mov_b32_e32 v23, v193
	v_mov_b32_e32 v24, v194
	v_mov_b32_e32 v25, v195
	s_nop 0
	v_pk_fma_f32 v[20:21], v[12:13], v[154:155], v[20:21]
	v_pk_fma_f32 v[14:15], v[14:15], v[152:153], v[22:23]
	v_pk_fma_f32 v[16:17], v[16:17], v[150:151], v[24:25]
	v_pk_fma_f32 v[12:13], v[10:11], v[156:157], v[18:19]
	v_cvt_pk_bf16_f32 v10, v14, v15
	v_lshl_add_u64 v[14:15], s[12:13], 0, v[26:27]
	v_cvt_pk_bf16_f32 v11, v16, v17
	v_cvt_pk_bf16_f32 v12, v12, v13
	v_cvt_pk_bf16_f32 v13, v20, v21
	v_lshl_add_u64 v[18:19], v[14:15], 0, v[122:123]
	global_store_dwordx4 v[18:19], v[10:13], off offset:2048
	s_nop 1
	s_waitcnt vmcnt(7)
	v_mov_b32_e32 v10, v196
	v_mov_b32_e32 v11, v197
	v_mov_b32_e32 v12, v198
	v_mov_b32_e32 v13, v199
	s_nop 0
	v_mov_b32_e32 v14, v200
	v_mov_b32_e32 v15, v201
	v_mov_b32_e32 v16, v202
	v_mov_b32_e32 v17, v203
	s_nop 0
	v_pk_fma_f32 v[12:13], v[4:5], v[146:147], v[12:13]
	v_pk_fma_f32 v[8:9], v[8:9], v[142:143], v[16:17]
	v_pk_fma_f32 v[6:7], v[6:7], v[144:145], v[14:15]
	v_pk_fma_f32 v[4:5], v[2:3], v[148:149], v[10:11]
	v_cvt_pk_bf16_f32 v2, v6, v7
	v_cvt_pk_bf16_f32 v3, v8, v9
	v_cvt_pk_bf16_f32 v4, v4, v5
	v_cvt_pk_bf16_f32 v5, v12, v13
	global_store_dwordx4 v[18:19], v[2:5], off offset:2304
	s_cbranch_vccz .LBB0_389
	s_waitcnt vmcnt(0)
	s_cmpk_gt_u32 s30, 0xff
	s_cbranch_scc1 .LBB0_404
	s_barrier

.LBB0_527:
	v_mov_b64_e32 v[2:3], s[80:81]
	s_ashr_i32 s15, s14, 31
	v_cmp_lt_i64_e32 vcc, s[16:17], v[2:3]
	s_lshl_b64 s[16:17], s[14:15], 19
	s_add_u32 s16, s29, s16
	s_addc_u32 s17, s30, s17
	s_and_b64 s[18:19], vcc, exec
	s_cselect_b32 s11, s17, s21
	s_cselect_b32 s15, s16, s20
	s_ashr_i32 s13, s12, 31
	s_lshl_b64 s[18:19], s[12:13], 19
	s_add_u32 s18, s31, s18
	s_addc_u32 s19, s33, s19
	s_and_b64 s[24:25], vcc, exec
	s_cselect_b32 s13, s19, s23
	s_cselect_b32 s51, s18, s22
	s_add_u32 s20, s20, 0x40080
	s_addc_u32 s21, s21, 0
	s_add_u32 s52, s22, 0x100
	s_addc_u32 s53, s23, 0
	s_mov_b32 s54, -2
	s_add_u32 s22, s20, 0xfffc0080
	s_addc_u32 s23, s21, -1
	s_add_i32 s55, 0, 0x10000
	v_add_u32_e32 v144, s55, v146
	ds_read_b128 v[150:153], v144
	ds_read_b128 v[154:157], v144 offset:1024
	ds_read_b128 v[158:161], v144 offset:2048
	ds_read_b128 v[162:165], v144 offset:3072
	s_cmp_eq_u32 s54, 12
	s_cselect_b32 s25, s11, s23
	s_cselect_b32 s24, s15, s22
	s_cselect_b32 s23, s13, s53
	s_cselect_b32 s22, s51, s52
	s_add_i32 m0, s41, 0xc000
	ds_read_b128 v[166:169], v148
	ds_read_b128 v[170:173], v148 offset:1024
	ds_read_b128 v[174:177], v148 offset:2048
	ds_read_b128 v[190:193], v148 offset:3072
	ds_read_b128 v[194:197], v148 offset:4096
	ds_read_b128 v[198:201], v148 offset:5120
	ds_read_b128 v[202:205], v148 offset:6144
	ds_read_b128 v[206:209], v148 offset:7168
	global_load_lds_dwordx4 v140, s[20:21]
	v_lshl_add_u64 v[144:145], s[20:21], 0, v[142:143]
	s_add_i32 m0, s41, 0xe000
	s_nop 0
	global_load_lds_dwordx4 v[144:145], off
	s_waitcnt lgkmcnt(8)
	s_barrier
	s_waitcnt lgkmcnt(0)
	s_waitcnt lgkmcnt(0)
	v_mfma_f32_16x16x32_bf16 v[86:89], v[150:153], v[166:169], 0
	v_mfma_f32_16x16x32_bf16 v[82:85], v[158:161], v[166:169], 0
	v_mfma_f32_16x16x32_bf16 v[78:81], v[150:153], v[174:177], 0
	v_mfma_f32_16x16x32_bf16 v[74:77], v[158:161], v[174:177], 0
	v_mfma_f32_16x16x32_bf16 v[62:65], v[150:153], v[194:197], 0
	v_mfma_f32_16x16x32_bf16 v[58:61], v[158:161], v[194:197], 0
	v_mfma_f32_16x16x32_bf16 v[54:57], v[150:153], v[202:205], 0
	v_mfma_f32_16x16x32_bf16 v[50:53], v[158:161], v[202:205], 0
	v_mfma_f32_16x16x32_bf16 v[86:89], v[154:157], v[170:173], v[86:89]
	v_mfma_f32_16x16x32_bf16 v[82:85], v[162:165], v[170:173], v[82:85]
	v_mfma_f32_16x16x32_bf16 v[78:81], v[154:157], v[190:193], v[78:81]
	v_mfma_f32_16x16x32_bf16 v[74:77], v[162:165], v[190:193], v[74:77]
	v_mfma_f32_16x16x32_bf16 v[62:65], v[154:157], v[198:201], v[62:65]
	v_mfma_f32_16x16x32_bf16 v[58:61], v[162:165], v[198:201], v[58:61]
	v_mfma_f32_16x16x32_bf16 v[54:57], v[154:157], v[206:209], v[54:57]
	v_mfma_f32_16x16x32_bf16 v[50:53], v[162:165], v[206:209], v[50:53]
	s_barrier
	s_add_i32 s58, 0, 0x14000
	v_add_u32_e32 v144, s58, v146
	s_add_i32 s55, s55, s35
	ds_read_b128 v[210:213], v144
	ds_read_b128 v[214:217], v144 offset:1024
	ds_read_b128 v[218:221], v144 offset:2048
	ds_read_b128 v[222:225], v144 offset:3072
	s_add_u32 s64, s22, 0x80
	s_addc_u32 s65, s23, 0
	s_mov_b32 m0, s55
	s_nop 0
	global_load_lds_dwordx4 v134, s[22:23]
	s_add_i32 m0, s55, 0x2000
	s_nop 0
	global_load_lds_dwordx4 v130, s[22:23]
	s_barrier
	s_waitcnt lgkmcnt(0)
	s_waitcnt lgkmcnt(0)
	v_mfma_f32_16x16x32_bf16 v[126:129], v[210:213], v[166:169], 0
	v_mfma_f32_16x16x32_bf16 v[122:125], v[218:221], v[166:169], 0
	v_mfma_f32_16x16x32_bf16 v[118:121], v[210:213], v[174:177], 0
	v_mfma_f32_16x16x32_bf16 v[114:117], v[218:221], v[174:177], 0
	v_mfma_f32_16x16x32_bf16 v[110:113], v[210:213], v[194:197], 0
	v_mfma_f32_16x16x32_bf16 v[106:109], v[218:221], v[194:197], 0
	v_mfma_f32_16x16x32_bf16 v[102:105], v[210:213], v[202:205], 0
	v_mfma_f32_16x16x32_bf16 v[98:101], v[218:221], v[202:205], 0
	ds_read_b128 v[166:169], v148 offset:16384
	v_mfma_f32_16x16x32_bf16 v[126:129], v[214:217], v[170:173], v[126:129]
	v_mfma_f32_16x16x32_bf16 v[122:125], v[222:225], v[170:173], v[122:125]
	ds_read_b128 v[174:177], v148 offset:18432
	v_mfma_f32_16x16x32_bf16 v[118:121], v[214:217], v[190:193], v[118:121]
	v_mfma_f32_16x16x32_bf16 v[114:117], v[222:225], v[190:193], v[114:117]
	ds_read_b128 v[194:197], v148 offset:20480
	v_mfma_f32_16x16x32_bf16 v[110:113], v[214:217], v[198:201], v[110:113]
	v_mfma_f32_16x16x32_bf16 v[106:109], v[222:225], v[198:201], v[106:109]
	ds_read_b128 v[202:205], v148 offset:22528
	v_mfma_f32_16x16x32_bf16 v[102:105], v[214:217], v[206:209], v[102:105]
	v_mfma_f32_16x16x32_bf16 v[98:101], v[222:225], v[206:209], v[98:101]
	s_barrier
	s_mov_b32 m0, s41
	s_add_u32 s62, s24, 0x80
	s_addc_u32 s63, s25, 0
	ds_read_b128 v[170:173], v148 offset:17408
	ds_read_b128 v[190:193], v148 offset:19456
	ds_read_b128 v[198:201], v148 offset:21504
	ds_read_b128 v[206:209], v148 offset:23552
	global_load_lds_dwordx4 v136, s[24:25]
	s_mov_b32 m0, s42
	s_nop 0
	global_load_lds_dwordx4 v132, s[24:25]
	s_waitcnt vmcnt(10)
	s_barrier
	s_waitcnt lgkmcnt(0)
	s_waitcnt lgkmcnt(0)
	v_mfma_f32_16x16x32_bf16 v[34:37], v[150:153], v[166:169], 0
	v_mfma_f32_16x16x32_bf16 v[26:29], v[158:161], v[166:169], 0
	v_mfma_f32_16x16x32_bf16 v[22:25], v[150:153], v[174:177], 0
	v_mfma_f32_16x16x32_bf16 v[18:21], v[158:161], v[174:177], 0
	v_mfma_f32_16x16x32_bf16 v[14:17], v[150:153], v[194:197], 0
	v_mfma_f32_16x16x32_bf16 v[10:13], v[158:161], v[194:197], 0
	v_mfma_f32_16x16x32_bf16 v[6:9], v[150:153], v[202:205], 0
	v_mfma_f32_16x16x32_bf16 v[2:5], v[158:161], v[202:205], 0
	v_mfma_f32_16x16x32_bf16 v[34:37], v[154:157], v[170:173], v[34:37]
	v_mfma_f32_16x16x32_bf16 v[26:29], v[162:165], v[170:173], v[26:29]
	v_mfma_f32_16x16x32_bf16 v[22:25], v[154:157], v[190:193], v[22:25]
	v_mfma_f32_16x16x32_bf16 v[18:21], v[162:165], v[190:193], v[18:21]
	v_mfma_f32_16x16x32_bf16 v[14:17], v[154:157], v[198:201], v[14:17]
	v_mfma_f32_16x16x32_bf16 v[10:13], v[162:165], v[198:201], v[10:13]
	v_mfma_f32_16x16x32_bf16 v[6:9], v[154:157], v[206:209], v[6:9]
	v_mfma_f32_16x16x32_bf16 v[2:5], v[162:165], v[206:209], v[2:5]
	s_barrier
	v_add_u32_e32 v162, 0x18000, v146
	ds_read_b128 v[150:153], v162
	ds_read_b128 v[154:157], v162 offset:1024
	ds_read_b128 v[158:161], v162 offset:2048
	ds_read_b128 v[162:165], v162 offset:3072
	s_add_u32 s56, s22, 0x40000
	s_addc_u32 s57, s23, 0
	s_add_i32 s55, s58, s35
	s_mov_b32 m0, s55
	s_nop 0
	global_load_lds_dwordx4 v134, s[56:57]
	s_add_i32 m0, s55, 0x2000
	s_nop 0
	global_load_lds_dwordx4 v130, s[56:57]
	s_waitcnt vmcnt(6)
	s_barrier
	v_mfma_f32_16x16x32_bf16 v[94:97], v[210:213], v[166:169], 0
	v_mfma_f32_16x16x32_bf16 v[90:93], v[218:221], v[166:169], 0
	v_mfma_f32_16x16x32_bf16 v[70:73], v[210:213], v[174:177], 0
	v_mfma_f32_16x16x32_bf16 v[66:69], v[218:221], v[174:177], 0
	v_mfma_f32_16x16x32_bf16 v[46:49], v[210:213], v[194:197], 0
	v_mfma_f32_16x16x32_bf16 v[42:45], v[218:221], v[194:197], 0
	v_mfma_f32_16x16x32_bf16 v[38:41], v[210:213], v[202:205], 0
	v_mfma_f32_16x16x32_bf16 v[30:33], v[218:221], v[202:205], 0
	v_mfma_f32_16x16x32_bf16 v[94:97], v[214:217], v[170:173], v[94:97]
	v_mfma_f32_16x16x32_bf16 v[90:93], v[222:225], v[170:173], v[90:93]
	v_mfma_f32_16x16x32_bf16 v[70:73], v[214:217], v[190:193], v[70:73]
	v_mfma_f32_16x16x32_bf16 v[66:69], v[222:225], v[190:193], v[66:69]
	v_mfma_f32_16x16x32_bf16 v[46:49], v[214:217], v[198:201], v[46:49]
	v_mfma_f32_16x16x32_bf16 v[42:45], v[222:225], v[198:201], v[42:45]
	v_mfma_f32_16x16x32_bf16 v[38:41], v[214:217], v[206:209], v[38:41]
	v_mfma_f32_16x16x32_bf16 v[30:33], v[222:225], v[206:209], v[30:33]
	s_barrier
	s_add_i32 s55, 0, 0x18000
	v_add_u32_e32 v149, s55, v146
	s_add_u32 s24, s24, 0x40000
	s_addc_u32 s25, s25, 0
	s_mov_b32 m0, s43
	ds_read_b128 v[166:169], v148 offset:32768
	ds_read_b128 v[170:173], v148 offset:33792
	ds_read_b128 v[174:177], v148 offset:34816
	ds_read_b128 v[190:193], v148 offset:35840
	ds_read_b128 v[194:197], v148 offset:36864
	ds_read_b128 v[198:201], v148 offset:37888
	ds_read_b128 v[202:205], v148 offset:38912
	ds_read_b128 v[206:209], v148 offset:39936
	global_load_lds_dwordx4 v136, s[24:25]
	s_mov_b32 m0, s44
	s_nop 0
	global_load_lds_dwordx4 v132, s[24:25]
	s_waitcnt lgkmcnt(8)
	s_barrier
	s_waitcnt lgkmcnt(0)
	s_waitcnt lgkmcnt(0)
	v_mfma_f32_16x16x32_bf16 v[86:89], v[150:153], v[166:169], v[86:89]
	v_mfma_f32_16x16x32_bf16 v[82:85], v[158:161], v[166:169], v[82:85]
	v_mfma_f32_16x16x32_bf16 v[78:81], v[150:153], v[174:177], v[78:81]
	v_mfma_f32_16x16x32_bf16 v[74:77], v[158:161], v[174:177], v[74:77]
	v_mfma_f32_16x16x32_bf16 v[62:65], v[150:153], v[194:197], v[62:65]
	v_mfma_f32_16x16x32_bf16 v[58:61], v[158:161], v[194:197], v[58:61]
	v_mfma_f32_16x16x32_bf16 v[54:57], v[150:153], v[202:205], v[54:57]
	v_mfma_f32_16x16x32_bf16 v[50:53], v[158:161], v[202:205], v[50:53]
	v_mfma_f32_16x16x32_bf16 v[86:89], v[154:157], v[170:173], v[86:89]
	v_mfma_f32_16x16x32_bf16 v[82:85], v[162:165], v[170:173], v[82:85]
	v_mfma_f32_16x16x32_bf16 v[78:81], v[154:157], v[190:193], v[78:81]
	v_mfma_f32_16x16x32_bf16 v[74:77], v[162:165], v[190:193], v[74:77]
	v_mfma_f32_16x16x32_bf16 v[62:65], v[154:157], v[198:201], v[62:65]
	v_mfma_f32_16x16x32_bf16 v[58:61], v[162:165], v[198:201], v[58:61]
	v_mfma_f32_16x16x32_bf16 v[54:57], v[154:157], v[206:209], v[54:57]
	v_mfma_f32_16x16x32_bf16 v[50:53], v[162:165], v[206:209], v[50:53]
	s_barrier
	s_add_i32 s24, 0, 0x1c000
	s_add_i32 s25, s55, s35
	v_add_u32_e32 v149, s24, v146
	s_mov_b32 m0, s25
	ds_read_b128 v[210:213], v149
	ds_read_b128 v[214:217], v149 offset:1024
	ds_read_b128 v[218:221], v149 offset:2048
	ds_read_b128 v[222:225], v149 offset:3072
	global_load_lds_dwordx4 v134, s[64:65]
	s_add_i32 m0, s25, 0x2000
	s_nop 0
	global_load_lds_dwordx4 v130, s[64:65]
	s_barrier
	s_waitcnt lgkmcnt(0)
	s_waitcnt lgkmcnt(0)
	v_mfma_f32_16x16x32_bf16 v[126:129], v[210:213], v[166:169], v[126:129]
	v_mfma_f32_16x16x32_bf16 v[122:125], v[218:221], v[166:169], v[122:125]
	v_mfma_f32_16x16x32_bf16 v[118:121], v[210:213], v[174:177], v[118:121]
	v_mfma_f32_16x16x32_bf16 v[114:117], v[218:221], v[174:177], v[114:117]
	v_mfma_f32_16x16x32_bf16 v[110:113], v[210:213], v[194:197], v[110:113]
	v_mfma_f32_16x16x32_bf16 v[106:109], v[218:221], v[194:197], v[106:109]
	v_mfma_f32_16x16x32_bf16 v[102:105], v[210:213], v[202:205], v[102:105]
	v_mfma_f32_16x16x32_bf16 v[98:101], v[218:221], v[202:205], v[98:101]
	ds_read_b128 v[166:169], v148 offset:49152
	v_mfma_f32_16x16x32_bf16 v[126:129], v[214:217], v[170:173], v[126:129]
	v_mfma_f32_16x16x32_bf16 v[122:125], v[222:225], v[170:173], v[122:125]
	ds_read_b128 v[174:177], v148 offset:51200
	v_mfma_f32_16x16x32_bf16 v[118:121], v[214:217], v[190:193], v[118:121]
	v_mfma_f32_16x16x32_bf16 v[114:117], v[222:225], v[190:193], v[114:117]
	ds_read_b128 v[194:197], v148 offset:53248
	v_mfma_f32_16x16x32_bf16 v[110:113], v[214:217], v[198:201], v[110:113]
	v_mfma_f32_16x16x32_bf16 v[106:109], v[222:225], v[198:201], v[106:109]
	ds_read_b128 v[202:205], v148 offset:55296
	v_mfma_f32_16x16x32_bf16 v[102:105], v[214:217], v[206:209], v[102:105]
	v_mfma_f32_16x16x32_bf16 v[98:101], v[222:225], v[206:209], v[98:101]
	s_barrier
	s_mov_b32 m0, s46
	ds_read_b128 v[170:173], v148 offset:50176
	ds_read_b128 v[190:193], v148 offset:52224
	ds_read_b128 v[198:201], v148 offset:54272
	ds_read_b128 v[206:209], v148 offset:56320
	global_load_lds_dwordx4 v136, s[62:63]
	s_mov_b32 m0, s47
	s_nop 0
	global_load_lds_dwordx4 v132, s[62:63]
	s_waitcnt vmcnt(10)
	s_barrier
	s_waitcnt lgkmcnt(0)
	s_waitcnt lgkmcnt(0)
	v_mfma_f32_16x16x32_bf16 v[34:37], v[150:153], v[166:169], v[34:37]
	v_mfma_f32_16x16x32_bf16 v[26:29], v[158:161], v[166:169], v[26:29]
	v_mfma_f32_16x16x32_bf16 v[22:25], v[150:153], v[174:177], v[22:25]
	v_mfma_f32_16x16x32_bf16 v[18:21], v[158:161], v[174:177], v[18:21]
	v_mfma_f32_16x16x32_bf16 v[14:17], v[150:153], v[194:197], v[14:17]
	v_mfma_f32_16x16x32_bf16 v[10:13], v[158:161], v[194:197], v[10:13]
	v_mfma_f32_16x16x32_bf16 v[6:9], v[150:153], v[202:205], v[6:9]
	v_mfma_f32_16x16x32_bf16 v[2:5], v[158:161], v[202:205], v[2:5]
	v_mfma_f32_16x16x32_bf16 v[34:37], v[154:157], v[170:173], v[34:37]
	v_mfma_f32_16x16x32_bf16 v[26:29], v[162:165], v[170:173], v[26:29]
	v_mfma_f32_16x16x32_bf16 v[22:25], v[154:157], v[190:193], v[22:25]
	v_mfma_f32_16x16x32_bf16 v[18:21], v[162:165], v[190:193], v[18:21]
	v_mfma_f32_16x16x32_bf16 v[14:17], v[154:157], v[198:201], v[14:17]
	v_mfma_f32_16x16x32_bf16 v[10:13], v[162:165], v[198:201], v[10:13]
	v_mfma_f32_16x16x32_bf16 v[6:9], v[154:157], v[206:209], v[6:9]
	v_mfma_f32_16x16x32_bf16 v[2:5], v[162:165], v[206:209], v[2:5]
	s_barrier
	v_add_u32_e32 v162, 0x10000, v146
	ds_read_b128 v[150:153], v162
	ds_read_b128 v[154:157], v162 offset:1024
	ds_read_b128 v[158:161], v162 offset:2048
	ds_read_b128 v[162:165], v162 offset:3072
	s_add_u32 s22, s22, 0x40080
	s_addc_u32 s23, s23, 0
	s_add_i32 s24, s24, s35
	s_mov_b32 m0, s24
	s_nop 0
	global_load_lds_dwordx4 v134, s[22:23]
	v_lshl_add_u64 v[144:145], s[22:23], 0, v[130:131]
	s_add_i32 m0, s24, 0x2000
	s_nop 0
	global_load_lds_dwordx4 v[144:145], off
	s_waitcnt vmcnt(6)
	s_barrier
	v_mfma_f32_16x16x32_bf16 v[94:97], v[210:213], v[166:169], v[94:97]
	v_mfma_f32_16x16x32_bf16 v[90:93], v[218:221], v[166:169], v[90:93]
	v_mfma_f32_16x16x32_bf16 v[70:73], v[210:213], v[174:177], v[70:73]
	v_mfma_f32_16x16x32_bf16 v[66:69], v[218:221], v[174:177], v[66:69]
	v_mfma_f32_16x16x32_bf16 v[46:49], v[210:213], v[194:197], v[46:49]
	v_mfma_f32_16x16x32_bf16 v[42:45], v[218:221], v[194:197], v[42:45]
	v_mfma_f32_16x16x32_bf16 v[38:41], v[210:213], v[202:205], v[38:41]
	v_mfma_f32_16x16x32_bf16 v[30:33], v[218:221], v[202:205], v[30:33]
	v_mfma_f32_16x16x32_bf16 v[94:97], v[214:217], v[170:173], v[94:97]
	v_mfma_f32_16x16x32_bf16 v[90:93], v[222:225], v[170:173], v[90:93]
	v_mfma_f32_16x16x32_bf16 v[70:73], v[214:217], v[190:193], v[70:73]
	v_mfma_f32_16x16x32_bf16 v[66:69], v[222:225], v[190:193], v[66:69]
	v_mfma_f32_16x16x32_bf16 v[46:49], v[214:217], v[198:201], v[46:49]
	v_mfma_f32_16x16x32_bf16 v[42:45], v[222:225], v[198:201], v[42:45]
	v_mfma_f32_16x16x32_bf16 v[38:41], v[214:217], v[206:209], v[38:41]
	v_mfma_f32_16x16x32_bf16 v[30:33], v[222:225], v[206:209], v[30:33]
	s_barrier
	s_add_i32 s54, s54, 2
	s_add_u32 s20, s20, 0x100
	s_addc_u32 s21, s21, 0
	s_add_u32 s52, s52, 0x100
	s_addc_u32 s53, s53, 0
.LBB0_528:
	s_add_u32 s22, s20, 0xfffc0080
	s_addc_u32 s23, s21, -1
	s_add_i32 s55, 0, 0x10000
	v_add_u32_e32 v144, s55, v146
	s_cmp_eq_u32 s54, 12
	s_cselect_b32 s25, s11, s23
	s_cselect_b32 s24, s15, s22
	s_cselect_b32 s23, s13, s53
	s_cselect_b32 s22, s51, s52
	s_add_i32 m0, s41, 0xc000
	ds_read_b128 v[166:169], v148
	ds_read_b128 v[170:173], v148 offset:1024
	ds_read_b128 v[174:177], v148 offset:2048
	ds_read_b128 v[190:193], v148 offset:3072
	ds_read_b128 v[194:197], v148 offset:4096
	ds_read_b128 v[198:201], v148 offset:5120
	ds_read_b128 v[202:205], v148 offset:6144
	ds_read_b128 v[206:209], v148 offset:7168
	global_load_lds_dwordx4 v140, s[20:21]
	v_lshl_add_u64 v[144:145], s[20:21], 0, v[142:143]
	s_add_i32 m0, s41, 0xe000
	s_nop 0
	global_load_lds_dwordx4 v[144:145], off
	s_waitcnt lgkmcnt(8)
	s_barrier
	s_waitcnt lgkmcnt(0)
	s_waitcnt lgkmcnt(0)
	v_mfma_f32_16x16x32_bf16 v[86:89], v[150:153], v[166:169], v[86:89]
	v_mfma_f32_16x16x32_bf16 v[82:85], v[158:161], v[166:169], v[82:85]
	v_mfma_f32_16x16x32_bf16 v[78:81], v[150:153], v[174:177], v[78:81]
	v_mfma_f32_16x16x32_bf16 v[74:77], v[158:161], v[174:177], v[74:77]
	v_mfma_f32_16x16x32_bf16 v[62:65], v[150:153], v[194:197], v[62:65]
	v_mfma_f32_16x16x32_bf16 v[58:61], v[158:161], v[194:197], v[58:61]
	v_mfma_f32_16x16x32_bf16 v[54:57], v[150:153], v[202:205], v[54:57]
	v_mfma_f32_16x16x32_bf16 v[50:53], v[158:161], v[202:205], v[50:53]
	v_mfma_f32_16x16x32_bf16 v[86:89], v[154:157], v[170:173], v[86:89]
	v_mfma_f32_16x16x32_bf16 v[82:85], v[162:165], v[170:173], v[82:85]
	v_mfma_f32_16x16x32_bf16 v[78:81], v[154:157], v[190:193], v[78:81]
	v_mfma_f32_16x16x32_bf16 v[74:77], v[162:165], v[190:193], v[74:77]
	v_mfma_f32_16x16x32_bf16 v[62:65], v[154:157], v[198:201], v[62:65]
	v_mfma_f32_16x16x32_bf16 v[58:61], v[162:165], v[198:201], v[58:61]
	v_mfma_f32_16x16x32_bf16 v[54:57], v[154:157], v[206:209], v[54:57]
	v_mfma_f32_16x16x32_bf16 v[50:53], v[162:165], v[206:209], v[50:53]
	s_barrier
	s_add_i32 s58, 0, 0x14000
	v_add_u32_e32 v144, s58, v146
	s_add_i32 s55, s55, s35
	ds_read_b128 v[210:213], v144
	ds_read_b128 v[214:217], v144 offset:1024
	ds_read_b128 v[218:221], v144 offset:2048
	ds_read_b128 v[222:225], v144 offset:3072
	s_add_u32 s64, s22, 0x80
	s_addc_u32 s65, s23, 0
	s_mov_b32 m0, s55
	s_nop 0
	global_load_lds_dwordx4 v134, s[22:23]
	s_add_i32 m0, s55, 0x2000
	s_nop 0
	global_load_lds_dwordx4 v130, s[22:23]
	s_barrier
	s_waitcnt lgkmcnt(0)
	s_waitcnt lgkmcnt(0)
	v_mfma_f32_16x16x32_bf16 v[126:129], v[210:213], v[166:169], v[126:129]
	v_mfma_f32_16x16x32_bf16 v[122:125], v[218:221], v[166:169], v[122:125]
	v_mfma_f32_16x16x32_bf16 v[118:121], v[210:213], v[174:177], v[118:121]
	v_mfma_f32_16x16x32_bf16 v[114:117], v[218:221], v[174:177], v[114:117]
	v_mfma_f32_16x16x32_bf16 v[110:113], v[210:213], v[194:197], v[110:113]
	v_mfma_f32_16x16x32_bf16 v[106:109], v[218:221], v[194:197], v[106:109]
	v_mfma_f32_16x16x32_bf16 v[102:105], v[210:213], v[202:205], v[102:105]
	v_mfma_f32_16x16x32_bf16 v[98:101], v[218:221], v[202:205], v[98:101]
	ds_read_b128 v[166:169], v148 offset:16384
	v_mfma_f32_16x16x32_bf16 v[126:129], v[214:217], v[170:173], v[126:129]
	v_mfma_f32_16x16x32_bf16 v[122:125], v[222:225], v[170:173], v[122:125]
	ds_read_b128 v[174:177], v148 offset:18432
	v_mfma_f32_16x16x32_bf16 v[118:121], v[214:217], v[190:193], v[118:121]
	v_mfma_f32_16x16x32_bf16 v[114:117], v[222:225], v[190:193], v[114:117]
	ds_read_b128 v[194:197], v148 offset:20480
	v_mfma_f32_16x16x32_bf16 v[110:113], v[214:217], v[198:201], v[110:113]
	v_mfma_f32_16x16x32_bf16 v[106:109], v[222:225], v[198:201], v[106:109]
	ds_read_b128 v[202:205], v148 offset:22528
	v_mfma_f32_16x16x32_bf16 v[102:105], v[214:217], v[206:209], v[102:105]
	v_mfma_f32_16x16x32_bf16 v[98:101], v[222:225], v[206:209], v[98:101]
	s_barrier
	s_mov_b32 m0, s41
	s_add_u32 s62, s24, 0x80
	s_addc_u32 s63, s25, 0
	ds_read_b128 v[170:173], v148 offset:17408
	ds_read_b128 v[190:193], v148 offset:19456
	ds_read_b128 v[198:201], v148 offset:21504
	ds_read_b128 v[206:209], v148 offset:23552
	global_load_lds_dwordx4 v136, s[24:25]
	s_mov_b32 m0, s42
	s_nop 0
	global_load_lds_dwordx4 v132, s[24:25]
	s_waitcnt vmcnt(10)
	s_barrier
	s_waitcnt lgkmcnt(0)
	s_waitcnt lgkmcnt(0)
	v_mfma_f32_16x16x32_bf16 v[34:37], v[150:153], v[166:169], v[34:37]
	v_mfma_f32_16x16x32_bf16 v[26:29], v[158:161], v[166:169], v[26:29]
	v_mfma_f32_16x16x32_bf16 v[22:25], v[150:153], v[174:177], v[22:25]
	v_mfma_f32_16x16x32_bf16 v[18:21], v[158:161], v[174:177], v[18:21]
	v_mfma_f32_16x16x32_bf16 v[14:17], v[150:153], v[194:197], v[14:17]
	v_mfma_f32_16x16x32_bf16 v[10:13], v[158:161], v[194:197], v[10:13]
	v_mfma_f32_16x16x32_bf16 v[6:9], v[150:153], v[202:205], v[6:9]
	v_mfma_f32_16x16x32_bf16 v[2:5], v[158:161], v[202:205], v[2:5]
	v_mfma_f32_16x16x32_bf16 v[34:37], v[154:157], v[170:173], v[34:37]
	v_mfma_f32_16x16x32_bf16 v[26:29], v[162:165], v[170:173], v[26:29]
	v_mfma_f32_16x16x32_bf16 v[22:25], v[154:157], v[190:193], v[22:25]
	v_mfma_f32_16x16x32_bf16 v[18:21], v[162:165], v[190:193], v[18:21]
	v_mfma_f32_16x16x32_bf16 v[14:17], v[154:157], v[198:201], v[14:17]
	v_mfma_f32_16x16x32_bf16 v[10:13], v[162:165], v[198:201], v[10:13]
	v_mfma_f32_16x16x32_bf16 v[6:9], v[154:157], v[206:209], v[6:9]
	v_mfma_f32_16x16x32_bf16 v[2:5], v[162:165], v[206:209], v[2:5]
	s_barrier
	v_add_u32_e32 v162, 0x18000, v146
	ds_read_b128 v[150:153], v162
	ds_read_b128 v[154:157], v162 offset:1024
	ds_read_b128 v[158:161], v162 offset:2048
	ds_read_b128 v[162:165], v162 offset:3072
	s_add_u32 s56, s22, 0x40000
	s_addc_u32 s57, s23, 0
	s_add_i32 s55, s58, s35
	s_mov_b32 m0, s55
	s_nop 0
	global_load_lds_dwordx4 v134, s[56:57]
	s_add_i32 m0, s55, 0x2000
	s_nop 0
	global_load_lds_dwordx4 v130, s[56:57]
	s_waitcnt vmcnt(6)
	s_barrier
	v_mfma_f32_16x16x32_bf16 v[94:97], v[210:213], v[166:169], v[94:97]
	v_mfma_f32_16x16x32_bf16 v[90:93], v[218:221], v[166:169], v[90:93]
	v_mfma_f32_16x16x32_bf16 v[70:73], v[210:213], v[174:177], v[70:73]
	v_mfma_f32_16x16x32_bf16 v[66:69], v[218:221], v[174:177], v[66:69]
	v_mfma_f32_16x16x32_bf16 v[46:49], v[210:213], v[194:197], v[46:49]
	v_mfma_f32_16x16x32_bf16 v[42:45], v[218:221], v[194:197], v[42:45]
	v_mfma_f32_16x16x32_bf16 v[38:41], v[210:213], v[202:205], v[38:41]
	v_mfma_f32_16x16x32_bf16 v[30:33], v[218:221], v[202:205], v[30:33]
	v_mfma_f32_16x16x32_bf16 v[94:97], v[214:217], v[170:173], v[94:97]
	v_mfma_f32_16x16x32_bf16 v[90:93], v[222:225], v[170:173], v[90:93]
	v_mfma_f32_16x16x32_bf16 v[70:73], v[214:217], v[190:193], v[70:73]
	v_mfma_f32_16x16x32_bf16 v[66:69], v[222:225], v[190:193], v[66:69]
	v_mfma_f32_16x16x32_bf16 v[46:49], v[214:217], v[198:201], v[46:49]
	v_mfma_f32_16x16x32_bf16 v[42:45], v[222:225], v[198:201], v[42:45]
	v_mfma_f32_16x16x32_bf16 v[38:41], v[214:217], v[206:209], v[38:41]
	v_mfma_f32_16x16x32_bf16 v[30:33], v[222:225], v[206:209], v[30:33]
	s_barrier
	s_add_i32 s55, 0, 0x18000
	v_add_u32_e32 v149, s55, v146
	s_add_u32 s24, s24, 0x40000
	s_addc_u32 s25, s25, 0
	s_mov_b32 m0, s43
	ds_read_b128 v[166:169], v148 offset:32768
	ds_read_b128 v[170:173], v148 offset:33792
	ds_read_b128 v[174:177], v148 offset:34816
	ds_read_b128 v[190:193], v148 offset:35840
	ds_read_b128 v[194:197], v148 offset:36864
	ds_read_b128 v[198:201], v148 offset:37888
	ds_read_b128 v[202:205], v148 offset:38912
	ds_read_b128 v[206:209], v148 offset:39936
	global_load_lds_dwordx4 v136, s[24:25]
	s_mov_b32 m0, s44
	s_nop 0
	global_load_lds_dwordx4 v132, s[24:25]
	s_waitcnt lgkmcnt(8)
	s_barrier
	s_waitcnt lgkmcnt(0)
	s_waitcnt lgkmcnt(0)
	v_mfma_f32_16x16x32_bf16 v[86:89], v[150:153], v[166:169], v[86:89]
	v_mfma_f32_16x16x32_bf16 v[82:85], v[158:161], v[166:169], v[82:85]
	v_mfma_f32_16x16x32_bf16 v[78:81], v[150:153], v[174:177], v[78:81]
	v_mfma_f32_16x16x32_bf16 v[74:77], v[158:161], v[174:177], v[74:77]
	v_mfma_f32_16x16x32_bf16 v[62:65], v[150:153], v[194:197], v[62:65]
	v_mfma_f32_16x16x32_bf16 v[58:61], v[158:161], v[194:197], v[58:61]
	v_mfma_f32_16x16x32_bf16 v[54:57], v[150:153], v[202:205], v[54:57]
	v_mfma_f32_16x16x32_bf16 v[50:53], v[158:161], v[202:205], v[50:53]
	v_mfma_f32_16x16x32_bf16 v[86:89], v[154:157], v[170:173], v[86:89]
	v_mfma_f32_16x16x32_bf16 v[82:85], v[162:165], v[170:173], v[82:85]
	v_mfma_f32_16x16x32_bf16 v[78:81], v[154:157], v[190:193], v[78:81]
	v_mfma_f32_16x16x32_bf16 v[74:77], v[162:165], v[190:193], v[74:77]
	v_mfma_f32_16x16x32_bf16 v[62:65], v[154:157], v[198:201], v[62:65]
	v_mfma_f32_16x16x32_bf16 v[58:61], v[162:165], v[198:201], v[58:61]
	v_mfma_f32_16x16x32_bf16 v[54:57], v[154:157], v[206:209], v[54:57]
	v_mfma_f32_16x16x32_bf16 v[50:53], v[162:165], v[206:209], v[50:53]
	s_barrier
	s_add_i32 s24, 0, 0x1c000
	s_add_i32 s25, s55, s35
	v_add_u32_e32 v149, s24, v146
	s_mov_b32 m0, s25
	ds_read_b128 v[210:213], v149
	ds_read_b128 v[214:217], v149 offset:1024
	ds_read_b128 v[218:221], v149 offset:2048
	ds_read_b128 v[222:225], v149 offset:3072
	global_load_lds_dwordx4 v134, s[64:65]
	s_add_i32 m0, s25, 0x2000
	s_nop 0
	global_load_lds_dwordx4 v130, s[64:65]
	s_barrier
	s_waitcnt lgkmcnt(0)
	s_waitcnt lgkmcnt(0)
	v_mfma_f32_16x16x32_bf16 v[126:129], v[210:213], v[166:169], v[126:129]
	v_mfma_f32_16x16x32_bf16 v[122:125], v[218:221], v[166:169], v[122:125]
	v_mfma_f32_16x16x32_bf16 v[118:121], v[210:213], v[174:177], v[118:121]
	v_mfma_f32_16x16x32_bf16 v[114:117], v[218:221], v[174:177], v[114:117]
	v_mfma_f32_16x16x32_bf16 v[110:113], v[210:213], v[194:197], v[110:113]
	v_mfma_f32_16x16x32_bf16 v[106:109], v[218:221], v[194:197], v[106:109]
	v_mfma_f32_16x16x32_bf16 v[102:105], v[210:213], v[202:205], v[102:105]
	v_mfma_f32_16x16x32_bf16 v[98:101], v[218:221], v[202:205], v[98:101]
	ds_read_b128 v[166:169], v148 offset:49152
	v_mfma_f32_16x16x32_bf16 v[126:129], v[214:217], v[170:173], v[126:129]
	v_mfma_f32_16x16x32_bf16 v[122:125], v[222:225], v[170:173], v[122:125]
	ds_read_b128 v[174:177], v148 offset:51200
	v_mfma_f32_16x16x32_bf16 v[118:121], v[214:217], v[190:193], v[118:121]
	v_mfma_f32_16x16x32_bf16 v[114:117], v[222:225], v[190:193], v[114:117]
	ds_read_b128 v[194:197], v148 offset:53248
	v_mfma_f32_16x16x32_bf16 v[110:113], v[214:217], v[198:201], v[110:113]
	v_mfma_f32_16x16x32_bf16 v[106:109], v[222:225], v[198:201], v[106:109]
	ds_read_b128 v[202:205], v148 offset:55296
	v_mfma_f32_16x16x32_bf16 v[102:105], v[214:217], v[206:209], v[102:105]
	v_mfma_f32_16x16x32_bf16 v[98:101], v[222:225], v[206:209], v[98:101]
	s_barrier
	s_mov_b32 m0, s46
	ds_read_b128 v[170:173], v148 offset:50176
	ds_read_b128 v[190:193], v148 offset:52224
	ds_read_b128 v[198:201], v148 offset:54272
	ds_read_b128 v[206:209], v148 offset:56320
	global_load_lds_dwordx4 v136, s[62:63]
	s_mov_b32 m0, s47
	s_nop 0
	global_load_lds_dwordx4 v132, s[62:63]
	s_waitcnt vmcnt(10)
	s_barrier
	s_waitcnt lgkmcnt(0)
	s_waitcnt lgkmcnt(0)
	v_mfma_f32_16x16x32_bf16 v[34:37], v[150:153], v[166:169], v[34:37]
	v_mfma_f32_16x16x32_bf16 v[26:29], v[158:161], v[166:169], v[26:29]
	v_mfma_f32_16x16x32_bf16 v[22:25], v[150:153], v[174:177], v[22:25]
	v_mfma_f32_16x16x32_bf16 v[18:21], v[158:161], v[174:177], v[18:21]
	v_mfma_f32_16x16x32_bf16 v[14:17], v[150:153], v[194:197], v[14:17]
	v_mfma_f32_16x16x32_bf16 v[10:13], v[158:161], v[194:197], v[10:13]
	v_mfma_f32_16x16x32_bf16 v[6:9], v[150:153], v[202:205], v[6:9]
	v_mfma_f32_16x16x32_bf16 v[2:5], v[158:161], v[202:205], v[2:5]
	v_mfma_f32_16x16x32_bf16 v[34:37], v[154:157], v[170:173], v[34:37]
	v_mfma_f32_16x16x32_bf16 v[26:29], v[162:165], v[170:173], v[26:29]
	v_mfma_f32_16x16x32_bf16 v[22:25], v[154:157], v[190:193], v[22:25]
	v_mfma_f32_16x16x32_bf16 v[18:21], v[162:165], v[190:193], v[18:21]
	v_mfma_f32_16x16x32_bf16 v[14:17], v[154:157], v[198:201], v[14:17]
	v_mfma_f32_16x16x32_bf16 v[10:13], v[162:165], v[198:201], v[10:13]
	v_mfma_f32_16x16x32_bf16 v[6:9], v[154:157], v[206:209], v[6:9]
	v_mfma_f32_16x16x32_bf16 v[2:5], v[162:165], v[206:209], v[2:5]
	s_barrier
	v_add_u32_e32 v162, 0x10000, v146
	ds_read_b128 v[150:153], v162
	ds_read_b128 v[154:157], v162 offset:1024
	ds_read_b128 v[158:161], v162 offset:2048
	ds_read_b128 v[162:165], v162 offset:3072
	s_add_u32 s22, s22, 0x40080
	s_addc_u32 s23, s23, 0
	s_add_i32 s24, s24, s35
	s_mov_b32 m0, s24
	s_nop 0
	global_load_lds_dwordx4 v134, s[22:23]
	v_lshl_add_u64 v[144:145], s[22:23], 0, v[130:131]
	s_add_i32 m0, s24, 0x2000
	s_nop 0
	global_load_lds_dwordx4 v[144:145], off
	s_waitcnt vmcnt(6)
	s_barrier
	v_mfma_f32_16x16x32_bf16 v[94:97], v[210:213], v[166:169], v[94:97]
	v_mfma_f32_16x16x32_bf16 v[90:93], v[218:221], v[166:169], v[90:93]
	v_mfma_f32_16x16x32_bf16 v[70:73], v[210:213], v[174:177], v[70:73]
	v_mfma_f32_16x16x32_bf16 v[66:69], v[218:221], v[174:177], v[66:69]
	v_mfma_f32_16x16x32_bf16 v[46:49], v[210:213], v[194:197], v[46:49]
	v_mfma_f32_16x16x32_bf16 v[42:45], v[218:221], v[194:197], v[42:45]
	v_mfma_f32_16x16x32_bf16 v[38:41], v[210:213], v[202:205], v[38:41]
	v_mfma_f32_16x16x32_bf16 v[30:33], v[218:221], v[202:205], v[30:33]
	v_mfma_f32_16x16x32_bf16 v[94:97], v[214:217], v[170:173], v[94:97]
	v_mfma_f32_16x16x32_bf16 v[90:93], v[222:225], v[170:173], v[90:93]
	v_mfma_f32_16x16x32_bf16 v[70:73], v[214:217], v[190:193], v[70:73]
	v_mfma_f32_16x16x32_bf16 v[66:69], v[222:225], v[190:193], v[66:69]
	v_mfma_f32_16x16x32_bf16 v[46:49], v[214:217], v[198:201], v[46:49]
	v_mfma_f32_16x16x32_bf16 v[42:45], v[222:225], v[198:201], v[42:45]
	v_mfma_f32_16x16x32_bf16 v[38:41], v[214:217], v[206:209], v[38:41]
	v_mfma_f32_16x16x32_bf16 v[30:33], v[222:225], v[206:209], v[30:33]
	s_barrier
	s_add_i32 s54, s54, 2
	s_add_u32 s20, s20, 0x100
	s_addc_u32 s21, s21, 0
	s_add_u32 s52, s52, 0x100
	s_addc_u32 s53, s53, 0
	s_cmp_gt_u32 s54, 13
	s_cbranch_scc0 .LBB0_528
	s_waitcnt lgkmcnt(0)
	v_lshl_add_u32 v144, s10, 8, v1
	s_cmp_lg_u32 s50, s45
	s_mov_b64 s[10:11], -1
	s_cbranch_scc0 .LBB0_531
	v_lshl_or_b32 v154, s50, 8, v147
	v_readlane_b32 s13, v255, 32
	v_ashrrev_i32_e32 v155, 31, v154
	v_lshlrev_b64 v[154:155], 1, v[154:155]
	v_mad_i64_i32 v[156:157], s[10:11], v144, s13, 0
	v_lshl_add_u64 v[156:157], v[156:157], 1, s[6:7]
	v_lshl_add_u64 v[156:157], v[156:157], 0, v[154:155]
	v_cvt_pk_bf16_f32 v126, v126, v127
	v_cvt_pk_bf16_f32 v127, v128, v129
	v_cvt_pk_bf16_f32 v128, v122, v123
	v_cvt_pk_bf16_f32 v129, v124, v125
	global_store_dwordx4 v[156:157], v[126:129], off offset:256
	v_cvt_pk_bf16_f32 v150, v86, v87
	v_cvt_pk_bf16_f32 v151, v88, v89
	v_or_b32_e32 v126, 16, v144
	v_mad_i64_i32 v[126:127], s[10:11], v126, s13, 0
	v_lshl_add_u64 v[126:127], v[126:127], 1, s[6:7]
	v_cvt_pk_bf16_f32 v152, v82, v83
	v_cvt_pk_bf16_f32 v153, v84, v85
	v_lshl_add_u64 v[126:127], v[126:127], 0, v[154:155]
	v_cvt_pk_bf16_f32 v118, v118, v119
	v_cvt_pk_bf16_f32 v119, v120, v121
	v_cvt_pk_bf16_f32 v120, v114, v115
	v_cvt_pk_bf16_f32 v121, v116, v117
	global_store_dwordx4 v[156:157], v[150:153], off
	global_store_dwordx4 v[126:127], v[118:121], off offset:256
	v_cvt_pk_bf16_f32 v122, v78, v79
	v_cvt_pk_bf16_f32 v123, v80, v81
	v_or_b32_e32 v118, 32, v144
	v_mad_i64_i32 v[118:119], s[10:11], v118, s13, 0
	v_lshl_add_u64 v[118:119], v[118:119], 1, s[6:7]
	v_cvt_pk_bf16_f32 v124, v74, v75
	v_cvt_pk_bf16_f32 v125, v76, v77
	v_lshl_add_u64 v[118:119], v[118:119], 0, v[154:155]
	v_cvt_pk_bf16_f32 v110, v110, v111
	v_cvt_pk_bf16_f32 v111, v112, v113
	v_cvt_pk_bf16_f32 v112, v106, v107
	v_cvt_pk_bf16_f32 v113, v108, v109
	global_store_dwordx4 v[126:127], v[122:125], off
	global_store_dwordx4 v[118:119], v[110:113], off offset:256
	v_cvt_pk_bf16_f32 v114, v62, v63
	v_cvt_pk_bf16_f32 v115, v64, v65
	v_or_b32_e32 v110, 48, v144
	v_mad_i64_i32 v[110:111], s[10:11], v110, s13, 0
	v_lshl_add_u64 v[110:111], v[110:111], 1, s[6:7]
	v_cvt_pk_bf16_f32 v116, v58, v59
	v_cvt_pk_bf16_f32 v117, v60, v61
	v_lshl_add_u64 v[110:111], v[110:111], 0, v[154:155]
	v_cvt_pk_bf16_f32 v102, v102, v103
	v_cvt_pk_bf16_f32 v103, v104, v105
	v_cvt_pk_bf16_f32 v104, v98, v99
	v_cvt_pk_bf16_f32 v105, v100, v101
	global_store_dwordx4 v[118:119], v[114:117], off
	global_store_dwordx4 v[110:111], v[102:105], off offset:256
	v_cvt_pk_bf16_f32 v106, v54, v55
	v_cvt_pk_bf16_f32 v107, v56, v57
	v_add_u32_e32 v102, 0x80, v144
	v_mad_i64_i32 v[102:103], s[10:11], v102, s13, 0
	v_lshl_add_u64 v[102:103], v[102:103], 1, s[6:7]
	v_cvt_pk_bf16_f32 v108, v50, v51
	v_cvt_pk_bf16_f32 v109, v52, v53
	v_lshl_add_u64 v[102:103], v[102:103], 0, v[154:155]
	v_cvt_pk_bf16_f32 v94, v94, v95
	v_cvt_pk_bf16_f32 v95, v96, v97
	v_cvt_pk_bf16_f32 v96, v90, v91
	v_cvt_pk_bf16_f32 v97, v92, v93
	global_store_dwordx4 v[110:111], v[106:109], off
	global_store_dwordx4 v[102:103], v[94:97], off offset:256
	v_cvt_pk_bf16_f32 v98, v34, v35
	v_cvt_pk_bf16_f32 v99, v36, v37
	v_add_u32_e32 v94, 0x90, v144
	v_mad_i64_i32 v[94:95], s[10:11], v94, s13, 0
	v_lshl_add_u64 v[94:95], v[94:95], 1, s[6:7]
	v_cvt_pk_bf16_f32 v100, v26, v27
	v_cvt_pk_bf16_f32 v101, v28, v29
	v_lshl_add_u64 v[94:95], v[94:95], 0, v[154:155]
	v_cvt_pk_bf16_f32 v70, v70, v71
	v_cvt_pk_bf16_f32 v71, v72, v73
	v_cvt_pk_bf16_f32 v72, v66, v67
	v_cvt_pk_bf16_f32 v73, v68, v69
	global_store_dwordx4 v[102:103], v[98:101], off
	global_store_dwordx4 v[94:95], v[70:73], off offset:256
	v_cvt_pk_bf16_f32 v90, v22, v23
	v_cvt_pk_bf16_f32 v91, v24, v25
	v_add_u32_e32 v70, 0xa0, v144
	v_mad_i64_i32 v[70:71], s[10:11], v70, s13, 0
	v_lshl_add_u64 v[70:71], v[70:71], 1, s[6:7]
	v_cvt_pk_bf16_f32 v92, v18, v19
	v_cvt_pk_bf16_f32 v93, v20, v21
	v_lshl_add_u64 v[70:71], v[70:71], 0, v[154:155]
	v_cvt_pk_bf16_f32 v46, v46, v47
	v_cvt_pk_bf16_f32 v47, v48, v49
	v_cvt_pk_bf16_f32 v48, v42, v43
	v_cvt_pk_bf16_f32 v49, v44, v45
	global_store_dwordx4 v[94:95], v[90:93], off
	global_store_dwordx4 v[70:71], v[46:49], off offset:256
	v_cvt_pk_bf16_f32 v66, v14, v15
	v_cvt_pk_bf16_f32 v67, v16, v17
	v_add_u32_e32 v46, 0xb0, v144
	v_mad_i64_i32 v[46:47], s[10:11], v46, s13, 0
	v_lshl_add_u64 v[46:47], v[46:47], 1, s[6:7]
	v_cvt_pk_bf16_f32 v68, v10, v11
	v_cvt_pk_bf16_f32 v69, v12, v13
	v_cvt_pk_bf16_f32 v42, v6, v7
	v_cvt_pk_bf16_f32 v43, v8, v9
	v_cvt_pk_bf16_f32 v44, v2, v3
	v_cvt_pk_bf16_f32 v45, v4, v5
	v_lshl_add_u64 v[46:47], v[46:47], 0, v[154:155]
	v_cvt_pk_bf16_f32 v38, v38, v39
	v_cvt_pk_bf16_f32 v39, v40, v41
	v_cvt_pk_bf16_f32 v40, v30, v31
	v_cvt_pk_bf16_f32 v41, v32, v33
	global_store_dwordx4 v[70:71], v[66:69], off
	global_store_dwordx4 v[46:47], v[42:45], off
	global_store_dwordx4 v[46:47], v[38:41], off offset:256
	s_mov_b64 s[10:11], 0

.LBB0_1407:
	s_ashr_i32 s3, s2, 31
	s_lshl_b64 s[12:13], s[2:3], 20
	s_add_u32 s12, s24, s12
	s_addc_u32 s13, s25, s13
	s_and_b64 s[6:7], s[6:7], exec
	s_cselect_b32 s3, s13, s17
	s_cselect_b32 s44, s12, s16
	s_add_u32 s45, s16, 0x100
	s_addc_u32 s46, s17, 0
	s_add_u32 s6, s14, 0x80
	s_addc_u32 s7, s15, 0
	v_lshl_add_u64 v[142:143], s[6:7], 0, v[138:139]
	v_lshl_add_u64 v[144:145], s[6:7], 0, v[140:141]
	s_mov_b32 s47, -2
	s_mov_b64 s[6:7], 0
	s_add_u32 s16, s14, s6
	s_addc_u32 s17, s15, s7
	s_add_u32 s16, s16, 0x100
	s_addc_u32 s17, s17, 0
	s_add_u32 s48, s45, s6
	s_addc_u32 s49, s46, s7
	s_add_i32 s50, 0, 0x10000
	v_add_u32_e32 v158, s50, v164
	ds_read_b128 v[146:149], v158
	ds_read_b128 v[150:153], v158 offset:1024
	ds_read_b128 v[154:157], v158 offset:2048
	ds_read_b128 v[158:161], v158 offset:3072
	s_cmpk_eq_i32 s6, 0xf00
	s_cselect_b32 s19, s11, s17
	s_cselect_b32 s18, s10, s16
	s_cselect_b32 s17, s3, s49
	s_cselect_b32 s16, s44, s48
	v_lshl_add_u64 v[162:163], v[142:143], 0, s[6:7]
	s_add_i32 m0, s30, 0xc000
	ds_read_b128 v[168:171], v166
	ds_read_b128 v[172:175], v166 offset:1024
	ds_read_b128 v[186:189], v166 offset:2048
	ds_read_b128 v[190:193], v166 offset:3072
	ds_read_b128 v[194:197], v166 offset:4096
	ds_read_b128 v[198:201], v166 offset:5120
	ds_read_b128 v[202:205], v166 offset:6144
	ds_read_b128 v[206:209], v166 offset:7168
	global_load_lds_dwordx4 v[162:163], off
	v_lshl_add_u64 v[162:163], v[144:145], 0, s[6:7]
	s_add_i32 m0, s30, 0xe000
	s_nop 0
	global_load_lds_dwordx4 v[162:163], off
	s_waitcnt lgkmcnt(8)
	s_barrier
	s_waitcnt lgkmcnt(0)
	s_waitcnt lgkmcnt(0)
	v_mfma_f32_16x16x32_bf16 v[126:129], v[146:149], v[168:171], 0
	v_mfma_f32_16x16x32_bf16 v[122:125], v[154:157], v[168:171], 0
	v_mfma_f32_16x16x32_bf16 v[110:113], v[146:149], v[186:189], 0
	v_mfma_f32_16x16x32_bf16 v[106:109], v[154:157], v[186:189], 0
	v_mfma_f32_16x16x32_bf16 v[94:97], v[146:149], v[194:197], 0
	v_mfma_f32_16x16x32_bf16 v[90:93], v[154:157], v[194:197], 0
	v_mfma_f32_16x16x32_bf16 v[78:81], v[146:149], v[202:205], 0
	v_mfma_f32_16x16x32_bf16 v[74:77], v[154:157], v[202:205], 0
	v_mfma_f32_16x16x32_bf16 v[126:129], v[150:153], v[172:175], v[126:129]
	v_mfma_f32_16x16x32_bf16 v[122:125], v[158:161], v[172:175], v[122:125]
	v_mfma_f32_16x16x32_bf16 v[110:113], v[150:153], v[190:193], v[110:113]
	v_mfma_f32_16x16x32_bf16 v[106:109], v[158:161], v[190:193], v[106:109]
	v_mfma_f32_16x16x32_bf16 v[94:97], v[150:153], v[198:201], v[94:97]
	v_mfma_f32_16x16x32_bf16 v[90:93], v[158:161], v[198:201], v[90:93]
	v_mfma_f32_16x16x32_bf16 v[78:81], v[150:153], v[206:209], v[78:81]
	v_mfma_f32_16x16x32_bf16 v[74:77], v[158:161], v[206:209], v[74:77]
	s_barrier
	s_add_i32 s51, 0, 0x14000
	v_add_u32_e32 v162, s51, v164
	s_add_i32 s48, s50, s29
	ds_read_b128 v[210:213], v162
	ds_read_b128 v[214:217], v162 offset:1024
	ds_read_b128 v[218:221], v162 offset:2048
	ds_read_b128 v[222:225], v162 offset:3072
	s_add_u32 s64, s16, 0x80
	s_addc_u32 s65, s17, 0
	s_mov_b32 m0, s48
	s_nop 0
	global_load_lds_dwordx4 v132, s[16:17]
	s_add_i32 m0, s48, 0x2000
	s_nop 0
	global_load_lds_dwordx4 v136, s[16:17]
	s_barrier
	s_waitcnt lgkmcnt(0)
	s_waitcnt lgkmcnt(0)
	v_mfma_f32_16x16x32_bf16 v[118:121], v[210:213], v[168:171], 0
	v_mfma_f32_16x16x32_bf16 v[114:117], v[218:221], v[168:171], 0
	v_mfma_f32_16x16x32_bf16 v[102:105], v[210:213], v[186:189], 0
	v_mfma_f32_16x16x32_bf16 v[98:101], v[218:221], v[186:189], 0
	v_mfma_f32_16x16x32_bf16 v[86:89], v[210:213], v[194:197], 0
	v_mfma_f32_16x16x32_bf16 v[82:85], v[218:221], v[194:197], 0
	v_mfma_f32_16x16x32_bf16 v[70:73], v[210:213], v[202:205], 0
	v_mfma_f32_16x16x32_bf16 v[66:69], v[218:221], v[202:205], 0
	ds_read_b128 v[168:171], v166 offset:16384
	v_mfma_f32_16x16x32_bf16 v[118:121], v[214:217], v[172:175], v[118:121]
	v_mfma_f32_16x16x32_bf16 v[114:117], v[222:225], v[172:175], v[114:117]
	ds_read_b128 v[186:189], v166 offset:18432
	v_mfma_f32_16x16x32_bf16 v[102:105], v[214:217], v[190:193], v[102:105]
	v_mfma_f32_16x16x32_bf16 v[98:101], v[222:225], v[190:193], v[98:101]
	ds_read_b128 v[194:197], v166 offset:20480
	v_mfma_f32_16x16x32_bf16 v[86:89], v[214:217], v[198:201], v[86:89]
	v_mfma_f32_16x16x32_bf16 v[82:85], v[222:225], v[198:201], v[82:85]
	ds_read_b128 v[202:205], v166 offset:22528
	v_mfma_f32_16x16x32_bf16 v[70:73], v[214:217], v[206:209], v[70:73]
	v_mfma_f32_16x16x32_bf16 v[66:69], v[222:225], v[206:209], v[66:69]
	s_barrier
	s_mov_b32 m0, s30
	s_add_u32 s62, s18, 0x80
	s_addc_u32 s63, s19, 0
	ds_read_b128 v[172:175], v166 offset:17408
	ds_read_b128 v[190:193], v166 offset:19456
	ds_read_b128 v[198:201], v166 offset:21504
	ds_read_b128 v[206:209], v166 offset:23552
	global_load_lds_dwordx4 v130, s[18:19]
	s_mov_b32 m0, s31
	s_nop 0
	global_load_lds_dwordx4 v134, s[18:19]
	s_waitcnt vmcnt(10)
	s_barrier
	s_waitcnt lgkmcnt(0)
	s_waitcnt lgkmcnt(0)
	v_mfma_f32_16x16x32_bf16 v[62:65], v[146:149], v[168:171], 0
	v_mfma_f32_16x16x32_bf16 v[58:61], v[154:157], v[168:171], 0
	v_mfma_f32_16x16x32_bf16 v[46:49], v[146:149], v[186:189], 0
	v_mfma_f32_16x16x32_bf16 v[42:45], v[154:157], v[186:189], 0
	v_mfma_f32_16x16x32_bf16 v[30:33], v[146:149], v[194:197], 0
	v_mfma_f32_16x16x32_bf16 v[26:29], v[154:157], v[194:197], 0
	v_mfma_f32_16x16x32_bf16 v[14:17], v[146:149], v[202:205], 0
	v_mfma_f32_16x16x32_bf16 v[10:13], v[154:157], v[202:205], 0
	v_mfma_f32_16x16x32_bf16 v[62:65], v[150:153], v[172:175], v[62:65]
	v_mfma_f32_16x16x32_bf16 v[58:61], v[158:161], v[172:175], v[58:61]
	v_mfma_f32_16x16x32_bf16 v[46:49], v[150:153], v[190:193], v[46:49]
	v_mfma_f32_16x16x32_bf16 v[42:45], v[158:161], v[190:193], v[42:45]
	v_mfma_f32_16x16x32_bf16 v[30:33], v[150:153], v[198:201], v[30:33]
	v_mfma_f32_16x16x32_bf16 v[26:29], v[158:161], v[198:201], v[26:29]
	v_mfma_f32_16x16x32_bf16 v[14:17], v[150:153], v[206:209], v[14:17]
	v_mfma_f32_16x16x32_bf16 v[10:13], v[158:161], v[206:209], v[10:13]
	s_barrier
	v_add_u32_e32 v158, 0x18000, v164
	ds_read_b128 v[146:149], v158
	ds_read_b128 v[150:153], v158 offset:1024
	ds_read_b128 v[154:157], v158 offset:2048
	ds_read_b128 v[158:161], v158 offset:3072
	s_add_u32 s48, s16, 0x80000
	s_addc_u32 s49, s17, 0
	s_add_i32 s50, s51, s29
	s_mov_b32 m0, s50
	s_nop 0
	global_load_lds_dwordx4 v132, s[48:49]
	s_add_i32 m0, s50, 0x2000
	s_nop 0
	global_load_lds_dwordx4 v136, s[48:49]
	s_waitcnt vmcnt(6)
	s_barrier
	v_mfma_f32_16x16x32_bf16 v[54:57], v[210:213], v[168:171], 0
	v_mfma_f32_16x16x32_bf16 v[50:53], v[218:221], v[168:171], 0
	v_mfma_f32_16x16x32_bf16 v[38:41], v[210:213], v[186:189], 0
	v_mfma_f32_16x16x32_bf16 v[34:37], v[218:221], v[186:189], 0
	v_mfma_f32_16x16x32_bf16 v[22:25], v[210:213], v[194:197], 0
	v_mfma_f32_16x16x32_bf16 v[18:21], v[218:221], v[194:197], 0
	v_mfma_f32_16x16x32_bf16 v[6:9], v[210:213], v[202:205], 0
	v_mfma_f32_16x16x32_bf16 v[2:5], v[218:221], v[202:205], 0
	v_mfma_f32_16x16x32_bf16 v[54:57], v[214:217], v[172:175], v[54:57]
	v_mfma_f32_16x16x32_bf16 v[50:53], v[222:225], v[172:175], v[50:53]
	v_mfma_f32_16x16x32_bf16 v[38:41], v[214:217], v[190:193], v[38:41]
	v_mfma_f32_16x16x32_bf16 v[34:37], v[222:225], v[190:193], v[34:37]
	v_mfma_f32_16x16x32_bf16 v[22:25], v[214:217], v[198:201], v[22:25]
	v_mfma_f32_16x16x32_bf16 v[18:21], v[222:225], v[198:201], v[18:21]
	v_mfma_f32_16x16x32_bf16 v[6:9], v[214:217], v[206:209], v[6:9]
	v_mfma_f32_16x16x32_bf16 v[2:5], v[222:225], v[206:209], v[2:5]
	s_barrier
	s_add_i32 s48, 0, 0x18000
	s_add_u32 s18, s18, s80
	s_addc_u32 s19, s19, 0
	s_mov_b32 m0, s34
	ds_read_b128 v[168:171], v166 offset:32768
	ds_read_b128 v[172:175], v166 offset:33792
	ds_read_b128 v[186:189], v166 offset:34816
	ds_read_b128 v[190:193], v166 offset:35840
	ds_read_b128 v[194:197], v166 offset:36864
	ds_read_b128 v[198:201], v166 offset:37888
	ds_read_b128 v[202:205], v166 offset:38912
	ds_read_b128 v[206:209], v166 offset:39936
	global_load_lds_dwordx4 v130, s[18:19]
	s_mov_b32 m0, s35
	s_nop 0
	global_load_lds_dwordx4 v134, s[18:19]
	s_waitcnt lgkmcnt(8)
	s_barrier
	s_waitcnt lgkmcnt(0)
	s_waitcnt lgkmcnt(0)
	v_mfma_f32_16x16x32_bf16 v[126:129], v[146:149], v[168:171], v[126:129]
	v_mfma_f32_16x16x32_bf16 v[122:125], v[154:157], v[168:171], v[122:125]
	v_mfma_f32_16x16x32_bf16 v[110:113], v[146:149], v[186:189], v[110:113]
	v_mfma_f32_16x16x32_bf16 v[106:109], v[154:157], v[186:189], v[106:109]
	v_mfma_f32_16x16x32_bf16 v[94:97], v[146:149], v[194:197], v[94:97]
	v_mfma_f32_16x16x32_bf16 v[90:93], v[154:157], v[194:197], v[90:93]
	v_mfma_f32_16x16x32_bf16 v[78:81], v[146:149], v[202:205], v[78:81]
	v_mfma_f32_16x16x32_bf16 v[74:77], v[154:157], v[202:205], v[74:77]
	v_mfma_f32_16x16x32_bf16 v[126:129], v[150:153], v[172:175], v[126:129]
	v_mfma_f32_16x16x32_bf16 v[122:125], v[158:161], v[172:175], v[122:125]
	v_mfma_f32_16x16x32_bf16 v[110:113], v[150:153], v[190:193], v[110:113]
	v_mfma_f32_16x16x32_bf16 v[106:109], v[158:161], v[190:193], v[106:109]
	v_mfma_f32_16x16x32_bf16 v[94:97], v[150:153], v[198:201], v[94:97]
	v_mfma_f32_16x16x32_bf16 v[90:93], v[158:161], v[198:201], v[90:93]
	v_mfma_f32_16x16x32_bf16 v[78:81], v[150:153], v[206:209], v[78:81]
	v_mfma_f32_16x16x32_bf16 v[74:77], v[158:161], v[206:209], v[74:77]
	s_barrier
	s_add_i32 s18, 0, 0x1c000
	s_add_i32 s19, s48, s29
	v_add_u32_e32 v167, s18, v164
	s_mov_b32 m0, s19
	ds_read_b128 v[210:213], v167
	ds_read_b128 v[214:217], v167 offset:1024
	ds_read_b128 v[218:221], v167 offset:2048
	ds_read_b128 v[222:225], v167 offset:3072
	global_load_lds_dwordx4 v132, s[64:65]
	s_add_i32 m0, s19, 0x2000
	s_nop 0
	global_load_lds_dwordx4 v136, s[64:65]
	s_barrier
	s_waitcnt lgkmcnt(0)
	s_waitcnt lgkmcnt(0)
	v_mfma_f32_16x16x32_bf16 v[118:121], v[210:213], v[168:171], v[118:121]
	v_mfma_f32_16x16x32_bf16 v[114:117], v[218:221], v[168:171], v[114:117]
	v_mfma_f32_16x16x32_bf16 v[102:105], v[210:213], v[186:189], v[102:105]
	v_mfma_f32_16x16x32_bf16 v[98:101], v[218:221], v[186:189], v[98:101]
	v_mfma_f32_16x16x32_bf16 v[86:89], v[210:213], v[194:197], v[86:89]
	v_mfma_f32_16x16x32_bf16 v[82:85], v[218:221], v[194:197], v[82:85]
	v_mfma_f32_16x16x32_bf16 v[70:73], v[210:213], v[202:205], v[70:73]
	v_mfma_f32_16x16x32_bf16 v[66:69], v[218:221], v[202:205], v[66:69]
	ds_read_b128 v[168:171], v166 offset:49152
	v_mfma_f32_16x16x32_bf16 v[118:121], v[214:217], v[172:175], v[118:121]
	v_mfma_f32_16x16x32_bf16 v[114:117], v[222:225], v[172:175], v[114:117]
	ds_read_b128 v[186:189], v166 offset:51200
	v_mfma_f32_16x16x32_bf16 v[102:105], v[214:217], v[190:193], v[102:105]
	v_mfma_f32_16x16x32_bf16 v[98:101], v[222:225], v[190:193], v[98:101]
	ds_read_b128 v[194:197], v166 offset:53248
	v_mfma_f32_16x16x32_bf16 v[86:89], v[214:217], v[198:201], v[86:89]
	v_mfma_f32_16x16x32_bf16 v[82:85], v[222:225], v[198:201], v[82:85]
	ds_read_b128 v[202:205], v166 offset:55296
	v_mfma_f32_16x16x32_bf16 v[70:73], v[214:217], v[206:209], v[70:73]
	v_mfma_f32_16x16x32_bf16 v[66:69], v[222:225], v[206:209], v[66:69]
	s_barrier
	s_mov_b32 m0, s38
	ds_read_b128 v[172:175], v166 offset:50176
	ds_read_b128 v[190:193], v166 offset:52224
	ds_read_b128 v[198:201], v166 offset:54272
	ds_read_b128 v[206:209], v166 offset:56320
	global_load_lds_dwordx4 v130, s[62:63]
	s_mov_b32 m0, s39
	s_nop 0
	global_load_lds_dwordx4 v134, s[62:63]
	s_waitcnt vmcnt(10)
	s_barrier
	s_waitcnt lgkmcnt(0)
	s_waitcnt lgkmcnt(0)
	v_mfma_f32_16x16x32_bf16 v[62:65], v[146:149], v[168:171], v[62:65]
	v_mfma_f32_16x16x32_bf16 v[58:61], v[154:157], v[168:171], v[58:61]
	v_mfma_f32_16x16x32_bf16 v[46:49], v[146:149], v[186:189], v[46:49]
	v_mfma_f32_16x16x32_bf16 v[42:45], v[154:157], v[186:189], v[42:45]
	v_mfma_f32_16x16x32_bf16 v[30:33], v[146:149], v[194:197], v[30:33]
	v_mfma_f32_16x16x32_bf16 v[26:29], v[154:157], v[194:197], v[26:29]
	v_mfma_f32_16x16x32_bf16 v[14:17], v[146:149], v[202:205], v[14:17]
	v_mfma_f32_16x16x32_bf16 v[10:13], v[154:157], v[202:205], v[10:13]
	v_mfma_f32_16x16x32_bf16 v[62:65], v[150:153], v[172:175], v[62:65]
	v_mfma_f32_16x16x32_bf16 v[58:61], v[158:161], v[172:175], v[58:61]
	v_mfma_f32_16x16x32_bf16 v[46:49], v[150:153], v[190:193], v[46:49]
	v_mfma_f32_16x16x32_bf16 v[42:45], v[158:161], v[190:193], v[42:45]
	v_mfma_f32_16x16x32_bf16 v[30:33], v[150:153], v[198:201], v[30:33]
	v_mfma_f32_16x16x32_bf16 v[26:29], v[158:161], v[198:201], v[26:29]
	v_mfma_f32_16x16x32_bf16 v[14:17], v[150:153], v[206:209], v[14:17]
	v_mfma_f32_16x16x32_bf16 v[10:13], v[158:161], v[206:209], v[10:13]
	s_barrier
	v_add_u32_e32 v158, 0x10000, v164
	ds_read_b128 v[146:149], v158
	ds_read_b128 v[150:153], v158 offset:1024
	ds_read_b128 v[154:157], v158 offset:2048
	ds_read_b128 v[158:161], v158 offset:3072
	s_add_u32 s16, s16, 0x80080
	s_addc_u32 s17, s17, 0
	s_add_i32 s18, s18, s29
	s_mov_b32 m0, s18
	s_nop 0
	global_load_lds_dwordx4 v132, s[16:17]
	s_add_i32 m0, s18, 0x2000
	s_nop 0
	global_load_lds_dwordx4 v136, s[16:17]
	s_waitcnt vmcnt(6)
	s_barrier
	v_mfma_f32_16x16x32_bf16 v[54:57], v[210:213], v[168:171], v[54:57]
	v_mfma_f32_16x16x32_bf16 v[50:53], v[218:221], v[168:171], v[50:53]
	v_mfma_f32_16x16x32_bf16 v[38:41], v[210:213], v[186:189], v[38:41]
	v_mfma_f32_16x16x32_bf16 v[34:37], v[218:221], v[186:189], v[34:37]
	v_mfma_f32_16x16x32_bf16 v[22:25], v[210:213], v[194:197], v[22:25]
	v_mfma_f32_16x16x32_bf16 v[18:21], v[218:221], v[194:197], v[18:21]
	v_mfma_f32_16x16x32_bf16 v[6:9], v[210:213], v[202:205], v[6:9]
	v_mfma_f32_16x16x32_bf16 v[2:5], v[218:221], v[202:205], v[2:5]
	v_mfma_f32_16x16x32_bf16 v[54:57], v[214:217], v[172:175], v[54:57]
	v_mfma_f32_16x16x32_bf16 v[50:53], v[222:225], v[172:175], v[50:53]
	v_mfma_f32_16x16x32_bf16 v[38:41], v[214:217], v[190:193], v[38:41]
	v_mfma_f32_16x16x32_bf16 v[34:37], v[222:225], v[190:193], v[34:37]
	v_mfma_f32_16x16x32_bf16 v[22:25], v[214:217], v[198:201], v[22:25]
	v_mfma_f32_16x16x32_bf16 v[18:21], v[222:225], v[198:201], v[18:21]
	v_mfma_f32_16x16x32_bf16 v[6:9], v[214:217], v[206:209], v[6:9]
	v_mfma_f32_16x16x32_bf16 v[2:5], v[222:225], v[206:209], v[2:5]
	s_barrier
	s_add_i32 s47, s47, 2
	s_add_u32 s6, s6, 0x100
	s_addc_u32 s7, s7, 0
.LBB0_1408:
	s_add_u32 s16, s14, s6
	s_addc_u32 s17, s15, s7
	s_add_u32 s16, s16, 0x100
	s_addc_u32 s17, s17, 0
	s_add_u32 s48, s45, s6
	s_addc_u32 s49, s46, s7
	s_add_i32 s50, 0, 0x10000
	s_cmpk_eq_i32 s6, 0xf00
	s_cselect_b32 s19, s11, s17
	s_cselect_b32 s18, s10, s16
	s_cselect_b32 s17, s3, s49
	s_cselect_b32 s16, s44, s48
	v_lshl_add_u64 v[162:163], v[142:143], 0, s[6:7]
	s_add_i32 m0, s30, 0xc000
	ds_read_b128 v[168:171], v166
	ds_read_b128 v[172:175], v166 offset:1024
	ds_read_b128 v[186:189], v166 offset:2048
	ds_read_b128 v[190:193], v166 offset:3072
	ds_read_b128 v[194:197], v166 offset:4096
	ds_read_b128 v[198:201], v166 offset:5120
	ds_read_b128 v[202:205], v166 offset:6144
	ds_read_b128 v[206:209], v166 offset:7168
	global_load_lds_dwordx4 v[162:163], off
	v_lshl_add_u64 v[162:163], v[144:145], 0, s[6:7]
	s_add_i32 m0, s30, 0xe000
	s_nop 0
	global_load_lds_dwordx4 v[162:163], off
	s_waitcnt lgkmcnt(8)
	s_barrier
	s_waitcnt lgkmcnt(0)
	s_waitcnt lgkmcnt(0)
	v_mfma_f32_16x16x32_bf16 v[126:129], v[146:149], v[168:171], v[126:129]
	v_mfma_f32_16x16x32_bf16 v[122:125], v[154:157], v[168:171], v[122:125]
	v_mfma_f32_16x16x32_bf16 v[110:113], v[146:149], v[186:189], v[110:113]
	v_mfma_f32_16x16x32_bf16 v[106:109], v[154:157], v[186:189], v[106:109]
	v_mfma_f32_16x16x32_bf16 v[94:97], v[146:149], v[194:197], v[94:97]
	v_mfma_f32_16x16x32_bf16 v[90:93], v[154:157], v[194:197], v[90:93]
	v_mfma_f32_16x16x32_bf16 v[78:81], v[146:149], v[202:205], v[78:81]
	v_mfma_f32_16x16x32_bf16 v[74:77], v[154:157], v[202:205], v[74:77]
	v_mfma_f32_16x16x32_bf16 v[126:129], v[150:153], v[172:175], v[126:129]
	v_mfma_f32_16x16x32_bf16 v[122:125], v[158:161], v[172:175], v[122:125]
	v_mfma_f32_16x16x32_bf16 v[110:113], v[150:153], v[190:193], v[110:113]
	v_mfma_f32_16x16x32_bf16 v[106:109], v[158:161], v[190:193], v[106:109]
	v_mfma_f32_16x16x32_bf16 v[94:97], v[150:153], v[198:201], v[94:97]
	v_mfma_f32_16x16x32_bf16 v[90:93], v[158:161], v[198:201], v[90:93]
	v_mfma_f32_16x16x32_bf16 v[78:81], v[150:153], v[206:209], v[78:81]
	v_mfma_f32_16x16x32_bf16 v[74:77], v[158:161], v[206:209], v[74:77]
	s_barrier
	s_add_i32 s51, 0, 0x14000
	v_add_u32_e32 v162, s51, v164
	s_add_i32 s48, s50, s29
	ds_read_b128 v[210:213], v162
	ds_read_b128 v[214:217], v162 offset:1024
	ds_read_b128 v[218:221], v162 offset:2048
	ds_read_b128 v[222:225], v162 offset:3072
	s_add_u32 s64, s16, 0x80
	s_addc_u32 s65, s17, 0
	s_mov_b32 m0, s48
	s_nop 0
	global_load_lds_dwordx4 v132, s[16:17]
	s_add_i32 m0, s48, 0x2000
	s_nop 0
	global_load_lds_dwordx4 v136, s[16:17]
	s_barrier
	s_waitcnt lgkmcnt(0)
	s_waitcnt lgkmcnt(0)
	v_mfma_f32_16x16x32_bf16 v[118:121], v[210:213], v[168:171], v[118:121]
	v_mfma_f32_16x16x32_bf16 v[114:117], v[218:221], v[168:171], v[114:117]
	v_mfma_f32_16x16x32_bf16 v[102:105], v[210:213], v[186:189], v[102:105]
	v_mfma_f32_16x16x32_bf16 v[98:101], v[218:221], v[186:189], v[98:101]
	v_mfma_f32_16x16x32_bf16 v[86:89], v[210:213], v[194:197], v[86:89]
	v_mfma_f32_16x16x32_bf16 v[82:85], v[218:221], v[194:197], v[82:85]
	v_mfma_f32_16x16x32_bf16 v[70:73], v[210:213], v[202:205], v[70:73]
	v_mfma_f32_16x16x32_bf16 v[66:69], v[218:221], v[202:205], v[66:69]
	ds_read_b128 v[168:171], v166 offset:16384
	v_mfma_f32_16x16x32_bf16 v[118:121], v[214:217], v[172:175], v[118:121]
	v_mfma_f32_16x16x32_bf16 v[114:117], v[222:225], v[172:175], v[114:117]
	ds_read_b128 v[186:189], v166 offset:18432
	v_mfma_f32_16x16x32_bf16 v[102:105], v[214:217], v[190:193], v[102:105]
	v_mfma_f32_16x16x32_bf16 v[98:101], v[222:225], v[190:193], v[98:101]
	ds_read_b128 v[194:197], v166 offset:20480
	v_mfma_f32_16x16x32_bf16 v[86:89], v[214:217], v[198:201], v[86:89]
	v_mfma_f32_16x16x32_bf16 v[82:85], v[222:225], v[198:201], v[82:85]
	ds_read_b128 v[202:205], v166 offset:22528
	v_mfma_f32_16x16x32_bf16 v[70:73], v[214:217], v[206:209], v[70:73]
	v_mfma_f32_16x16x32_bf16 v[66:69], v[222:225], v[206:209], v[66:69]
	s_barrier
	s_mov_b32 m0, s30
	s_add_u32 s62, s18, 0x80
	s_addc_u32 s63, s19, 0
	ds_read_b128 v[172:175], v166 offset:17408
	ds_read_b128 v[190:193], v166 offset:19456
	ds_read_b128 v[198:201], v166 offset:21504
	ds_read_b128 v[206:209], v166 offset:23552
	global_load_lds_dwordx4 v130, s[18:19]
	s_mov_b32 m0, s31
	s_nop 0
	global_load_lds_dwordx4 v134, s[18:19]
	s_waitcnt vmcnt(10)
	s_barrier
	s_waitcnt lgkmcnt(0)
	s_waitcnt lgkmcnt(0)
	v_mfma_f32_16x16x32_bf16 v[62:65], v[146:149], v[168:171], v[62:65]
	v_mfma_f32_16x16x32_bf16 v[58:61], v[154:157], v[168:171], v[58:61]
	v_mfma_f32_16x16x32_bf16 v[46:49], v[146:149], v[186:189], v[46:49]
	v_mfma_f32_16x16x32_bf16 v[42:45], v[154:157], v[186:189], v[42:45]
	v_mfma_f32_16x16x32_bf16 v[30:33], v[146:149], v[194:197], v[30:33]
	v_mfma_f32_16x16x32_bf16 v[26:29], v[154:157], v[194:197], v[26:29]
	v_mfma_f32_16x16x32_bf16 v[14:17], v[146:149], v[202:205], v[14:17]
	v_mfma_f32_16x16x32_bf16 v[10:13], v[154:157], v[202:205], v[10:13]
	v_mfma_f32_16x16x32_bf16 v[62:65], v[150:153], v[172:175], v[62:65]
	v_mfma_f32_16x16x32_bf16 v[58:61], v[158:161], v[172:175], v[58:61]
	v_mfma_f32_16x16x32_bf16 v[46:49], v[150:153], v[190:193], v[46:49]
	v_mfma_f32_16x16x32_bf16 v[42:45], v[158:161], v[190:193], v[42:45]
	v_mfma_f32_16x16x32_bf16 v[30:33], v[150:153], v[198:201], v[30:33]
	v_mfma_f32_16x16x32_bf16 v[26:29], v[158:161], v[198:201], v[26:29]
	v_mfma_f32_16x16x32_bf16 v[14:17], v[150:153], v[206:209], v[14:17]
	v_mfma_f32_16x16x32_bf16 v[10:13], v[158:161], v[206:209], v[10:13]
	s_barrier
	v_add_u32_e32 v158, 0x18000, v164
	ds_read_b128 v[146:149], v158
	ds_read_b128 v[150:153], v158 offset:1024
	ds_read_b128 v[154:157], v158 offset:2048
	ds_read_b128 v[158:161], v158 offset:3072
	s_add_u32 s48, s16, 0x80000
	s_addc_u32 s49, s17, 0
	s_add_i32 s50, s51, s29
	s_mov_b32 m0, s50
	s_nop 0
	global_load_lds_dwordx4 v132, s[48:49]
	s_add_i32 m0, s50, 0x2000
	s_nop 0
	global_load_lds_dwordx4 v136, s[48:49]
	s_waitcnt vmcnt(6)
	s_barrier
	v_mfma_f32_16x16x32_bf16 v[54:57], v[210:213], v[168:171], v[54:57]
	v_mfma_f32_16x16x32_bf16 v[50:53], v[218:221], v[168:171], v[50:53]
	v_mfma_f32_16x16x32_bf16 v[38:41], v[210:213], v[186:189], v[38:41]
	v_mfma_f32_16x16x32_bf16 v[34:37], v[218:221], v[186:189], v[34:37]
	v_mfma_f32_16x16x32_bf16 v[22:25], v[210:213], v[194:197], v[22:25]
	v_mfma_f32_16x16x32_bf16 v[18:21], v[218:221], v[194:197], v[18:21]
	v_mfma_f32_16x16x32_bf16 v[6:9], v[210:213], v[202:205], v[6:9]
	v_mfma_f32_16x16x32_bf16 v[2:5], v[218:221], v[202:205], v[2:5]
	v_mfma_f32_16x16x32_bf16 v[54:57], v[214:217], v[172:175], v[54:57]
	v_mfma_f32_16x16x32_bf16 v[50:53], v[222:225], v[172:175], v[50:53]
	v_mfma_f32_16x16x32_bf16 v[38:41], v[214:217], v[190:193], v[38:41]
	v_mfma_f32_16x16x32_bf16 v[34:37], v[222:225], v[190:193], v[34:37]
	v_mfma_f32_16x16x32_bf16 v[22:25], v[214:217], v[198:201], v[22:25]
	v_mfma_f32_16x16x32_bf16 v[18:21], v[222:225], v[198:201], v[18:21]
	v_mfma_f32_16x16x32_bf16 v[6:9], v[214:217], v[206:209], v[6:9]
	v_mfma_f32_16x16x32_bf16 v[2:5], v[222:225], v[206:209], v[2:5]
	s_barrier
	s_add_i32 s48, 0, 0x18000
	s_add_u32 s18, s18, s80
	s_addc_u32 s19, s19, 0
	s_mov_b32 m0, s34
	ds_read_b128 v[168:171], v166 offset:32768
	ds_read_b128 v[172:175], v166 offset:33792
	ds_read_b128 v[186:189], v166 offset:34816
	ds_read_b128 v[190:193], v166 offset:35840
	ds_read_b128 v[194:197], v166 offset:36864
	ds_read_b128 v[198:201], v166 offset:37888
	ds_read_b128 v[202:205], v166 offset:38912
	ds_read_b128 v[206:209], v166 offset:39936
	global_load_lds_dwordx4 v130, s[18:19]
	s_mov_b32 m0, s35
	s_nop 0
	global_load_lds_dwordx4 v134, s[18:19]
	s_waitcnt lgkmcnt(8)
	s_barrier
	s_waitcnt lgkmcnt(0)
	s_waitcnt lgkmcnt(0)
	v_mfma_f32_16x16x32_bf16 v[126:129], v[146:149], v[168:171], v[126:129]
	v_mfma_f32_16x16x32_bf16 v[122:125], v[154:157], v[168:171], v[122:125]
	v_mfma_f32_16x16x32_bf16 v[110:113], v[146:149], v[186:189], v[110:113]
	v_mfma_f32_16x16x32_bf16 v[106:109], v[154:157], v[186:189], v[106:109]
	v_mfma_f32_16x16x32_bf16 v[94:97], v[146:149], v[194:197], v[94:97]
	v_mfma_f32_16x16x32_bf16 v[90:93], v[154:157], v[194:197], v[90:93]
	v_mfma_f32_16x16x32_bf16 v[78:81], v[146:149], v[202:205], v[78:81]
	v_mfma_f32_16x16x32_bf16 v[74:77], v[154:157], v[202:205], v[74:77]
	v_mfma_f32_16x16x32_bf16 v[126:129], v[150:153], v[172:175], v[126:129]
	v_mfma_f32_16x16x32_bf16 v[122:125], v[158:161], v[172:175], v[122:125]
	v_mfma_f32_16x16x32_bf16 v[110:113], v[150:153], v[190:193], v[110:113]
	v_mfma_f32_16x16x32_bf16 v[106:109], v[158:161], v[190:193], v[106:109]
	v_mfma_f32_16x16x32_bf16 v[94:97], v[150:153], v[198:201], v[94:97]
	v_mfma_f32_16x16x32_bf16 v[90:93], v[158:161], v[198:201], v[90:93]
	v_mfma_f32_16x16x32_bf16 v[78:81], v[150:153], v[206:209], v[78:81]
	v_mfma_f32_16x16x32_bf16 v[74:77], v[158:161], v[206:209], v[74:77]
	s_barrier
	s_add_i32 s18, 0, 0x1c000
	s_add_i32 s19, s48, s29
	v_add_u32_e32 v167, s18, v164
	s_mov_b32 m0, s19
	ds_read_b128 v[210:213], v167
	ds_read_b128 v[214:217], v167 offset:1024
	ds_read_b128 v[218:221], v167 offset:2048
	ds_read_b128 v[222:225], v167 offset:3072
	global_load_lds_dwordx4 v132, s[64:65]
	s_add_i32 m0, s19, 0x2000
	s_nop 0
	global_load_lds_dwordx4 v136, s[64:65]
	s_barrier
	s_waitcnt lgkmcnt(0)
	s_waitcnt lgkmcnt(0)
	v_mfma_f32_16x16x32_bf16 v[118:121], v[210:213], v[168:171], v[118:121]
	v_mfma_f32_16x16x32_bf16 v[114:117], v[218:221], v[168:171], v[114:117]
	v_mfma_f32_16x16x32_bf16 v[102:105], v[210:213], v[186:189], v[102:105]
	v_mfma_f32_16x16x32_bf16 v[98:101], v[218:221], v[186:189], v[98:101]
	v_mfma_f32_16x16x32_bf16 v[86:89], v[210:213], v[194:197], v[86:89]
	v_mfma_f32_16x16x32_bf16 v[82:85], v[218:221], v[194:197], v[82:85]
	v_mfma_f32_16x16x32_bf16 v[70:73], v[210:213], v[202:205], v[70:73]
	v_mfma_f32_16x16x32_bf16 v[66:69], v[218:221], v[202:205], v[66:69]
	ds_read_b128 v[168:171], v166 offset:49152
	v_mfma_f32_16x16x32_bf16 v[118:121], v[214:217], v[172:175], v[118:121]
	v_mfma_f32_16x16x32_bf16 v[114:117], v[222:225], v[172:175], v[114:117]
	ds_read_b128 v[186:189], v166 offset:51200
	v_mfma_f32_16x16x32_bf16 v[102:105], v[214:217], v[190:193], v[102:105]
	v_mfma_f32_16x16x32_bf16 v[98:101], v[222:225], v[190:193], v[98:101]
	ds_read_b128 v[194:197], v166 offset:53248
	v_mfma_f32_16x16x32_bf16 v[86:89], v[214:217], v[198:201], v[86:89]
	v_mfma_f32_16x16x32_bf16 v[82:85], v[222:225], v[198:201], v[82:85]
	ds_read_b128 v[202:205], v166 offset:55296
	v_mfma_f32_16x16x32_bf16 v[70:73], v[214:217], v[206:209], v[70:73]
	v_mfma_f32_16x16x32_bf16 v[66:69], v[222:225], v[206:209], v[66:69]
	s_barrier
	s_mov_b32 m0, s38
	ds_read_b128 v[172:175], v166 offset:50176
	ds_read_b128 v[190:193], v166 offset:52224
	ds_read_b128 v[198:201], v166 offset:54272
	ds_read_b128 v[206:209], v166 offset:56320
	global_load_lds_dwordx4 v130, s[62:63]
	s_mov_b32 m0, s39
	s_nop 0
	global_load_lds_dwordx4 v134, s[62:63]
	s_waitcnt vmcnt(10)
	s_barrier
	s_waitcnt lgkmcnt(0)
	s_waitcnt lgkmcnt(0)
	v_mfma_f32_16x16x32_bf16 v[62:65], v[146:149], v[168:171], v[62:65]
	v_mfma_f32_16x16x32_bf16 v[58:61], v[154:157], v[168:171], v[58:61]
	v_mfma_f32_16x16x32_bf16 v[46:49], v[146:149], v[186:189], v[46:49]
	v_mfma_f32_16x16x32_bf16 v[42:45], v[154:157], v[186:189], v[42:45]
	v_mfma_f32_16x16x32_bf16 v[30:33], v[146:149], v[194:197], v[30:33]
	v_mfma_f32_16x16x32_bf16 v[26:29], v[154:157], v[194:197], v[26:29]
	v_mfma_f32_16x16x32_bf16 v[14:17], v[146:149], v[202:205], v[14:17]
	v_mfma_f32_16x16x32_bf16 v[10:13], v[154:157], v[202:205], v[10:13]
	v_mfma_f32_16x16x32_bf16 v[62:65], v[150:153], v[172:175], v[62:65]
	v_mfma_f32_16x16x32_bf16 v[58:61], v[158:161], v[172:175], v[58:61]
	v_mfma_f32_16x16x32_bf16 v[46:49], v[150:153], v[190:193], v[46:49]
	v_mfma_f32_16x16x32_bf16 v[42:45], v[158:161], v[190:193], v[42:45]
	v_mfma_f32_16x16x32_bf16 v[30:33], v[150:153], v[198:201], v[30:33]
	v_mfma_f32_16x16x32_bf16 v[26:29], v[158:161], v[198:201], v[26:29]
	v_mfma_f32_16x16x32_bf16 v[14:17], v[150:153], v[206:209], v[14:17]
	v_mfma_f32_16x16x32_bf16 v[10:13], v[158:161], v[206:209], v[10:13]
	s_barrier
	v_add_u32_e32 v158, 0x10000, v164
	ds_read_b128 v[146:149], v158
	ds_read_b128 v[150:153], v158 offset:1024
	ds_read_b128 v[154:157], v158 offset:2048
	ds_read_b128 v[158:161], v158 offset:3072
	s_add_u32 s16, s16, 0x80080
	s_addc_u32 s17, s17, 0
	s_add_i32 s18, s18, s29
	s_mov_b32 m0, s18
	s_nop 0
	global_load_lds_dwordx4 v132, s[16:17]
	s_add_i32 m0, s18, 0x2000
	s_nop 0
	global_load_lds_dwordx4 v136, s[16:17]
	s_waitcnt vmcnt(6)
	s_barrier
	v_mfma_f32_16x16x32_bf16 v[54:57], v[210:213], v[168:171], v[54:57]
	v_mfma_f32_16x16x32_bf16 v[50:53], v[218:221], v[168:171], v[50:53]
	v_mfma_f32_16x16x32_bf16 v[38:41], v[210:213], v[186:189], v[38:41]
	v_mfma_f32_16x16x32_bf16 v[34:37], v[218:221], v[186:189], v[34:37]
	v_mfma_f32_16x16x32_bf16 v[22:25], v[210:213], v[194:197], v[22:25]
	v_mfma_f32_16x16x32_bf16 v[18:21], v[218:221], v[194:197], v[18:21]
	v_mfma_f32_16x16x32_bf16 v[6:9], v[210:213], v[202:205], v[6:9]
	v_mfma_f32_16x16x32_bf16 v[2:5], v[218:221], v[202:205], v[2:5]
	v_mfma_f32_16x16x32_bf16 v[54:57], v[214:217], v[172:175], v[54:57]
	v_mfma_f32_16x16x32_bf16 v[50:53], v[222:225], v[172:175], v[50:53]
	v_mfma_f32_16x16x32_bf16 v[38:41], v[214:217], v[190:193], v[38:41]
	v_mfma_f32_16x16x32_bf16 v[34:37], v[222:225], v[190:193], v[34:37]
	v_mfma_f32_16x16x32_bf16 v[22:25], v[214:217], v[198:201], v[22:25]
	v_mfma_f32_16x16x32_bf16 v[18:21], v[222:225], v[198:201], v[18:21]
	v_mfma_f32_16x16x32_bf16 v[6:9], v[214:217], v[206:209], v[6:9]
	v_mfma_f32_16x16x32_bf16 v[2:5], v[222:225], v[206:209], v[2:5]
	s_barrier
	s_add_i32 s47, s47, 2
	s_add_u32 s6, s6, 0x100
	s_addc_u32 s7, s7, 0
	s_cmp_gt_u32 s47, 29
	s_cbranch_scc0 .LBB0_1408
	s_waitcnt lgkmcnt(0)
	s_ashr_i32 s3, s33, 5
	s_mul_hi_i32 s7, s3, 0x9000
	s_mul_i32 s3, s3, 0x9000
	v_lshl_or_b32 v168, s43, 8, v165
	s_add_u32 s6, s36, s3
	s_addc_u32 s7, s37, s7
	v_ashrrev_i32_e32 v169, 31, v168
	v_lshl_add_u64 v[162:163], v[168:169], 2, s[6:7]
	global_load_dwordx4 v[142:145], v[162:163], off offset:16
	global_load_dwordx4 v[146:149], v[162:163], off
	v_mov_b32_e32 v158, v162
	v_mov_b32_e32 v159, v163
	v_lshl_add_u32 v162, s33, 8, v1
	v_ashrrev_i32_e32 v163, 31, v162
	v_lshlrev_b64 v[152:153], 12, v[162:163]
	v_lshl_add_u64 v[152:153], s[8:9], 0, v[152:153]
	v_lshl_add_u64 v[152:153], v[168:169], 1, v[152:153]
	v_mov_b32_e32 v156, 0x10000
	v_mov_b32_e32 v157, 0
	global_load_dwordx4 v[174:177], v[152:153], off offset:2048
	global_load_dwordx4 v[186:189], v[152:153], off offset:2304
	v_lshl_add_u64 v[152:153], v[152:153], 0, v[156:157]
	global_load_dwordx4 v[190:193], v[152:153], off offset:2048
	global_load_dwordx4 v[194:197], v[152:153], off offset:2304
	v_lshl_add_u64 v[152:153], v[152:153], 0, v[156:157]
	global_load_dwordx4 v[198:201], v[152:153], off offset:2048
	global_load_dwordx4 v[202:205], v[152:153], off offset:2304
	v_lshl_add_u64 v[152:153], v[152:153], 0, v[156:157]
	global_load_dwordx4 v[206:209], v[152:153], off offset:2048
	global_load_dwordx4 v[210:213], v[152:153], off offset:2304
	v_mov_b32_e32 v156, 0x50000
	v_lshl_add_u64 v[152:153], v[152:153], 0, v[156:157]
	v_mov_b32_e32 v156, 0x10000
	global_load_dwordx4 v[214:217], v[152:153], off offset:2048
	global_load_dwordx4 v[218:221], v[152:153], off offset:2304
	v_lshl_add_u64 v[152:153], v[152:153], 0, v[156:157]
	global_load_dwordx4 v[222:225], v[152:153], off offset:2048
	global_load_dwordx4 v[226:229], v[152:153], off offset:2304
	v_lshl_add_u64 v[152:153], v[152:153], 0, v[156:157]
	global_load_dwordx4 v[230:233], v[152:153], off offset:2048
	global_load_dwordx4 v[236:239], v[152:153], off offset:2304
	v_lshl_add_u64 v[152:153], v[152:153], 0, v[156:157]
	global_load_dwordx4 v[246:249], v[152:153], off offset:2048
	global_load_dwordx4 v[250:253], v[152:153], off offset:2304
	s_mov_b64 s[6:7], 0x80000
	s_and_b64 vcc, exec, s[4:5]
	s_mov_b32 s43, s2
	s_mov_b64 s[16:17], s[12:13]
	s_mov_b64 s[14:15], s[10:11]
	s_waitcnt vmcnt(16)
	v_pk_add_f32 v[150:151], v[144:145], 1.0 op_sel_hi:[1,0]
	v_pk_add_f32 v[154:155], v[142:143], 1.0 op_sel_hi:[1,0]
	global_load_dwordx4 v[142:145], v[158:159], off offset:512
	global_load_dwordx4 v[158:161], v[158:159], off offset:528
	v_pk_add_f32 v[156:157], v[146:147], 1.0 op_sel_hi:[1,0]
	v_pk_add_f32 v[152:153], v[148:149], 1.0 op_sel_hi:[1,0]
	s_mov_b32 s33, s42
	s_waitcnt vmcnt(0)
	v_pk_add_f32 v[146:147], v[144:145], 1.0 op_sel_hi:[1,0]
	v_pk_add_f32 v[144:145], v[158:159], 1.0 op_sel_hi:[1,0]
	v_lshlrev_b64 v[158:159], 12, v[162:163]
	v_pk_add_f32 v[148:149], v[142:143], 1.0 op_sel_hi:[1,0]
	v_pk_add_f32 v[142:143], v[160:161], 1.0 op_sel_hi:[1,0]
	v_lshl_add_u64 v[158:159], s[8:9], 0, v[158:159]
	v_lshlrev_b64 v[160:161], 1, v[168:169]
	v_lshl_add_u64 v[158:159], v[158:159], 0, v[160:161]
	v_mov_b32_e32 v168, v174
	v_mov_b32_e32 v169, v175
	v_mov_b32_e32 v170, v176
	v_mov_b32_e32 v171, v177
	s_nop 0
	v_lshlrev_b32_e32 v172, 16, v168
	v_and_b32_e32 v173, 0xffff0000, v168
	v_lshlrev_b32_e32 v168, 16, v169
	v_and_b32_e32 v169, 0xffff0000, v169
	v_pk_fma_f32 v[128:129], v[128:129], v[152:153], v[168:169]
	v_lshlrev_b32_e32 v168, 16, v170
	v_and_b32_e32 v169, 0xffff0000, v170
	v_pk_fma_f32 v[168:169], v[122:123], v[154:155], v[168:169]
	v_lshlrev_b32_e32 v122, 16, v171
	v_and_b32_e32 v123, 0xffff0000, v171
	v_pk_fma_f32 v[126:127], v[126:127], v[156:157], v[172:173]
	v_pk_fma_f32 v[170:171], v[124:125], v[150:151], v[122:123]
	v_cvt_pk_bf16_f32 v122, v126, v127
	v_cvt_pk_bf16_f32 v123, v128, v129
	v_cvt_pk_bf16_f32 v124, v168, v169
	v_cvt_pk_bf16_f32 v125, v170, v171
	global_store_dwordx4 v[158:159], v[122:125], off offset:2048
	s_nop 1
	v_mov_b32_e32 v122, v186
	v_mov_b32_e32 v123, v187
	v_mov_b32_e32 v124, v188
	v_mov_b32_e32 v125, v189
	s_nop 0
	v_lshlrev_b32_e32 v126, 16, v122
	v_and_b32_e32 v127, 0xffff0000, v122
	v_lshlrev_b32_e32 v122, 16, v123
	v_and_b32_e32 v123, 0xffff0000, v123
	v_pk_fma_f32 v[120:121], v[120:121], v[146:147], v[122:123]
	v_lshlrev_b32_e32 v122, 16, v124
	v_and_b32_e32 v123, 0xffff0000, v124
	v_pk_fma_f32 v[122:123], v[114:115], v[144:145], v[122:123]
	v_lshlrev_b32_e32 v114, 16, v125
	v_and_b32_e32 v115, 0xffff0000, v125
	v_pk_fma_f32 v[118:119], v[118:119], v[148:149], v[126:127]
	v_pk_fma_f32 v[124:125], v[116:117], v[142:143], v[114:115]
	v_cvt_pk_bf16_f32 v114, v118, v119
	v_cvt_pk_bf16_f32 v115, v120, v121
	v_cvt_pk_bf16_f32 v116, v122, v123
	v_cvt_pk_bf16_f32 v117, v124, v125
	global_store_dwordx4 v[158:159], v[114:117], off offset:2304
	s_nop 1
	v_or_b32_e32 v114, 16, v162
	v_ashrrev_i32_e32 v115, 31, v114
	v_lshlrev_b64 v[114:115], 12, v[114:115]
	v_lshl_add_u64 v[114:115], s[8:9], 0, v[114:115]
	v_lshl_add_u64 v[118:119], v[114:115], 0, v[160:161]
	v_mov_b32_e32 v114, v190
	v_mov_b32_e32 v115, v191
	v_mov_b32_e32 v116, v192
	v_mov_b32_e32 v117, v193
	s_nop 0
	v_lshlrev_b32_e32 v120, 16, v114
	v_and_b32_e32 v121, 0xffff0000, v114
	v_lshlrev_b32_e32 v114, 16, v115
	v_and_b32_e32 v115, 0xffff0000, v115
	v_pk_fma_f32 v[112:113], v[112:113], v[152:153], v[114:115]
	v_lshlrev_b32_e32 v114, 16, v116
	v_and_b32_e32 v115, 0xffff0000, v116
	v_pk_fma_f32 v[114:115], v[106:107], v[154:155], v[114:115]
	v_lshlrev_b32_e32 v106, 16, v117
	v_and_b32_e32 v107, 0xffff0000, v117
	v_pk_fma_f32 v[110:111], v[110:111], v[156:157], v[120:121]
	v_pk_fma_f32 v[116:117], v[108:109], v[150:151], v[106:107]
	v_cvt_pk_bf16_f32 v106, v110, v111
	v_cvt_pk_bf16_f32 v107, v112, v113
	v_cvt_pk_bf16_f32 v108, v114, v115
	v_cvt_pk_bf16_f32 v109, v116, v117
	global_store_dwordx4 v[118:119], v[106:109], off offset:2048
	s_nop 1
	v_mov_b32_e32 v106, v194
	v_mov_b32_e32 v107, v195
	v_mov_b32_e32 v108, v196
	v_mov_b32_e32 v109, v197
	s_nop 0
	v_lshlrev_b32_e32 v110, 16, v106
	v_and_b32_e32 v111, 0xffff0000, v106
	v_lshlrev_b32_e32 v106, 16, v107
	v_and_b32_e32 v107, 0xffff0000, v107
	v_pk_fma_f32 v[104:105], v[104:105], v[146:147], v[106:107]
	v_lshlrev_b32_e32 v106, 16, v108
	v_and_b32_e32 v107, 0xffff0000, v108
	v_pk_fma_f32 v[106:107], v[98:99], v[144:145], v[106:107]
	v_lshlrev_b32_e32 v98, 16, v109
	v_and_b32_e32 v99, 0xffff0000, v109
	v_pk_fma_f32 v[102:103], v[102:103], v[148:149], v[110:111]
	v_pk_fma_f32 v[108:109], v[100:101], v[142:143], v[98:99]
	v_cvt_pk_bf16_f32 v98, v102, v103
	v_cvt_pk_bf16_f32 v99, v104, v105
	v_cvt_pk_bf16_f32 v100, v106, v107
	v_cvt_pk_bf16_f32 v101, v108, v109
	global_store_dwordx4 v[118:119], v[98:101], off offset:2304
	s_nop 1
	v_or_b32_e32 v98, 32, v162
	v_ashrrev_i32_e32 v99, 31, v98
	v_lshlrev_b64 v[98:99], 12, v[98:99]
	v_lshl_add_u64 v[98:99], s[8:9], 0, v[98:99]
	v_lshl_add_u64 v[102:103], v[98:99], 0, v[160:161]
	v_mov_b32_e32 v98, v198
	v_mov_b32_e32 v99, v199
	v_mov_b32_e32 v100, v200
	v_mov_b32_e32 v101, v201
	s_nop 0
	v_lshlrev_b32_e32 v104, 16, v98
	v_and_b32_e32 v105, 0xffff0000, v98
	v_lshlrev_b32_e32 v98, 16, v99
	v_and_b32_e32 v99, 0xffff0000, v99
	v_pk_fma_f32 v[96:97], v[96:97], v[152:153], v[98:99]
	v_lshlrev_b32_e32 v98, 16, v100
	v_and_b32_e32 v99, 0xffff0000, v100
	v_pk_fma_f32 v[98:99], v[90:91], v[154:155], v[98:99]
	v_lshlrev_b32_e32 v90, 16, v101
	v_and_b32_e32 v91, 0xffff0000, v101
	v_pk_fma_f32 v[94:95], v[94:95], v[156:157], v[104:105]
	v_pk_fma_f32 v[100:101], v[92:93], v[150:151], v[90:91]
	v_cvt_pk_bf16_f32 v90, v94, v95
	v_cvt_pk_bf16_f32 v91, v96, v97
	v_cvt_pk_bf16_f32 v92, v98, v99
	v_cvt_pk_bf16_f32 v93, v100, v101
	global_store_dwordx4 v[102:103], v[90:93], off offset:2048
	s_nop 1
	v_mov_b32_e32 v90, v202
	v_mov_b32_e32 v91, v203
	v_mov_b32_e32 v92, v204
	v_mov_b32_e32 v93, v205
	s_nop 0
	v_lshlrev_b32_e32 v94, 16, v90
	v_and_b32_e32 v95, 0xffff0000, v90
	v_lshlrev_b32_e32 v90, 16, v91
	v_and_b32_e32 v91, 0xffff0000, v91
	v_pk_fma_f32 v[88:89], v[88:89], v[146:147], v[90:91]
	v_lshlrev_b32_e32 v90, 16, v92
	v_and_b32_e32 v91, 0xffff0000, v92
	v_pk_fma_f32 v[90:91], v[82:83], v[144:145], v[90:91]
	v_lshlrev_b32_e32 v82, 16, v93
	v_and_b32_e32 v83, 0xffff0000, v93
	v_pk_fma_f32 v[86:87], v[86:87], v[148:149], v[94:95]
	v_pk_fma_f32 v[92:93], v[84:85], v[142:143], v[82:83]
	v_cvt_pk_bf16_f32 v82, v86, v87
	v_cvt_pk_bf16_f32 v83, v88, v89
	v_cvt_pk_bf16_f32 v84, v90, v91
	v_cvt_pk_bf16_f32 v85, v92, v93
	global_store_dwordx4 v[102:103], v[82:85], off offset:2304
	s_nop 1
	v_or_b32_e32 v82, 48, v162
	v_ashrrev_i32_e32 v83, 31, v82
	v_lshlrev_b64 v[82:83], 12, v[82:83]
	v_lshl_add_u64 v[82:83], s[8:9], 0, v[82:83]
	v_lshl_add_u64 v[82:83], v[82:83], 0, v[160:161]
	v_mov_b32_e32 v84, v206
	v_mov_b32_e32 v85, v207
	v_mov_b32_e32 v86, v208
	v_mov_b32_e32 v87, v209
	s_nop 0
	v_lshlrev_b32_e32 v88, 16, v84
	v_and_b32_e32 v89, 0xffff0000, v84
	v_lshlrev_b32_e32 v84, 16, v85
	v_and_b32_e32 v85, 0xffff0000, v85
	v_pk_fma_f32 v[80:81], v[80:81], v[152:153], v[84:85]
	v_lshlrev_b32_e32 v84, 16, v86
	v_and_b32_e32 v85, 0xffff0000, v86
	v_pk_fma_f32 v[84:85], v[74:75], v[154:155], v[84:85]
	v_lshlrev_b32_e32 v74, 16, v87
	v_and_b32_e32 v75, 0xffff0000, v87
	v_pk_fma_f32 v[78:79], v[78:79], v[156:157], v[88:89]
	v_pk_fma_f32 v[86:87], v[76:77], v[150:151], v[74:75]
	v_cvt_pk_bf16_f32 v74, v78, v79
	v_cvt_pk_bf16_f32 v75, v80, v81
	v_cvt_pk_bf16_f32 v76, v84, v85
	v_cvt_pk_bf16_f32 v77, v86, v87
	global_store_dwordx4 v[82:83], v[74:77], off offset:2048
	s_nop 1
	v_mov_b32_e32 v74, v210
	v_mov_b32_e32 v75, v211
	v_mov_b32_e32 v76, v212
	v_mov_b32_e32 v77, v213
	s_nop 0
	v_lshlrev_b32_e32 v78, 16, v74
	v_and_b32_e32 v79, 0xffff0000, v74
	v_lshlrev_b32_e32 v74, 16, v75
	v_and_b32_e32 v75, 0xffff0000, v75
	v_pk_fma_f32 v[72:73], v[72:73], v[146:147], v[74:75]
	v_lshlrev_b32_e32 v74, 16, v76
	v_and_b32_e32 v75, 0xffff0000, v76
	v_pk_fma_f32 v[74:75], v[66:67], v[144:145], v[74:75]
	v_lshlrev_b32_e32 v66, 16, v77
	v_and_b32_e32 v67, 0xffff0000, v77
	v_pk_fma_f32 v[70:71], v[70:71], v[148:149], v[78:79]
	v_pk_fma_f32 v[76:77], v[68:69], v[142:143], v[66:67]
	v_cvt_pk_bf16_f32 v66, v70, v71
	v_cvt_pk_bf16_f32 v67, v72, v73
	v_cvt_pk_bf16_f32 v68, v74, v75
	v_cvt_pk_bf16_f32 v69, v76, v77
	v_lshl_add_u64 v[70:71], v[158:159], 0, s[6:7]
	global_store_dwordx4 v[82:83], v[66:69], off offset:2304
	s_nop 1
	v_mov_b32_e32 v66, v214
	v_mov_b32_e32 v67, v215
	v_mov_b32_e32 v68, v216
	v_mov_b32_e32 v69, v217
	s_mov_b64 s[6:7], 0x90000
	s_nop 0
	v_lshlrev_b32_e32 v72, 16, v66
	v_and_b32_e32 v73, 0xffff0000, v66
	v_lshlrev_b32_e32 v66, 16, v67
	v_and_b32_e32 v67, 0xffff0000, v67
	v_pk_fma_f32 v[64:65], v[64:65], v[152:153], v[66:67]
	v_lshlrev_b32_e32 v66, 16, v68
	v_and_b32_e32 v67, 0xffff0000, v68
	v_pk_fma_f32 v[66:67], v[58:59], v[154:155], v[66:67]
	v_lshlrev_b32_e32 v58, 16, v69
	v_and_b32_e32 v59, 0xffff0000, v69
	v_pk_fma_f32 v[62:63], v[62:63], v[156:157], v[72:73]
	v_pk_fma_f32 v[68:69], v[60:61], v[150:151], v[58:59]
	v_cvt_pk_bf16_f32 v58, v62, v63
	v_cvt_pk_bf16_f32 v59, v64, v65
	v_cvt_pk_bf16_f32 v60, v66, v67
	v_cvt_pk_bf16_f32 v61, v68, v69
	global_store_dwordx4 v[70:71], v[58:61], off offset:2048
	s_nop 1
	v_mov_b32_e32 v58, v218
	v_mov_b32_e32 v59, v219
	v_mov_b32_e32 v60, v220
	v_mov_b32_e32 v61, v221
	s_nop 0
	v_lshlrev_b32_e32 v62, 16, v58
	v_and_b32_e32 v63, 0xffff0000, v58
	v_lshlrev_b32_e32 v58, 16, v59
	v_and_b32_e32 v59, 0xffff0000, v59
	v_pk_fma_f32 v[56:57], v[56:57], v[146:147], v[58:59]
	v_lshlrev_b32_e32 v58, 16, v60
	v_and_b32_e32 v59, 0xffff0000, v60
	v_pk_fma_f32 v[58:59], v[50:51], v[144:145], v[58:59]
	v_lshlrev_b32_e32 v50, 16, v61
	v_and_b32_e32 v51, 0xffff0000, v61
	v_pk_fma_f32 v[54:55], v[54:55], v[148:149], v[62:63]
	v_pk_fma_f32 v[60:61], v[52:53], v[142:143], v[50:51]
	v_cvt_pk_bf16_f32 v50, v54, v55
	v_cvt_pk_bf16_f32 v51, v56, v57
	v_cvt_pk_bf16_f32 v52, v58, v59
	v_cvt_pk_bf16_f32 v53, v60, v61
	v_lshl_add_u64 v[54:55], v[158:159], 0, s[6:7]
	global_store_dwordx4 v[70:71], v[50:53], off offset:2304
	s_nop 1
	v_mov_b32_e32 v50, v222
	v_mov_b32_e32 v51, v223
	v_mov_b32_e32 v52, v224
	v_mov_b32_e32 v53, v225
	s_mov_b64 s[6:7], 0xa0000
	s_nop 0
	v_lshlrev_b32_e32 v56, 16, v50
	v_and_b32_e32 v57, 0xffff0000, v50
	v_lshlrev_b32_e32 v50, 16, v51
	v_and_b32_e32 v51, 0xffff0000, v51
	v_pk_fma_f32 v[48:49], v[48:49], v[152:153], v[50:51]
	v_lshlrev_b32_e32 v50, 16, v52
	v_and_b32_e32 v51, 0xffff0000, v52
	v_pk_fma_f32 v[50:51], v[42:43], v[154:155], v[50:51]
	v_lshlrev_b32_e32 v42, 16, v53
	v_and_b32_e32 v43, 0xffff0000, v53
	v_pk_fma_f32 v[46:47], v[46:47], v[156:157], v[56:57]
	v_pk_fma_f32 v[52:53], v[44:45], v[150:151], v[42:43]
	v_cvt_pk_bf16_f32 v42, v46, v47
	v_cvt_pk_bf16_f32 v43, v48, v49
	v_cvt_pk_bf16_f32 v44, v50, v51
	v_cvt_pk_bf16_f32 v45, v52, v53
	global_store_dwordx4 v[54:55], v[42:45], off offset:2048
	s_nop 1
	v_mov_b32_e32 v42, v226
	v_mov_b32_e32 v43, v227
	v_mov_b32_e32 v44, v228
	v_mov_b32_e32 v45, v229
	s_nop 0
	v_lshlrev_b32_e32 v46, 16, v42
	v_and_b32_e32 v47, 0xffff0000, v42
	v_lshlrev_b32_e32 v42, 16, v43
	v_and_b32_e32 v43, 0xffff0000, v43
	v_pk_fma_f32 v[40:41], v[40:41], v[146:147], v[42:43]
	v_lshlrev_b32_e32 v42, 16, v44
	v_and_b32_e32 v43, 0xffff0000, v44
	v_pk_fma_f32 v[42:43], v[34:35], v[144:145], v[42:43]
	v_lshlrev_b32_e32 v34, 16, v45
	v_and_b32_e32 v35, 0xffff0000, v45
	v_pk_fma_f32 v[38:39], v[38:39], v[148:149], v[46:47]
	v_pk_fma_f32 v[44:45], v[36:37], v[142:143], v[34:35]
	v_cvt_pk_bf16_f32 v34, v38, v39
	v_cvt_pk_bf16_f32 v35, v40, v41
	v_cvt_pk_bf16_f32 v36, v42, v43
	v_cvt_pk_bf16_f32 v37, v44, v45
	v_lshl_add_u64 v[38:39], v[158:159], 0, s[6:7]
	global_store_dwordx4 v[54:55], v[34:37], off offset:2304
	s_nop 1
	v_mov_b32_e32 v34, v230
	v_mov_b32_e32 v35, v231
	v_mov_b32_e32 v36, v232
	v_mov_b32_e32 v37, v233
	s_mov_b64 s[6:7], 0xb0000
	s_nop 0
	v_lshlrev_b32_e32 v40, 16, v34
	v_and_b32_e32 v41, 0xffff0000, v34
	v_lshlrev_b32_e32 v34, 16, v35
	v_and_b32_e32 v35, 0xffff0000, v35
	v_pk_fma_f32 v[32:33], v[32:33], v[152:153], v[34:35]
	v_lshlrev_b32_e32 v34, 16, v36
	v_and_b32_e32 v35, 0xffff0000, v36
	v_pk_fma_f32 v[34:35], v[26:27], v[154:155], v[34:35]
	v_lshlrev_b32_e32 v26, 16, v37
	v_and_b32_e32 v27, 0xffff0000, v37
	v_pk_fma_f32 v[30:31], v[30:31], v[156:157], v[40:41]
	v_pk_fma_f32 v[36:37], v[28:29], v[150:151], v[26:27]
	v_cvt_pk_bf16_f32 v26, v30, v31
	v_cvt_pk_bf16_f32 v27, v32, v33
	v_cvt_pk_bf16_f32 v28, v34, v35
	v_cvt_pk_bf16_f32 v29, v36, v37
	global_store_dwordx4 v[38:39], v[26:29], off offset:2048
	s_nop 1
	v_mov_b32_e32 v26, v236
	v_mov_b32_e32 v27, v237
	v_mov_b32_e32 v28, v238
	v_mov_b32_e32 v29, v239
	s_nop 0
	v_lshlrev_b32_e32 v30, 16, v26
	v_and_b32_e32 v31, 0xffff0000, v26
	v_lshlrev_b32_e32 v26, 16, v27
	v_and_b32_e32 v27, 0xffff0000, v27
	v_pk_fma_f32 v[24:25], v[24:25], v[146:147], v[26:27]
	v_lshlrev_b32_e32 v26, 16, v28
	v_and_b32_e32 v27, 0xffff0000, v28
	v_pk_fma_f32 v[26:27], v[18:19], v[144:145], v[26:27]
	v_lshlrev_b32_e32 v18, 16, v29
	v_and_b32_e32 v19, 0xffff0000, v29
	v_pk_fma_f32 v[22:23], v[22:23], v[148:149], v[30:31]
	v_pk_fma_f32 v[28:29], v[20:21], v[142:143], v[18:19]
	v_cvt_pk_bf16_f32 v18, v22, v23
	v_cvt_pk_bf16_f32 v19, v24, v25
	v_cvt_pk_bf16_f32 v20, v26, v27
	v_cvt_pk_bf16_f32 v21, v28, v29
	global_store_dwordx4 v[38:39], v[18:21], off offset:2304
	s_nop 1
	v_lshl_add_u64 v[18:19], v[158:159], 0, s[6:7]
	v_mov_b32_e32 v20, v246
	v_mov_b32_e32 v21, v247
	v_mov_b32_e32 v22, v248
	v_mov_b32_e32 v23, v249
	s_nop 0
	v_lshlrev_b32_e32 v24, 16, v20
	v_and_b32_e32 v25, 0xffff0000, v20
	v_lshlrev_b32_e32 v20, 16, v21
	v_and_b32_e32 v21, 0xffff0000, v21
	v_pk_fma_f32 v[16:17], v[16:17], v[152:153], v[20:21]
	v_lshlrev_b32_e32 v20, 16, v22
	v_and_b32_e32 v21, 0xffff0000, v22
	v_pk_fma_f32 v[20:21], v[10:11], v[154:155], v[20:21]
	v_lshlrev_b32_e32 v10, 16, v23
	v_and_b32_e32 v11, 0xffff0000, v23
	v_pk_fma_f32 v[14:15], v[14:15], v[156:157], v[24:25]
	v_pk_fma_f32 v[22:23], v[12:13], v[150:151], v[10:11]
	v_cvt_pk_bf16_f32 v10, v14, v15
	v_cvt_pk_bf16_f32 v11, v16, v17
	v_cvt_pk_bf16_f32 v12, v20, v21
	v_cvt_pk_bf16_f32 v13, v22, v23
	global_store_dwordx4 v[18:19], v[10:13], off offset:2048
	s_nop 1
	v_mov_b32_e32 v10, v250
	v_mov_b32_e32 v11, v251
	v_mov_b32_e32 v12, v252
	v_mov_b32_e32 v13, v253
	s_nop 0
	v_lshlrev_b32_e32 v14, 16, v10
	v_and_b32_e32 v15, 0xffff0000, v10
	v_lshlrev_b32_e32 v10, 16, v11
	v_and_b32_e32 v11, 0xffff0000, v11
	v_pk_fma_f32 v[8:9], v[8:9], v[146:147], v[10:11]
	v_lshlrev_b32_e32 v10, 16, v12
	v_and_b32_e32 v11, 0xffff0000, v12
	v_pk_fma_f32 v[10:11], v[2:3], v[144:145], v[10:11]
	v_lshlrev_b32_e32 v2, 16, v13
	v_and_b32_e32 v3, 0xffff0000, v13
	v_pk_fma_f32 v[6:7], v[6:7], v[148:149], v[14:15]
	v_pk_fma_f32 v[12:13], v[4:5], v[142:143], v[2:3]
	v_cvt_pk_bf16_f32 v2, v6, v7
	v_cvt_pk_bf16_f32 v3, v8, v9
	v_cvt_pk_bf16_f32 v4, v10, v11
	v_cvt_pk_bf16_f32 v5, v12, v13
	global_store_dwordx4 v[18:19], v[2:5], off offset:2304
	s_cbranch_vccz .LBB0_1399
	s_waitcnt vmcnt(0)
	s_cmpk_gt_u32 s22, 0xff
	s_cbranch_scc1 .LBB0_1412
	s_barrier
